# EpiGlu second-half residual loads hoisted, attention and S5 waits no longer wait on store acknowledgements, gating W waits per path
# speedup vs baseline: 1.0085x; 1.0041x over previous
.LBB0_511:
	s_cmp_lg_u32 s74, 0x600
	s_cselect_b32 s98, 0x200, 0
	s_cselect_b32 s100, s82, 0
	s_cselect_b32 s101, s83, 0
	s_add_u32 s98, s74, s98
	s_addc_u32 s99, s75, 0
	v_lshl_add_u64 v[76:77], v[94:95], 0, s[98:99]
	global_load_dword v208, v[76:77], off
	v_lshl_add_u64 v[76:77], v[98:99], 0, s[0:1]
	v_lshl_add_u64 v[76:77], v[76:77], 0, s[100:101]
	v_lshl_add_u64 v[76:77], v[76:77], 0, v[148:149]
	global_load_dwordx4 v[192:195], v[76:77], off offset:-128
	global_load_dwordx4 v[196:199], v[76:77], off offset:-64
	global_load_dwordx4 v[200:203], v[76:77], off
	global_load_dwordx4 v[204:207], v[76:77], off offset:64
	s_waitcnt vmcnt(22)
	v_lshlrev_b32_e32 v77, 16, v0
	s_bitcmp1_b32 s88, 0
	s_waitcnt lgkmcnt(2)
	v_sub_f32_e32 v77, v77, v124
	s_waitcnt vmcnt(20)
	v_lshlrev_b32_e32 v78, 16, v8
	s_cselect_b32 s89, 0x8800, 0
	s_waitcnt lgkmcnt(1)
	v_mul_f32_e32 v77, v92, v77
	s_waitcnt lgkmcnt(0)
	v_sub_f32_e32 v78, v78, v125
	s_add_i32 s89, s89, 0
	s_waitcnt vmcnt(11)
	v_fma_f32 v77, v28, v77, v44
	v_mul_f32_e32 v78, v93, v78
	v_add3_u32 v76, s89, v126, v127
	v_fma_f32 v78, v28, v78, v44
	v_cvt_pk_bf16_f32 v77, v77, v78
	ds_write_b32 v76, v77
	v_and_b32_e32 v77, 0xffff0000, v0
	v_sub_f32_e32 v77, v77, v124
	v_and_b32_e32 v78, 0xffff0000, v8
	v_mul_f32_e32 v77, v92, v77
	v_sub_f32_e32 v78, v78, v125
	v_fma_f32 v77, v29, v77, v45
	v_mul_f32_e32 v78, v93, v78
	v_fma_f32 v78, v29, v78, v45
	v_cvt_pk_bf16_f32 v77, v77, v78
	ds_write_b32 v76, v77 offset:272
	v_lshlrev_b32_e32 v77, 16, v1
	v_sub_f32_e32 v77, v77, v124
	v_lshlrev_b32_e32 v78, 16, v9
	v_mul_f32_e32 v77, v92, v77
	v_sub_f32_e32 v78, v78, v125
	v_fma_f32 v77, v30, v77, v46
	v_mul_f32_e32 v78, v93, v78
	v_fma_f32 v78, v30, v78, v46
	v_cvt_pk_bf16_f32 v77, v77, v78
	ds_write_b32 v76, v77 offset:544
	v_and_b32_e32 v77, 0xffff0000, v1
	v_sub_f32_e32 v77, v77, v124
	v_and_b32_e32 v78, 0xffff0000, v9
	v_mul_f32_e32 v77, v92, v77
	v_sub_f32_e32 v78, v78, v125
	v_fma_f32 v77, v31, v77, v47
	v_mul_f32_e32 v78, v93, v78
	v_fma_f32 v78, v31, v78, v47
	v_cvt_pk_bf16_f32 v77, v77, v78
	ds_write_b32 v76, v77 offset:816
	v_lshlrev_b32_e32 v77, 16, v2
	v_sub_f32_e32 v77, v77, v124
	v_lshlrev_b32_e32 v78, 16, v10
	v_mul_f32_e32 v77, v92, v77
	v_sub_f32_e32 v78, v78, v125
	v_fma_f32 v77, v24, v77, v40
	v_mul_f32_e32 v78, v93, v78
	v_fma_f32 v78, v24, v78, v40
	v_cvt_pk_bf16_f32 v77, v77, v78
	ds_write_b32 v76, v77 offset:1088
	v_and_b32_e32 v77, 0xffff0000, v2
	v_sub_f32_e32 v77, v77, v124
	v_and_b32_e32 v78, 0xffff0000, v10
	v_mul_f32_e32 v77, v92, v77
	v_sub_f32_e32 v78, v78, v125
	v_fma_f32 v77, v25, v77, v41
	v_mul_f32_e32 v78, v93, v78
	v_fma_f32 v78, v25, v78, v41
	v_cvt_pk_bf16_f32 v77, v77, v78
	ds_write_b32 v76, v77 offset:1360
	v_lshlrev_b32_e32 v77, 16, v3
	v_sub_f32_e32 v77, v77, v124
	v_lshlrev_b32_e32 v78, 16, v11
	v_mul_f32_e32 v77, v92, v77
	v_sub_f32_e32 v78, v78, v125
	v_fma_f32 v77, v26, v77, v42
	v_mul_f32_e32 v78, v93, v78
	v_fma_f32 v78, v26, v78, v42
	v_cvt_pk_bf16_f32 v77, v77, v78
	ds_write_b32 v76, v77 offset:1632
	v_and_b32_e32 v77, 0xffff0000, v3
	v_sub_f32_e32 v77, v77, v124
	v_and_b32_e32 v78, 0xffff0000, v11
	v_mul_f32_e32 v77, v92, v77
	v_sub_f32_e32 v78, v78, v125
	v_fma_f32 v77, v27, v77, v43
	v_mul_f32_e32 v78, v93, v78
	v_fma_f32 v78, v27, v78, v43
	v_cvt_pk_bf16_f32 v77, v77, v78
	ds_write_b32 v76, v77 offset:1904
	v_lshlrev_b32_e32 v77, 16, v4
	v_sub_f32_e32 v77, v77, v124
	v_lshlrev_b32_e32 v78, 16, v12
	v_mul_f32_e32 v77, v92, v77
	v_sub_f32_e32 v78, v78, v125
	v_fma_f32 v77, v20, v77, v36
	v_mul_f32_e32 v78, v93, v78
	v_fma_f32 v78, v20, v78, v36
	v_cvt_pk_bf16_f32 v77, v77, v78
	ds_write_b32 v76, v77 offset:2176
	v_and_b32_e32 v77, 0xffff0000, v4
	v_sub_f32_e32 v77, v77, v124
	v_and_b32_e32 v78, 0xffff0000, v12
	v_mul_f32_e32 v77, v92, v77
	v_sub_f32_e32 v78, v78, v125
	v_fma_f32 v77, v21, v77, v37
	v_mul_f32_e32 v78, v93, v78
	v_fma_f32 v78, v21, v78, v37
	v_cvt_pk_bf16_f32 v77, v77, v78
	ds_write_b32 v76, v77 offset:2448
	v_lshlrev_b32_e32 v77, 16, v5
	v_sub_f32_e32 v77, v77, v124
	v_lshlrev_b32_e32 v78, 16, v13
	v_mul_f32_e32 v77, v92, v77
	v_sub_f32_e32 v78, v78, v125
	v_fma_f32 v77, v22, v77, v38
	v_mul_f32_e32 v78, v93, v78
	v_fma_f32 v78, v22, v78, v38
	v_cvt_pk_bf16_f32 v77, v77, v78
	ds_write_b32 v76, v77 offset:2720
	v_and_b32_e32 v77, 0xffff0000, v5
	v_sub_f32_e32 v77, v77, v124
	v_and_b32_e32 v78, 0xffff0000, v13
	v_mul_f32_e32 v77, v92, v77
	v_sub_f32_e32 v78, v78, v125
	v_fma_f32 v77, v23, v77, v39
	v_mul_f32_e32 v78, v93, v78
	v_fma_f32 v78, v23, v78, v39
	v_cvt_pk_bf16_f32 v77, v77, v78
	ds_write_b32 v76, v77 offset:2992
	v_lshlrev_b32_e32 v77, 16, v6
	v_sub_f32_e32 v77, v77, v124
	v_lshlrev_b32_e32 v78, 16, v14
	v_mul_f32_e32 v77, v92, v77
	v_sub_f32_e32 v78, v78, v125
	v_fma_f32 v77, v16, v77, v32
	v_mul_f32_e32 v78, v93, v78
	v_fma_f32 v78, v16, v78, v32
	v_cvt_pk_bf16_f32 v77, v77, v78
	ds_write_b32 v76, v77 offset:3264
	v_and_b32_e32 v77, 0xffff0000, v6
	v_sub_f32_e32 v77, v77, v124
	v_and_b32_e32 v78, 0xffff0000, v14
	v_mul_f32_e32 v77, v92, v77
	v_sub_f32_e32 v78, v78, v125
	v_fma_f32 v77, v17, v77, v33
	v_mul_f32_e32 v78, v93, v78
	v_fma_f32 v78, v17, v78, v33
	v_cvt_pk_bf16_f32 v77, v77, v78
	ds_write_b32 v76, v77 offset:3536
	v_lshlrev_b32_e32 v77, 16, v7
	v_sub_f32_e32 v77, v77, v124
	v_lshlrev_b32_e32 v78, 16, v15
	v_mul_f32_e32 v77, v92, v77
	v_sub_f32_e32 v78, v78, v125
	v_fma_f32 v77, v18, v77, v34
	v_mul_f32_e32 v78, v93, v78
	v_fma_f32 v78, v18, v78, v34
	v_cvt_pk_bf16_f32 v77, v77, v78
	ds_write_b32 v76, v77 offset:3808
	v_and_b32_e32 v77, 0xffff0000, v7
	v_sub_f32_e32 v77, v77, v124
	v_and_b32_e32 v78, 0xffff0000, v15
	v_mul_f32_e32 v77, v92, v77
	v_sub_f32_e32 v78, v78, v125
	v_fma_f32 v77, v19, v77, v35
	v_mul_f32_e32 v78, v93, v78
	s_cmpk_eq_i32 s74, 0x600
	v_fma_f32 v78, v19, v78, v35
	v_cvt_pk_bf16_f32 v77, v77, v78
	ds_write_b32 v76, v77 offset:4080
	s_cbranch_scc1 .Lgat_w3
	v_lshl_add_u64 v[8:9], v[100:101], 0, s[0:1]
	s_mov_b64 s[90:91], 0x13001100
	v_add_co_u32_e32 v0, vcc, 0x13001000, v8
	v_lshl_add_u64 v[4:5], v[8:9], 0, s[90:91]
	s_nop 0
	v_addc_co_u32_e32 v1, vcc, 0, v9, vcc
	s_mov_b64 s[90:91], 0x13003100
	v_lshl_add_u64 v[12:13], v[8:9], 0, s[90:91]
	v_add_co_u32_e32 v8, vcc, 0x13003000, v8
	s_nop 0
	v_addc_co_u32_e32 v9, vcc, 0, v9, vcc
	global_load_dwordx4 v[0:3], v[0:1], off offset:256
	s_nop 0
	global_load_dwordx4 v[4:7], v[4:5], off offset:16
	s_nop 0
	global_load_dwordx4 v[8:11], v[8:9], off offset:256
	s_nop 0
	global_load_dwordx4 v[12:15], v[12:13], off offset:16
	s_nop 0
	s_add_i32 s98, s88, 1
	s_lshl_b32 s98, s98, 9
	v_add_u32_e32 v146, s98, v147
	ds_read_b128 v[28:31], v146
	ds_read_b128 v[24:27], v146 offset:16
	ds_read_b128 v[20:23], v146 offset:32
	ds_read_b128 v[16:19], v146 offset:48
	ds_read_b128 v[44:47], v146 offset:2048
	ds_read_b128 v[40:43], v146 offset:2064
	ds_read_b128 v[36:39], v146 offset:2080
	ds_read_b128 v[32:35], v146 offset:2096
	v_readlane_b32 s90, v252, 6
	v_readlane_b32 s91, v252, 7
	s_waitcnt vmcnt(9)
	s_branch .LBB0_513

.LBB0_513:
	s_and_b64 vcc, exec, s[68:69]
	s_waitcnt lgkmcnt(0)
	s_barrier
	s_cbranch_vccnz .LBB0_519
	v_cndmask_b32_e64 v76, v68, 0, s[18:19]
	v_bfe_u32 v77, v76, 16, 1
	v_add3_u32 v76, v76, v77, s85
	v_cndmask_b32_e64 v77, v69, 0, s[20:21]
	v_bfe_u32 v78, v77, 16, 1
	v_lshrrev_b32_e32 v76, 16, v76
	v_add3_u32 v77, v77, v78, s85
	v_and_or_b32 v76, v77, s84, v76
	v_cndmask_b32_e64 v77, v70, 0, s[22:23]
	v_bfe_u32 v78, v77, 16, 1
	v_add3_u32 v77, v77, v78, s85
	v_cndmask_b32_e64 v78, v71, 0, s[24:25]
	v_bfe_u32 v79, v78, 16, 1
	v_lshrrev_b32_e32 v77, 16, v77
	v_add3_u32 v78, v78, v79, s85
	v_and_or_b32 v77, v78, s84, v77
	v_cndmask_b32_e64 v78, v60, 0, s[26:27]
	v_bfe_u32 v79, v78, 16, 1
	v_add3_u32 v78, v78, v79, s85
	v_cndmask_b32_e64 v79, v61, 0, s[28:29]
	v_bfe_u32 v84, v79, 16, 1
	v_lshrrev_b32_e32 v78, 16, v78
	v_add3_u32 v79, v79, v84, s85
	v_and_or_b32 v78, v79, s84, v78
	v_cndmask_b32_e64 v79, v62, 0, s[30:31]
	v_bfe_u32 v84, v79, 16, 1
	v_add3_u32 v79, v79, v84, s85
	v_cndmask_b32_e64 v84, v63, 0, s[34:35]
	v_bfe_u32 v85, v84, 16, 1
	v_lshrrev_b32_e32 v79, 16, v79
	v_add3_u32 v84, v84, v85, s85
	v_and_or_b32 v79, v84, s84, v79
	s_and_b64 vcc, exec, s[70:71]
	s_cbranch_vccz .LBB0_520

.LBB0_520:
	v_cndmask_b32_e64 v84, v64, 0, s[36:37]
	v_bfe_u32 v85, v84, 16, 1
	v_add3_u32 v84, v84, v85, s85
	v_cndmask_b32_e64 v85, v65, 0, s[38:39]
	v_bfe_u32 v86, v85, 16, 1
	v_lshrrev_b32_e32 v84, 16, v84
	v_add3_u32 v85, v85, v86, s85
	v_and_or_b32 v84, v85, s84, v84
	v_cndmask_b32_e64 v85, v66, 0, s[40:41]
	v_bfe_u32 v86, v85, 16, 1
	v_add3_u32 v85, v85, v86, s85
	v_cndmask_b32_e64 v86, v67, 0, s[42:43]
	v_bfe_u32 v87, v86, 16, 1
	v_lshrrev_b32_e32 v85, 16, v85
	v_add3_u32 v86, v86, v87, s85
	v_and_or_b32 v85, v86, s84, v85
	v_cndmask_b32_e64 v86, v52, 0, s[44:45]
	v_bfe_u32 v87, v86, 16, 1
	v_add3_u32 v86, v86, v87, s85
	v_cndmask_b32_e64 v87, v53, 0, s[46:47]
	v_bfe_u32 v88, v87, 16, 1
	v_lshrrev_b32_e32 v86, 16, v86
	v_add3_u32 v87, v87, v88, s85
	v_and_or_b32 v86, v87, s84, v86
	v_cndmask_b32_e64 v87, v54, 0, s[48:49]
	v_bfe_u32 v88, v87, 16, 1
	v_add3_u32 v87, v87, v88, s85
	v_cndmask_b32_e64 v88, v55, 0, s[50:51]
	v_bfe_u32 v89, v88, 16, 1
	v_lshrrev_b32_e32 v87, 16, v87
	v_add3_u32 v88, v88, v89, s85
	v_and_or_b32 v87, v88, s84, v87
	s_and_b64 vcc, exec, s[72:73]
	s_cbranch_vccnz .LBB0_516
.LBB0_521:
	v_cndmask_b32_e64 v88, v56, 0, s[52:53]
	v_bfe_u32 v89, v88, 16, 1
	v_add3_u32 v88, v88, v89, s85
	v_cndmask_b32_e64 v89, v57, 0, s[54:55]
	v_bfe_u32 v90, v89, 16, 1
	v_lshrrev_b32_e32 v88, 16, v88
	v_add3_u32 v89, v89, v90, s85
	v_and_or_b32 v88, v89, s84, v88
	v_cndmask_b32_e64 v89, v58, 0, s[56:57]
	v_bfe_u32 v90, v89, 16, 1
	v_add3_u32 v89, v89, v90, s85
	v_cndmask_b32_e64 v90, v59, 0, s[58:59]
	v_bfe_u32 v91, v90, 16, 1
	v_lshrrev_b32_e32 v89, 16, v89
	v_add3_u32 v90, v90, v91, s85
	v_and_or_b32 v89, v90, s84, v89
	v_cndmask_b32_e64 v90, v48, 0, s[60:61]
	v_bfe_u32 v91, v90, 16, 1
	v_add3_u32 v90, v90, v91, s85
	v_cndmask_b32_e64 v91, v49, 0, s[62:63]
	v_bfe_u32 v138, v91, 16, 1
	v_lshrrev_b32_e32 v90, 16, v90
	v_add3_u32 v91, v91, v138, s85
	v_and_or_b32 v90, v91, s84, v90
	v_cndmask_b32_e64 v91, v50, 0, s[64:65]
	v_bfe_u32 v138, v91, 16, 1
	v_add3_u32 v91, v91, v138, s85
	v_cndmask_b32_e64 v138, v51, 0, s[66:67]
	v_bfe_u32 v139, v138, 16, 1
	v_lshrrev_b32_e32 v91, 16, v91
	v_add3_u32 v138, v138, v139, s85
	v_and_or_b32 v91, v138, s84, v91
.LBB0_522:
	v_cndmask_b32_e64 v80, v80, 0, s[2:3]
	v_bfe_u32 v138, v80, 16, 1
	v_cndmask_b32_e64 v81, 0, v81, s[4:5]
	v_add3_u32 v80, v80, v138, s85
	v_bfe_u32 v138, v81, 16, 1
	v_lshrrev_b32_e32 v80, 16, v80
	v_add3_u32 v81, v81, v138, s85
	v_and_or_b32 v80, v81, s84, v80
	v_cndmask_b32_e64 v81, v82, 0, s[6:7]
	v_bfe_u32 v82, v81, 16, 1
	v_add3_u32 v81, v81, v82, s85
	v_cndmask_b32_e64 v82, v83, 0, s[8:9]
	v_bfe_u32 v83, v82, 16, 1
	v_add_u32_e32 v141, s89, v129
	v_lshrrev_b32_e32 v81, 16, v81
	v_add3_u32 v82, v82, v83, s85
	v_cndmask_b32_e64 v72, v72, 0, s[10:11]
	v_add_u32_e32 v138, v141, v130
	v_and_or_b32 v81, v82, s84, v81
	v_bfe_u32 v82, v72, 16, 1
	v_cndmask_b32_e64 v73, v73, 0, s[12:13]
	v_add3_u32 v72, v72, v82, s85
	v_bfe_u32 v82, v73, 16, 1
	v_lshrrev_b32_e32 v72, 16, v72
	v_add3_u32 v73, v73, v82, s85
	v_and_or_b32 v82, v73, s84, v72
	v_cndmask_b32_e64 v72, v74, 0, s[14:15]
	v_bfe_u32 v73, v72, 16, 1
	v_add3_u32 v72, v72, v73, s85
	v_cndmask_b32_e64 v73, v75, 0, s[16:17]
	v_bfe_u32 v74, v73, 16, 1
	v_lshrrev_b32_e32 v72, 16, v72
	v_add3_u32 v73, v73, v74, s85
	v_and_or_b32 v83, v73, s84, v72
	v_add_u32_e32 v150, v141, v131
	v_add_u32_e32 v151, v141, v132
	v_add_u32_e32 v152, v141, v133
	v_add_u32_e32 v153, v141, v134
	v_add_u32_e32 v154, v141, v128
	v_add_u32_e32 v155, v141, v135
	v_add_u32_e32 v156, v141, v136
	ds_read_b128 v[160:163], v138
	ds_read_b128 v[164:167], v138 offset:64
	ds_read_b128 v[168:171], v138 offset:128
	ds_read_b128 v[172:175], v138 offset:192
	ds_read_b128 v[176:179], v150 offset:4352
	ds_read_b128 v[180:183], v150 offset:4416
	ds_read_b128 v[184:187], v150 offset:4480
	ds_read_b128 v[188:191], v150 offset:4544
	ds_read_b128 v[48:51], v151 offset:8704
	ds_read_b128 v[52:55], v152 offset:8704
	ds_read_b128 v[56:59], v151 offset:8832
	ds_read_b128 v[60:63], v153 offset:8704
	ds_read_b128 v[64:67], v154 offset:13056
	ds_read_b128 v[68:71], v155 offset:13056
	ds_read_b128 v[72:75], v154 offset:13184
	ds_read_b128 v[142:145], v156 offset:13056
	v_mbcnt_lo_u32_b32 v148, -1, 0
	v_mbcnt_hi_u32_b32 v148, -1, v148
	v_lshrrev_b32_e32 v148, 4, v148
	v_and_b32_e32 v148, 1, v148
	v_mul_u32_u24_e32 v148, 24, v148
	v_mov_b32_e32 v149, 0
	v_lshl_add_u64 v[158:159], v[96:97], 0, s[0:1]
	v_lshl_add_u64 v[158:159], v[158:159], 0, v[148:149]
	s_waitcnt lgkmcnt(8)
	v_mfma_f32_16x16x32_bf16 v[224:227], v[160:163], v[80:83], 0
	v_mfma_f32_16x16x32_bf16 v[228:231], v[176:179], v[80:83], 0
	v_mfma_f32_16x16x32_bf16 v[224:227], v[164:167], v[76:79], v[224:227]
	v_mfma_f32_16x16x32_bf16 v[228:231], v[180:183], v[76:79], v[228:231]
	v_mfma_f32_16x16x32_bf16 v[224:227], v[168:171], v[84:87], v[224:227]
	v_mfma_f32_16x16x32_bf16 v[228:231], v[184:187], v[84:87], v[228:231]
	v_mfma_f32_16x16x32_bf16 v[224:227], v[172:175], v[88:91], v[224:227]
	v_mfma_f32_16x16x32_bf16 v[228:231], v[188:191], v[88:91], v[228:231]
	ds_read_b128 v[160:163], v138 offset:17408
	ds_read_b128 v[164:167], v138 offset:17472
	ds_read_b128 v[168:171], v138 offset:17536
	ds_read_b128 v[172:175], v138 offset:17600
	ds_read_b128 v[176:179], v150 offset:21760
	ds_read_b128 v[180:183], v150 offset:21824
	ds_read_b128 v[184:187], v150 offset:21888
	ds_read_b128 v[188:191], v150 offset:21952
	s_waitcnt lgkmcnt(8)
	v_mfma_f32_16x16x32_bf16 v[232:235], v[48:51], v[80:83], 0
	v_mfma_f32_16x16x32_bf16 v[236:239], v[64:67], v[80:83], 0
	v_mfma_f32_16x16x32_bf16 v[232:235], v[52:55], v[76:79], v[232:235]
	v_mfma_f32_16x16x32_bf16 v[236:239], v[68:71], v[76:79], v[236:239]
	v_mfma_f32_16x16x32_bf16 v[232:235], v[56:59], v[84:87], v[232:235]
	v_mfma_f32_16x16x32_bf16 v[236:239], v[72:75], v[84:87], v[236:239]
	v_mfma_f32_16x16x32_bf16 v[232:235], v[60:63], v[88:91], v[232:235]
	v_mfma_f32_16x16x32_bf16 v[236:239], v[142:145], v[88:91], v[236:239]
	ds_read_b128 v[48:51], v151 offset:26112
	ds_read_b128 v[52:55], v152 offset:26112
	ds_read_b128 v[56:59], v151 offset:26240
	ds_read_b128 v[60:63], v153 offset:26112
	ds_read_b128 v[64:67], v154 offset:30464
	ds_read_b128 v[68:71], v155 offset:30464
	ds_read_b128 v[72:75], v154 offset:30592
	ds_read_b128 v[142:145], v156 offset:30464
	v_lshlrev_b32_e32 v248, 16, v122
	v_add_f32_e32 v249, v137, v224
	v_mul_f32_e32 v249, v249, v248
	v_and_b32_e32 v248, 0xffff0000, v122
	v_add_f32_e32 v250, v137, v225
	v_mul_f32_e32 v250, v250, v248
	v_cvt_pk_bf16_f32 v240, v249, v250
	v_lshlrev_b32_e32 v248, 16, v123
	v_add_f32_e32 v249, v137, v226
	v_mul_f32_e32 v249, v249, v248
	v_and_b32_e32 v248, 0xffff0000, v123
	v_add_f32_e32 v250, v137, v227
	v_mul_f32_e32 v250, v250, v248
	v_cvt_pk_bf16_f32 v241, v249, v250
	v_lshlrev_b32_e32 v248, 16, v120
	v_add_f32_e32 v249, v137, v228
	v_mul_f32_e32 v249, v249, v248
	v_and_b32_e32 v248, 0xffff0000, v120
	v_add_f32_e32 v250, v137, v229
	v_mul_f32_e32 v250, v250, v248
	v_cvt_pk_bf16_f32 v242, v249, v250
	v_lshlrev_b32_e32 v248, 16, v121
	v_add_f32_e32 v249, v137, v230
	v_mul_f32_e32 v249, v249, v248
	v_and_b32_e32 v248, 0xffff0000, v121
	v_add_f32_e32 v250, v137, v231
	v_mul_f32_e32 v250, v250, v248
	v_cvt_pk_bf16_f32 v243, v249, v250
	s_nop 1
	v_permlane16_swap_b32_e32 v240, v242
	v_permlane16_swap_b32_e32 v241, v243
	global_store_dwordx4 v[158:159], v[240:243], off offset:-128
	s_waitcnt lgkmcnt(8)
	v_mfma_f32_16x16x32_bf16 v[224:227], v[160:163], v[80:83], 0
	v_mfma_f32_16x16x32_bf16 v[228:231], v[176:179], v[80:83], 0
	v_mfma_f32_16x16x32_bf16 v[224:227], v[164:167], v[76:79], v[224:227]
	v_mfma_f32_16x16x32_bf16 v[228:231], v[180:183], v[76:79], v[228:231]
	v_mfma_f32_16x16x32_bf16 v[224:227], v[168:171], v[84:87], v[224:227]
	v_mfma_f32_16x16x32_bf16 v[228:231], v[184:187], v[84:87], v[228:231]
	v_mfma_f32_16x16x32_bf16 v[224:227], v[172:175], v[88:91], v[224:227]
	v_mfma_f32_16x16x32_bf16 v[228:231], v[188:191], v[88:91], v[228:231]
	v_lshlrev_b32_e32 v248, 16, v118
	v_add_f32_e32 v249, v137, v232
	v_mul_f32_e32 v249, v249, v248
	v_and_b32_e32 v248, 0xffff0000, v118
	v_add_f32_e32 v250, v137, v233
	v_mul_f32_e32 v250, v250, v248
	v_cvt_pk_bf16_f32 v244, v249, v250
	v_lshlrev_b32_e32 v248, 16, v119
	v_add_f32_e32 v249, v137, v234
	v_mul_f32_e32 v249, v249, v248
	v_and_b32_e32 v248, 0xffff0000, v119
	v_add_f32_e32 v250, v137, v235
	v_mul_f32_e32 v250, v250, v248
	v_cvt_pk_bf16_f32 v245, v249, v250
	v_lshlrev_b32_e32 v248, 16, v116
	v_add_f32_e32 v249, v137, v236
	v_mul_f32_e32 v249, v249, v248
	v_and_b32_e32 v248, 0xffff0000, v116
	v_add_f32_e32 v250, v137, v237
	v_mul_f32_e32 v250, v250, v248
	v_cvt_pk_bf16_f32 v246, v249, v250
	v_lshlrev_b32_e32 v248, 16, v117
	v_add_f32_e32 v249, v137, v238
	v_mul_f32_e32 v249, v249, v248
	v_and_b32_e32 v248, 0xffff0000, v117
	v_add_f32_e32 v250, v137, v239
	v_mul_f32_e32 v250, v250, v248
	v_cvt_pk_bf16_f32 v247, v249, v250
	s_nop 1
	v_permlane16_swap_b32_e32 v244, v246
	v_permlane16_swap_b32_e32 v245, v247
	global_store_dwordx4 v[158:159], v[244:247], off offset:-64
	s_waitcnt lgkmcnt(0)
	v_mfma_f32_16x16x32_bf16 v[232:235], v[48:51], v[80:83], 0
	v_mfma_f32_16x16x32_bf16 v[236:239], v[64:67], v[80:83], 0
	v_mfma_f32_16x16x32_bf16 v[232:235], v[52:55], v[76:79], v[232:235]
	v_mfma_f32_16x16x32_bf16 v[236:239], v[68:71], v[76:79], v[236:239]
	v_mfma_f32_16x16x32_bf16 v[232:235], v[56:59], v[84:87], v[232:235]
	v_mfma_f32_16x16x32_bf16 v[236:239], v[72:75], v[84:87], v[236:239]
	v_mfma_f32_16x16x32_bf16 v[232:235], v[60:63], v[88:91], v[232:235]
	v_mfma_f32_16x16x32_bf16 v[236:239], v[142:145], v[88:91], v[236:239]
	v_lshlrev_b32_e32 v248, 16, v114
	v_add_f32_e32 v249, v137, v224
	v_mul_f32_e32 v249, v249, v248
	v_and_b32_e32 v248, 0xffff0000, v114
	v_add_f32_e32 v250, v137, v225
	v_mul_f32_e32 v250, v250, v248
	v_cvt_pk_bf16_f32 v240, v249, v250
	v_lshlrev_b32_e32 v248, 16, v115
	v_add_f32_e32 v249, v137, v226
	v_mul_f32_e32 v249, v249, v248
	v_and_b32_e32 v248, 0xffff0000, v115
	v_add_f32_e32 v250, v137, v227
	v_mul_f32_e32 v250, v250, v248
	v_cvt_pk_bf16_f32 v241, v249, v250
	v_lshlrev_b32_e32 v248, 16, v112
	v_add_f32_e32 v249, v137, v228
	v_mul_f32_e32 v249, v249, v248
	v_and_b32_e32 v248, 0xffff0000, v112
	v_add_f32_e32 v250, v137, v229
	v_mul_f32_e32 v250, v250, v248
	v_cvt_pk_bf16_f32 v242, v249, v250
	v_lshlrev_b32_e32 v248, 16, v113
	v_add_f32_e32 v249, v137, v230
	v_mul_f32_e32 v249, v249, v248
	v_and_b32_e32 v248, 0xffff0000, v113
	v_add_f32_e32 v250, v137, v231
	v_mul_f32_e32 v250, v250, v248
	v_cvt_pk_bf16_f32 v243, v249, v250
	s_nop 1
	v_permlane16_swap_b32_e32 v240, v242
	v_permlane16_swap_b32_e32 v241, v243
	global_store_dwordx4 v[158:159], v[240:243], off offset:0
	s_nop 7
	s_nop 7
	v_lshlrev_b32_e32 v248, 16, v110
	v_add_f32_e32 v249, v137, v232
	v_mul_f32_e32 v249, v249, v248
	v_and_b32_e32 v248, 0xffff0000, v110
	v_add_f32_e32 v250, v137, v233
	v_mul_f32_e32 v250, v250, v248
	v_cvt_pk_bf16_f32 v244, v249, v250
	v_lshlrev_b32_e32 v248, 16, v111
	v_add_f32_e32 v249, v137, v234
	v_mul_f32_e32 v249, v249, v248
	v_and_b32_e32 v248, 0xffff0000, v111
	v_add_f32_e32 v250, v137, v235
	v_mul_f32_e32 v250, v250, v248
	v_cvt_pk_bf16_f32 v245, v249, v250
	v_lshlrev_b32_e32 v248, 16, v108
	v_add_f32_e32 v249, v137, v236
	v_mul_f32_e32 v249, v249, v248
	v_and_b32_e32 v248, 0xffff0000, v108
	v_add_f32_e32 v250, v137, v237
	v_mul_f32_e32 v250, v250, v248
	v_cvt_pk_bf16_f32 v246, v249, v250
	v_lshlrev_b32_e32 v248, 16, v109
	v_add_f32_e32 v249, v137, v238
	v_mul_f32_e32 v249, v249, v248
	v_and_b32_e32 v248, 0xffff0000, v109
	v_add_f32_e32 v250, v137, v239
	v_mul_f32_e32 v250, v250, v248
	v_cvt_pk_bf16_f32 v247, v249, v250
	s_nop 1
	v_permlane16_swap_b32_e32 v244, v246
	v_permlane16_swap_b32_e32 v245, v247
	global_store_dwordx4 v[158:159], v[244:247], off offset:64
	s_waitcnt vmcnt(4)
	s_branch .LBB0_506

.LBB0_868:
.LBB0_869:
	s_add_i32 s0, 0, 0x23f94
	s_waitcnt vmcnt(0)
	v_mov_b32_e32 v0, s0
	v_mbcnt_lo_u32_b32 v58, -1, 0
	v_mbcnt_hi_u32_b32 v58, -1, v58
	ds_read_b32 v0, v0
	v_lshlrev_b32_e32 v71, 4, v58
	v_and_b32_e32 v59, 15, v58
	s_mov_b32 s1, 0
	v_ashrrev_i32_e32 v70, 4, v58
	s_waitcnt lgkmcnt(0)
	v_readfirstlane_b32 s0, v0
	s_and_b32 s4, s0, 7
	s_mul_i32 s5, s4, 0x1400000
	s_add_u32 s5, s94, s5
	s_addc_u32 s6, s95, 0
	s_lshl_b32 s4, s4, 22
	s_sub_u32 s4, 0, s4
	s_subb_u32 s7, 0, 0
	s_add_u32 s4, s5, s4
	s_addc_u32 s5, s6, s7
	s_lshl_b32 s8, s88, 10
	v_add_u32_e32 v0, s8, v71
	v_ashrrev_i32_e32 v1, 31, v0
	v_lshrrev_b32_e32 v1, 22, v1
	v_add_u32_e32 v1, v0, v1
	v_ashrrev_i32_e32 v1, 10, v1
	v_mul_i32_i24_e32 v2, 0x400, v1
	v_sub_u32_e32 v2, v0, v2
	v_lshrrev_b32_e32 v3, 4, v2
	v_bitop3_b32 v2, v3, v2, 32 bitop3:0x6c
	v_ashrrev_i32_e32 v4, 31, v2
	v_lshrrev_b32_e32 v4, 26, v4
	v_lshlrev_b32_e32 v3, 3, v1
	v_add_u32_e32 v4, v2, v4
	v_and_b32_e32 v3, -16, v3
	v_ashrrev_i32_e32 v5, 6, v4
	v_add_u32_e32 v104, v5, v3
	v_and_b32_e32 v3, 0xc0, v4
	v_lshlrev_b32_e32 v1, 5, v1
	v_sub_u32_e32 v2, v2, v3
	v_mov_b32_e32 v3, 1
	v_and_b32_e32 v1, 32, v1
	v_ashrrev_i16_sdwa v2, v3, sext(v2) dst_sel:DWORD dst_unused:UNUSED_PAD src0_sel:DWORD src1_sel:BYTE_0
	v_add_u32_sdwa v1, v1, sext(v2) dst_sel:DWORD dst_unused:UNUSED_PAD src0_sel:DWORD src1_sel:WORD_0
	v_lshlrev_b32_e32 v2, 10, v104
	v_add_u32_e32 v0, 0x2000, v0
	v_lshl_add_u32 v62, v1, 1, v2
	v_ashrrev_i32_e32 v1, 31, v0
	v_lshrrev_b32_e32 v1, 22, v1
	v_add_u32_e32 v1, v0, v1
	v_ashrrev_i32_e32 v1, 10, v1
	v_mul_i32_i24_e32 v2, 0x400, v1
	v_sub_u32_e32 v0, v0, v2
	v_lshrrev_b32_e32 v2, 4, v0
	s_lshl_b32 s6, s0, 3
	v_bitop3_b32 v0, v2, v0, 32 bitop3:0x6c
	s_and_b32 s6, s6, 56
	s_ashr_i32 s7, s0, 5
	v_ashrrev_i32_e32 v4, 31, v0
	s_add_i32 s9, s6, s7
	v_lshrrev_b32_e32 v4, 26, v4
	s_ashr_i32 s12, s9, 5
	v_lshlrev_b32_e32 v2, 3, v1
	v_add_u32_e32 v4, v0, v4
	s_bfe_u32 s0, s0, 0x20003
	s_lshl_b32 s6, s12, 2
	v_and_b32_e32 v2, -16, v2
	v_ashrrev_i32_e32 v5, 6, v4
	s_or_b32 s6, s6, s0
	v_add_u32_e32 v108, v5, v2
	v_and_b32_e32 v2, 0xffc0, v4
	s_ashr_i32 s7, s6, 31
	v_sub_u32_e32 v0, v0, v2
	s_lshl_b64 s[6:7], s[6:7], 18
	v_lshrrev_b16_e32 v2, 7, v0
	s_add_u32 s10, s94, s6
	v_and_b32_e32 v2, 1, v2
	s_addc_u32 s11, s95, s7
	v_lshlrev_b32_e32 v1, 5, v1
	v_add_u16_e32 v0, v0, v2
	s_add_u32 s6, s10, 0x11400000
	v_and_b32_e32 v1, 32, v1
	v_ashrrev_i16_sdwa v0, v3, sext(v0) dst_sel:DWORD dst_unused:UNUSED_PAD src0_sel:DWORD src1_sel:BYTE_0
	s_addc_u32 s7, s11, 0
	s_lshl_b32 s9, s9, 7
	v_add_u32_sdwa v0, v1, sext(v0) dst_sel:DWORD dst_unused:UNUSED_PAD src0_sel:DWORD src1_sel:WORD_0
	v_lshlrev_b32_e32 v1, 10, v108
	s_lshl_b32 s12, s12, 12
	s_and_b32 s9, s9, 0xf80
	v_lshl_add_u32 v64, v0, 1, v1
	v_lshl_or_b32 v1, s88, 4, v59
	s_or_b32 s9, s12, s9
	v_add_u32_e32 v2, s9, v1
	v_ashrrev_i32_e32 v3, 31, v2
	v_lshlrev_b64 v[2:3], 12, v[2:3]
	s_lshl_b32 s0, s0, 10
	v_lshl_add_u64 v[2:3], s[4:5], 0, v[2:3]
	v_lshlrev_b32_e32 v0, 3, v70
	v_lshl_add_u64 v[2:3], v[2:3], 0, s[0:1]
	s_mov_b64 s[0:1], 0x13000000
	v_ashrrev_i32_e32 v1, 31, v0
	v_lshl_add_u64 v[60:61], v[2:3], 0, s[0:1]
	v_lshl_add_u64 v[0:1], v[0:1], 1, v[60:61]
	s_mov_b64 s[0:1], 0xc00000
	v_lshl_add_u64 v[2:3], v[0:1], 0, s[0:1]
	s_mov_b32 s0, 0xc00000
	v_add_co_u32_e32 v0, vcc, s0, v0
	s_add_i32 s22, s8, 0
	s_nop 0
	v_addc_co_u32_e32 v1, vcc, 0, v1, vcc
	v_mov_b32_e32 v63, 0
	s_mov_b32 m0, s22
	s_add_i32 s21, s22, 0x2000
	global_load_dwordx4 v[72:75], v[2:3], off offset:64
	global_load_dwordx4 v[52:55], v[2:3], off offset:128
	global_load_dwordx4 v[48:51], v[2:3], off offset:192
	global_load_dwordx4 v[44:47], v[2:3], off offset:256
	global_load_dwordx4 v[40:43], v[2:3], off offset:320
	global_load_dwordx4 v[36:39], v[2:3], off offset:384
	global_load_dwordx4 v[32:35], v[2:3], off offset:448
	global_load_dwordx4 v[28:31], v[2:3], off offset:512
	global_load_dwordx4 v[24:27], v[2:3], off offset:576
	global_load_dwordx4 v[20:23], v[2:3], off offset:640
	global_load_dwordx4 v[16:19], v[2:3], off offset:704
	global_load_dwordx4 v[12:15], v[2:3], off offset:768
	global_load_dwordx4 v[8:11], v[2:3], off offset:832
	global_load_dwordx4 v[4:7], v[2:3], off offset:896
	global_load_dwordx4 v[76:79], v[0:1], off
	s_nop 0
	global_load_dwordx4 v[0:3], v[2:3], off offset:960
	v_mov_b32_e32 v65, v63
	global_load_lds_dwordx4 v62, s[6:7]
	v_mov_b32_e32 v240, v62
	s_mov_b32 m0, s21
	v_lshl_add_u64 v[66:67], s[6:7], 0, v[62:63]
	v_lshl_add_u64 v[68:69], s[6:7], 0, v[64:65]
	global_load_lds_dwordx4 v64, s[6:7]
	s_add_i32 s20, s22, 0x4000
	s_mov_b64 s[6:7], 0x80
	s_add_i32 s23, s22, 0x6000
	v_lshl_add_u64 v[56:57], v[66:67], 0, s[6:7]
	s_mov_b32 m0, s20
	s_add_u32 s0, s10, 0x11420000
	global_load_lds_dwordx4 v[56:57], off
	v_lshl_add_u64 v[56:57], v[68:69], 0, s[6:7]
	s_mov_b32 m0, s23
	s_addc_u32 s1, s11, 0
	s_add_i32 s24, s22, 0x8000
	global_load_lds_dwordx4 v[56:57], off
	s_mov_b32 m0, s24
	s_add_i32 s25, s22, 0xa000
	global_load_lds_dwordx4 v62, s[0:1]
	s_mov_b32 m0, s25
	s_mov_b64 s[4:5], 0x180
	global_load_lds_dwordx4 v64, s[0:1]
	s_add_u32 s0, s10, 0x11420080
	s_addc_u32 s1, s11, 0
	s_add_i32 s26, s22, 0xc000
	s_mov_b32 m0, s26
	s_add_i32 s27, s22, 0xe000
	global_load_lds_dwordx4 v62, s[0:1]
	s_mov_b32 m0, s27
	s_add_u32 s8, s10, 0x11c00000
	global_load_lds_dwordx4 v64, s[0:1]
	s_addc_u32 s9, s11, 0
	s_add_i32 s19, s22, 0x10000
	s_mov_b64 s[0:1], 0x100
	v_lshl_add_u64 v[56:57], v[66:67], 0, s[0:1]
	s_mov_b32 m0, s19
	s_add_i32 s13, s22, 0x12000
	s_waitcnt vmcnt(0)
	s_waitcnt vmcnt(0) lgkmcnt(0)
	s_barrier
	global_load_lds_dwordx4 v[56:57], off
	v_lshl_add_u64 v[56:57], v[68:69], 0, s[0:1]
	s_mov_b32 m0, s13
	s_add_i32 s12, s22, 0x14000
	s_add_i32 s14, s22, 0x16000
	global_load_lds_dwordx4 v[56:57], off
	v_lshl_add_u64 v[56:57], v[66:67], 0, s[4:5]
	s_mov_b32 m0, s12
	s_add_u32 s28, s10, 0x11420100
	global_load_lds_dwordx4 v[56:57], off
	v_lshl_add_u64 v[56:57], v[68:69], 0, s[4:5]
	s_mov_b32 m0, s14
	s_addc_u32 s29, s11, 0
	s_add_i32 s15, s22, 0x18000
	global_load_lds_dwordx4 v[56:57], off
	s_mov_b32 m0, s15
	s_add_i32 s16, s22, 0x1a000
	global_load_lds_dwordx4 v62, s[28:29]
	s_mov_b32 m0, s16
	v_and_b32_e32 v57, 48, v58
	global_load_lds_dwordx4 v64, s[28:29]
	s_add_u32 s28, s10, 0x11420180
	s_addc_u32 s29, s11, 0
	s_add_i32 s17, s22, 0x1c000
	s_mov_b32 m0, s17
	s_add_i32 s18, s22, 0x1e000
	global_load_lds_dwordx4 v62, s[28:29]
	s_mov_b32 m0, s18
	v_lshlrev_b32_e32 v58, 2, v58
	global_load_lds_dwordx4 v64, s[28:29]
	v_lshlrev_b32_e32 v56, 6, v59
	v_and_b32_e32 v58, 32, v58
	v_bitop3_b32 v56, v56, v58, v57 bitop3:0x36
	v_and_b32_e32 v57, 0xfffffc00, v71
	v_add3_u32 v65, 0, v56, v57
	v_mov_b32_e32 v71, v65
	ds_read_b128 v[56:59], v71
	ds_read_b128 v[80:83], v71 offset:2048
	s_waitcnt lgkmcnt(0)
	v_mfma_f32_16x16x32_bf16 v[84:87], v[56:59], v[76:79], 0
	ds_read_b128 v[56:59], v71 offset:4096
	ds_read_b128 v[88:91], v71 offset:6144
	ds_read_b128 v[96:99], v71 offset:8192
	ds_read_b128 v[100:103], v71 offset:10240
	s_waitcnt lgkmcnt(0)
	v_mfma_f32_16x16x32_bf16 v[92:95], v[56:59], v[76:79], 0
	v_lshlrev_b32_e32 v56, 9, v104
	ds_read_b128 v[104:107], v71 offset:12288
	v_lshlrev_b32_e32 v57, 9, v108
	ds_read_b128 v[108:111], v71 offset:14336
	ds_read_b128 v[112:115], v71 offset:32768
	ds_read_b128 v[116:119], v71 offset:34816
	ds_read_b128 v[120:123], v71 offset:36864
	ds_read_b128 v[124:127], v71 offset:38912
	ds_read_b128 v[128:131], v71 offset:40960
	ds_read_b128 v[132:135], v71 offset:43008
	ds_read_b128 v[136:139], v71 offset:45056
	ds_read_b128 v[140:143], v71 offset:47104
	v_mfma_f32_16x16x32_bf16 v[80:83], v[80:83], v[76:79], 0
	v_sub_u32_e32 v56, v62, v56
	v_mov_b32_e32 v241, v56
	v_sub_u32_e32 v58, v64, v57
	v_mfma_f32_16x16x32_bf16 v[88:91], v[88:91], v[76:79], 0
	v_mfma_f32_16x16x32_bf16 v[96:99], v[96:99], v[76:79], 0
	v_mfma_f32_16x16x32_bf16 v[100:103], v[100:103], v[76:79], 0
	s_waitcnt lgkmcnt(0)
	v_mfma_f32_16x16x32_bf16 v[104:107], v[104:107], v[76:79], 0
	v_mfma_f32_16x16x32_bf16 v[108:111], v[108:111], v[76:79], 0
	ds_read_b128 v[144:147], v71 offset:15360
	ds_read_b128 v[148:151], v71 offset:13312
	ds_read_b128 v[152:155], v71 offset:11264
	ds_read_b128 v[156:159], v71 offset:9216
	ds_read_b128 v[160:163], v71 offset:7168
	ds_read_b128 v[164:167], v71 offset:5120
	ds_read_b128 v[168:171], v71 offset:3072
	ds_read_b128 v[172:175], v71 offset:1024
	v_mfma_f32_16x16x32_bf16 v[112:115], v[112:115], v[76:79], 0
	v_mfma_f32_16x16x32_bf16 v[116:119], v[116:119], v[76:79], 0
	v_mfma_f32_16x16x32_bf16 v[120:123], v[120:123], v[76:79], 0
	v_mfma_f32_16x16x32_bf16 v[124:127], v[124:127], v[76:79], 0
	v_mfma_f32_16x16x32_bf16 v[128:131], v[128:131], v[76:79], 0
	v_mfma_f32_16x16x32_bf16 v[132:135], v[132:135], v[76:79], 0
	v_mfma_f32_16x16x32_bf16 v[136:139], v[136:139], v[76:79], 0
	v_mfma_f32_16x16x32_bf16 v[76:79], v[140:143], v[76:79], 0
	s_waitcnt lgkmcnt(0)
	v_mfma_f32_16x16x32_bf16 v[84:87], v[172:175], v[72:75], v[84:87]
	v_mfma_f32_16x16x32_bf16 v[80:83], v[168:171], v[72:75], v[80:83]
	v_mfma_f32_16x16x32_bf16 v[92:95], v[164:167], v[72:75], v[92:95]
	v_mfma_f32_16x16x32_bf16 v[88:91], v[160:163], v[72:75], v[88:91]
	v_mfma_f32_16x16x32_bf16 v[96:99], v[156:159], v[72:75], v[96:99]
	v_mfma_f32_16x16x32_bf16 v[100:103], v[152:155], v[72:75], v[100:103]
	ds_read_b128 v[140:143], v71 offset:33792
	ds_read_b128 v[152:155], v71 offset:35840
	ds_read_b128 v[156:159], v71 offset:37888
	ds_read_b128 v[160:163], v71 offset:39936
	v_mfma_f32_16x16x32_bf16 v[104:107], v[148:151], v[72:75], v[104:107]
	ds_read_b128 v[148:151], v71 offset:41984
	ds_read_b128 v[164:167], v71 offset:44032
	ds_read_b128 v[168:171], v71 offset:46080
	ds_read_b128 v[172:175], v71 offset:48128
	v_mfma_f32_16x16x32_bf16 v[108:111], v[144:147], v[72:75], v[108:111]
	s_waitcnt lgkmcnt(0)
	v_mfma_f32_16x16x32_bf16 v[112:115], v[140:143], v[72:75], v[112:115]
	v_mfma_f32_16x16x32_bf16 v[116:119], v[152:155], v[72:75], v[116:119]
	v_mfma_f32_16x16x32_bf16 v[120:123], v[156:159], v[72:75], v[120:123]
	v_mfma_f32_16x16x32_bf16 v[124:127], v[160:163], v[72:75], v[124:127]
	v_mfma_f32_16x16x32_bf16 v[128:131], v[148:151], v[72:75], v[128:131]
	ds_read_b128 v[140:143], v71 offset:30720
	ds_read_b128 v[144:147], v71 offset:28672
	ds_read_b128 v[148:151], v71 offset:26624
	ds_read_b128 v[152:155], v71 offset:24576
	v_mfma_f32_16x16x32_bf16 v[132:135], v[164:167], v[72:75], v[132:135]
	v_mfma_f32_16x16x32_bf16 v[136:139], v[168:171], v[72:75], v[136:139]
	ds_read_b128 v[156:159], v71 offset:22528
	ds_read_b128 v[160:163], v71 offset:20480
	ds_read_b128 v[164:167], v71 offset:18432
	ds_read_b128 v[168:171], v71 offset:16384
	v_mfma_f32_16x16x32_bf16 v[72:75], v[172:175], v[72:75], v[76:79]
	s_waitcnt lgkmcnt(0)
	v_mfma_f32_16x16x32_bf16 v[76:79], v[168:171], v[52:55], v[84:87]
	v_mfma_f32_16x16x32_bf16 v[80:83], v[164:167], v[52:55], v[80:83]
	v_mfma_f32_16x16x32_bf16 v[84:87], v[160:163], v[52:55], v[92:95]
	v_mfma_f32_16x16x32_bf16 v[88:91], v[156:159], v[52:55], v[88:91]
	v_mfma_f32_16x16x32_bf16 v[92:95], v[152:155], v[52:55], v[96:99]
	v_mfma_f32_16x16x32_bf16 v[96:99], v[148:151], v[52:55], v[100:103]
	s_nop 2
	ds_read_b128 v[100:103], v71 offset:49152
	ds_read_b128 v[148:151], v71 offset:51200
	ds_read_b128 v[152:155], v71 offset:53248
	ds_read_b128 v[156:159], v71 offset:55296
	v_mfma_f32_16x16x32_bf16 v[104:107], v[144:147], v[52:55], v[104:107]
	ds_read_b128 v[144:147], v71 offset:57344
	ds_read_b128 v[160:163], v71 offset:59392
	ds_read_b128 v[164:167], v71 offset:61440
	ds_read_b128 v[168:171], v71 offset:63488
	v_mfma_f32_16x16x32_bf16 v[108:111], v[140:143], v[52:55], v[108:111]
	s_waitcnt lgkmcnt(0)
	v_mfma_f32_16x16x32_bf16 v[100:103], v[100:103], v[52:55], v[112:115]
	v_mfma_f32_16x16x32_bf16 v[112:115], v[148:151], v[52:55], v[116:119]
	v_mfma_f32_16x16x32_bf16 v[116:119], v[152:155], v[52:55], v[120:123]
	v_mfma_f32_16x16x32_bf16 v[120:123], v[156:159], v[52:55], v[124:127]
	v_mfma_f32_16x16x32_bf16 v[124:127], v[144:147], v[52:55], v[128:131]
	v_mfma_f32_16x16x32_bf16 v[128:131], v[160:163], v[52:55], v[132:135]
	s_nop 2
	ds_read_b128 v[132:135], v71 offset:31744
	ds_read_b128 v[140:143], v71 offset:29696
	ds_read_b128 v[144:147], v71 offset:27648
	ds_read_b128 v[148:151], v71 offset:25600
	v_mfma_f32_16x16x32_bf16 v[136:139], v[164:167], v[52:55], v[136:139]
	ds_read_b128 v[152:155], v71 offset:23552
	ds_read_b128 v[156:159], v71 offset:21504
	ds_read_b128 v[160:163], v71 offset:19456
	ds_read_b128 v[164:167], v71 offset:17408
	v_mfma_f32_16x16x32_bf16 v[52:55], v[168:171], v[52:55], v[72:75]
	s_waitcnt lgkmcnt(0)
	v_mfma_f32_16x16x32_bf16 v[72:75], v[164:167], v[48:51], v[76:79]
	v_mfma_f32_16x16x32_bf16 v[76:79], v[160:163], v[48:51], v[80:83]
	v_mfma_f32_16x16x32_bf16 v[80:83], v[156:159], v[48:51], v[84:87]
	v_mfma_f32_16x16x32_bf16 v[84:87], v[152:155], v[48:51], v[88:91]
	v_mfma_f32_16x16x32_bf16 v[88:91], v[148:151], v[48:51], v[92:95]
	v_mfma_f32_16x16x32_bf16 v[92:95], v[144:147], v[48:51], v[96:99]
	s_nop 2
	ds_read_b128 v[96:99], v71 offset:50176
	ds_read_b128 v[144:147], v71 offset:52224
	ds_read_b128 v[148:151], v71 offset:54272
	ds_read_b128 v[152:155], v71 offset:56320
	v_mfma_f32_16x16x32_bf16 v[104:107], v[140:143], v[48:51], v[104:107]
	ds_read_b128 v[140:143], v71 offset:58368
	ds_read_b128 v[156:159], v71 offset:60416
	ds_read_b128 v[160:163], v71 offset:62464
	ds_read_b128 v[164:167], v71 offset:64512
	v_mfma_f32_16x16x32_bf16 v[108:111], v[132:135], v[48:51], v[108:111]
	s_waitcnt lgkmcnt(0)
	v_mfma_f32_16x16x32_bf16 v[96:99], v[96:99], v[48:51], v[100:103]
	v_mfma_f32_16x16x32_bf16 v[100:103], v[144:147], v[48:51], v[112:115]
	v_mfma_f32_16x16x32_bf16 v[112:115], v[148:151], v[48:51], v[116:119]
	v_mfma_f32_16x16x32_bf16 v[116:119], v[152:155], v[48:51], v[120:123]
	v_mfma_f32_16x16x32_bf16 v[120:123], v[140:143], v[48:51], v[124:127]
	v_mfma_f32_16x16x32_bf16 v[124:127], v[156:159], v[48:51], v[128:131]
	v_mfma_f32_16x16x32_bf16 v[128:131], v[160:163], v[48:51], v[136:139]
	v_mfma_f32_16x16x32_bf16 v[50:53], v[164:167], v[48:51], v[52:55]
	s_waitcnt vmcnt(0)
	s_waitcnt vmcnt(0)
	s_barrier
	v_add_u32_e32 v48, 0x10000, v65
	v_mov_b32_e32 v49, v48
	ds_read_b128 v[132:135], v49
	ds_read_b128 v[136:139], v49 offset:2048
	s_waitcnt lgkmcnt(0)
	v_mfma_f32_16x16x32_bf16 v[72:75], v[132:135], v[44:47], v[72:75]
	ds_read_b128 v[132:135], v49 offset:4096
	v_mfma_f32_16x16x32_bf16 v[76:79], v[136:139], v[44:47], v[76:79]
	ds_read_b128 v[136:139], v49 offset:6144
	s_waitcnt lgkmcnt(0)
	v_mfma_f32_16x16x32_bf16 v[80:83], v[132:135], v[44:47], v[80:83]
	ds_read_b128 v[132:135], v49 offset:8192
	v_mfma_f32_16x16x32_bf16 v[84:87], v[136:139], v[44:47], v[84:87]
	ds_read_b128 v[136:139], v49 offset:10240
	s_waitcnt lgkmcnt(0)
	v_mfma_f32_16x16x32_bf16 v[88:91], v[132:135], v[44:47], v[88:91]
	ds_read_b128 v[132:135], v49 offset:12288
	ds_read_b128 v[140:143], v49 offset:14336
	v_mfma_f32_16x16x32_bf16 v[92:95], v[136:139], v[44:47], v[92:95]
	ds_read_b128 v[136:139], v49 offset:32768
	ds_read_b128 v[144:147], v49 offset:34816
	ds_read_b128 v[148:151], v49 offset:36864
	ds_read_b128 v[152:155], v49 offset:38912
	s_waitcnt lgkmcnt(0)
	v_mfma_f32_16x16x32_bf16 v[104:107], v[132:135], v[44:47], v[104:107]
	ds_read_b128 v[132:135], v49 offset:40960
	ds_read_b128 v[156:159], v49 offset:43008
	ds_read_b128 v[160:163], v49 offset:45056
	ds_read_b128 v[164:167], v49 offset:47104
	v_mfma_f32_16x16x32_bf16 v[108:111], v[140:143], v[44:47], v[108:111]
	s_add_u32 s100, s10, 0x11400200
	s_addc_u32 s101, s11, 0
	s_mov_b32 m0, s22
	s_nop 0
	global_load_lds_dwordx4 v240, s[100:101]
	v_mfma_f32_16x16x32_bf16 v[96:99], v[136:139], v[44:47], v[96:99]
	v_mfma_f32_16x16x32_bf16 v[100:103], v[144:147], v[44:47], v[100:103]
	v_mfma_f32_16x16x32_bf16 v[112:115], v[148:151], v[44:47], v[112:115]
	v_mfma_f32_16x16x32_bf16 v[116:119], v[152:155], v[44:47], v[116:119]
	s_waitcnt lgkmcnt(0)
	v_mfma_f32_16x16x32_bf16 v[120:123], v[132:135], v[44:47], v[120:123]
	ds_read_b128 v[132:135], v49 offset:15360
	ds_read_b128 v[136:139], v49 offset:13312
	ds_read_b128 v[140:143], v49 offset:11264
	ds_read_b128 v[144:147], v49 offset:9216
	v_mfma_f32_16x16x32_bf16 v[124:127], v[156:159], v[44:47], v[124:127]
	v_mfma_f32_16x16x32_bf16 v[128:131], v[160:163], v[44:47], v[128:131]
	ds_read_b128 v[148:151], v49 offset:7168
	ds_read_b128 v[152:155], v49 offset:5120
	ds_read_b128 v[156:159], v49 offset:3072
	ds_read_b128 v[160:163], v49 offset:1024
	v_mfma_f32_16x16x32_bf16 v[44:47], v[164:167], v[44:47], v[50:53]
	s_add_u32 s100, s10, 0x11410200
	s_addc_u32 s101, s11, 0
	s_mov_b32 m0, s21
	s_nop 0
	global_load_lds_dwordx4 v240, s[100:101]
	s_waitcnt lgkmcnt(0)
	v_mfma_f32_16x16x32_bf16 v[50:53], v[160:163], v[40:43], v[72:75]
	v_mfma_f32_16x16x32_bf16 v[72:75], v[156:159], v[40:43], v[76:79]
	v_mfma_f32_16x16x32_bf16 v[76:79], v[152:155], v[40:43], v[80:83]
	v_mfma_f32_16x16x32_bf16 v[80:83], v[148:151], v[40:43], v[84:87]
	v_mfma_f32_16x16x32_bf16 v[84:87], v[144:147], v[40:43], v[88:91]
	v_mfma_f32_16x16x32_bf16 v[88:91], v[140:143], v[40:43], v[92:95]
	s_nop 2
	ds_read_b128 v[92:95], v49 offset:33792
	ds_read_b128 v[140:143], v49 offset:35840
	ds_read_b128 v[144:147], v49 offset:37888
	ds_read_b128 v[148:151], v49 offset:39936
	v_mfma_f32_16x16x32_bf16 v[104:107], v[136:139], v[40:43], v[104:107]
	ds_read_b128 v[136:139], v49 offset:41984
	ds_read_b128 v[152:155], v49 offset:44032
	ds_read_b128 v[156:159], v49 offset:46080
	ds_read_b128 v[160:163], v49 offset:48128
	v_mfma_f32_16x16x32_bf16 v[108:111], v[132:135], v[40:43], v[108:111]
	s_add_u32 s100, s10, 0x11400280
	s_addc_u32 s101, s11, 0
	s_mov_b32 m0, s20
	s_nop 0
	global_load_lds_dwordx4 v240, s[100:101]
	s_waitcnt lgkmcnt(0)
	v_mfma_f32_16x16x32_bf16 v[92:95], v[92:95], v[40:43], v[96:99]
	v_mfma_f32_16x16x32_bf16 v[96:99], v[140:143], v[40:43], v[100:103]
	v_mfma_f32_16x16x32_bf16 v[100:103], v[144:147], v[40:43], v[112:115]
	v_mfma_f32_16x16x32_bf16 v[112:115], v[148:151], v[40:43], v[116:119]
	v_mfma_f32_16x16x32_bf16 v[116:119], v[136:139], v[40:43], v[120:123]
	v_mfma_f32_16x16x32_bf16 v[120:123], v[152:155], v[40:43], v[124:127]
	s_nop 2
	ds_read_b128 v[124:127], v49 offset:30720
	ds_read_b128 v[132:135], v49 offset:28672
	ds_read_b128 v[136:139], v49 offset:26624
	ds_read_b128 v[140:143], v49 offset:24576
	v_mfma_f32_16x16x32_bf16 v[128:131], v[156:159], v[40:43], v[128:131]
	ds_read_b128 v[144:147], v49 offset:22528
	ds_read_b128 v[148:151], v49 offset:20480
	ds_read_b128 v[152:155], v49 offset:18432
	ds_read_b128 v[156:159], v49 offset:16384
	v_mfma_f32_16x16x32_bf16 v[40:43], v[160:163], v[40:43], v[44:47]
	s_add_u32 s100, s10, 0x11410280
	s_addc_u32 s101, s11, 0
	s_mov_b32 m0, s23
	s_nop 0
	global_load_lds_dwordx4 v240, s[100:101]
	s_waitcnt lgkmcnt(0)
	v_mfma_f32_16x16x32_bf16 v[44:47], v[156:159], v[36:39], v[50:53]
	v_mfma_f32_16x16x32_bf16 v[50:53], v[152:155], v[36:39], v[72:75]
	v_mfma_f32_16x16x32_bf16 v[72:75], v[148:151], v[36:39], v[76:79]
	v_mfma_f32_16x16x32_bf16 v[76:79], v[144:147], v[36:39], v[80:83]
	v_mfma_f32_16x16x32_bf16 v[80:83], v[140:143], v[36:39], v[84:87]
	v_mfma_f32_16x16x32_bf16 v[84:87], v[136:139], v[36:39], v[88:91]
	s_nop 2
	ds_read_b128 v[88:91], v49 offset:49152
	ds_read_b128 v[136:139], v49 offset:51200
	ds_read_b128 v[140:143], v49 offset:53248
	ds_read_b128 v[144:147], v49 offset:55296
	v_mfma_f32_16x16x32_bf16 v[104:107], v[132:135], v[36:39], v[104:107]
	ds_read_b128 v[132:135], v49 offset:57344
	ds_read_b128 v[148:151], v49 offset:59392
	ds_read_b128 v[152:155], v49 offset:61440
	ds_read_b128 v[156:159], v49 offset:63488
	v_mfma_f32_16x16x32_bf16 v[108:111], v[124:127], v[36:39], v[108:111]
	s_add_u32 s100, s10, 0x11420200
	s_addc_u32 s101, s11, 0
	s_mov_b32 m0, s24
	s_nop 0
	global_load_lds_dwordx4 v240, s[100:101]
	s_waitcnt lgkmcnt(0)
	v_mfma_f32_16x16x32_bf16 v[88:91], v[88:91], v[36:39], v[92:95]
	v_mfma_f32_16x16x32_bf16 v[92:95], v[136:139], v[36:39], v[96:99]
	v_mfma_f32_16x16x32_bf16 v[96:99], v[140:143], v[36:39], v[100:103]
	v_mfma_f32_16x16x32_bf16 v[100:103], v[144:147], v[36:39], v[112:115]
	v_mfma_f32_16x16x32_bf16 v[112:115], v[132:135], v[36:39], v[116:119]
	v_mfma_f32_16x16x32_bf16 v[116:119], v[148:151], v[36:39], v[120:123]
	s_nop 2
	ds_read_b128 v[120:123], v49 offset:31744
	ds_read_b128 v[124:127], v49 offset:29696
	ds_read_b128 v[132:135], v49 offset:27648
	ds_read_b128 v[136:139], v49 offset:25600
	v_mfma_f32_16x16x32_bf16 v[128:131], v[152:155], v[36:39], v[128:131]
	ds_read_b128 v[140:143], v49 offset:23552
	ds_read_b128 v[144:147], v49 offset:21504
	ds_read_b128 v[148:151], v49 offset:19456
	ds_read_b128 v[152:155], v49 offset:17408
	v_mfma_f32_16x16x32_bf16 v[36:39], v[156:159], v[36:39], v[40:43]
	s_add_u32 s100, s10, 0x11430200
	s_addc_u32 s101, s11, 0
	s_mov_b32 m0, s25
	s_nop 0
	global_load_lds_dwordx4 v240, s[100:101]
	s_waitcnt lgkmcnt(0)
	v_mfma_f32_16x16x32_bf16 v[40:43], v[152:155], v[32:35], v[44:47]
	v_mfma_f32_16x16x32_bf16 v[44:47], v[148:151], v[32:35], v[50:53]
	v_mfma_f32_16x16x32_bf16 v[50:53], v[144:147], v[32:35], v[72:75]
	v_mfma_f32_16x16x32_bf16 v[72:75], v[140:143], v[32:35], v[76:79]
	v_mfma_f32_16x16x32_bf16 v[76:79], v[136:139], v[32:35], v[80:83]
	v_mfma_f32_16x16x32_bf16 v[80:83], v[132:135], v[32:35], v[84:87]
	s_nop 2
	ds_read_b128 v[84:87], v49 offset:50176
	ds_read_b128 v[132:135], v49 offset:52224
	ds_read_b128 v[136:139], v49 offset:54272
	ds_read_b128 v[140:143], v49 offset:56320
	v_mfma_f32_16x16x32_bf16 v[104:107], v[124:127], v[32:35], v[104:107]
	ds_read_b128 v[124:127], v49 offset:58368
	ds_read_b128 v[144:147], v49 offset:60416
	ds_read_b128 v[148:151], v49 offset:62464
	ds_read_b128 v[152:155], v49 offset:64512
	v_mfma_f32_16x16x32_bf16 v[108:111], v[120:123], v[32:35], v[108:111]
	s_add_u32 s100, s10, 0x11420280
	s_addc_u32 s101, s11, 0
	s_mov_b32 m0, s26
	s_nop 0
	global_load_lds_dwordx4 v240, s[100:101]
	s_waitcnt lgkmcnt(0)
	v_mfma_f32_16x16x32_bf16 v[84:87], v[84:87], v[32:35], v[88:91]
	v_mfma_f32_16x16x32_bf16 v[88:91], v[132:135], v[32:35], v[92:95]
	v_mfma_f32_16x16x32_bf16 v[92:95], v[136:139], v[32:35], v[96:99]
	v_mfma_f32_16x16x32_bf16 v[96:99], v[140:143], v[32:35], v[100:103]
	v_mfma_f32_16x16x32_bf16 v[100:103], v[124:127], v[32:35], v[112:115]
	v_mfma_f32_16x16x32_bf16 v[112:115], v[144:147], v[32:35], v[116:119]
	v_mfma_f32_16x16x32_bf16 v[116:119], v[148:151], v[32:35], v[128:131]
	v_mfma_f32_16x16x32_bf16 v[32:35], v[152:155], v[32:35], v[36:39]
	s_add_u32 s100, s10, 0x11430280
	s_addc_u32 s101, s11, 0
	s_mov_b32 m0, s27
	s_nop 0
	global_load_lds_dwordx4 v240, s[100:101]
	s_nop 0
	s_waitcnt vmcnt(0)
	s_waitcnt vmcnt(0)
	s_barrier
	v_mov_b32_e32 v49, v65
	ds_read_b128 v[36:39], v49
	ds_read_b128 v[66:69], v49 offset:2048
	s_waitcnt lgkmcnt(0)
	v_mfma_f32_16x16x32_bf16 v[36:39], v[36:39], v[28:31], v[40:43]
	s_nop 2
	ds_read_b128 v[40:43], v49 offset:4096
	v_mfma_f32_16x16x32_bf16 v[44:47], v[66:69], v[28:31], v[44:47]
	ds_read_b128 v[66:69], v49 offset:6144
	s_waitcnt lgkmcnt(0)
	v_mfma_f32_16x16x32_bf16 v[40:43], v[40:43], v[28:31], v[50:53]
	s_nop 2
	ds_read_b128 v[50:53], v49 offset:8192
	v_mfma_f32_16x16x32_bf16 v[66:69], v[66:69], v[28:31], v[72:75]
	s_nop 2
	ds_read_b128 v[72:75], v49 offset:10240
	s_waitcnt lgkmcnt(0)
	v_mfma_f32_16x16x32_bf16 v[50:53], v[50:53], v[28:31], v[76:79]
	s_nop 2
	ds_read_b128 v[76:79], v49 offset:12288
	ds_read_b128 v[120:123], v49 offset:14336
	v_mfma_f32_16x16x32_bf16 v[72:75], v[72:75], v[28:31], v[80:83]
	s_nop 2
	ds_read_b128 v[80:83], v49 offset:32768
	ds_read_b128 v[124:127], v49 offset:34816
	ds_read_b128 v[128:131], v49 offset:36864
	ds_read_b128 v[132:135], v49 offset:38912
	s_waitcnt lgkmcnt(0)
	v_mfma_f32_16x16x32_bf16 v[76:79], v[76:79], v[28:31], v[104:107]
	s_nop 2
	ds_read_b128 v[104:107], v49 offset:40960
	ds_read_b128 v[136:139], v49 offset:43008
	ds_read_b128 v[140:143], v49 offset:45056
	ds_read_b128 v[144:147], v49 offset:47104
	v_mfma_f32_16x16x32_bf16 v[108:111], v[120:123], v[28:31], v[108:111]
	s_add_u32 s100, s10, 0x11400300
	s_addc_u32 s101, s11, 0
	s_mov_b32 m0, s19
	s_nop 0
	global_load_lds_dwordx4 v240, s[100:101]
	v_mfma_f32_16x16x32_bf16 v[80:83], v[80:83], v[28:31], v[84:87]
	v_mfma_f32_16x16x32_bf16 v[84:87], v[124:127], v[28:31], v[88:91]
	v_mfma_f32_16x16x32_bf16 v[88:91], v[128:131], v[28:31], v[92:95]
	v_mfma_f32_16x16x32_bf16 v[92:95], v[132:135], v[28:31], v[96:99]
	s_waitcnt lgkmcnt(0)
	v_mfma_f32_16x16x32_bf16 v[96:99], v[104:107], v[28:31], v[100:103]
	v_mfma_f32_16x16x32_bf16 v[100:103], v[136:139], v[28:31], v[112:115]
	ds_read_b128 v[104:107], v49 offset:15360
	s_nop 1
	ds_read_b128 v[112:115], v49 offset:13312
	ds_read_b128 v[120:123], v49 offset:11264
	ds_read_b128 v[124:127], v49 offset:9216
	v_mfma_f32_16x16x32_bf16 v[116:119], v[140:143], v[28:31], v[116:119]
	ds_read_b128 v[128:131], v49 offset:7168
	ds_read_b128 v[132:135], v49 offset:5120
	ds_read_b128 v[136:139], v49 offset:3072
	ds_read_b128 v[140:143], v49 offset:1024
	v_mfma_f32_16x16x32_bf16 v[28:31], v[144:147], v[28:31], v[32:35]
	s_add_u32 s100, s10, 0x11410300
	s_addc_u32 s101, s11, 0
	s_mov_b32 m0, s13
	s_nop 0
	global_load_lds_dwordx4 v240, s[100:101]
	s_waitcnt lgkmcnt(0)
	v_mfma_f32_16x16x32_bf16 v[32:35], v[140:143], v[24:27], v[36:39]
	v_mfma_f32_16x16x32_bf16 v[36:39], v[136:139], v[24:27], v[44:47]
	v_mfma_f32_16x16x32_bf16 v[40:43], v[132:135], v[24:27], v[40:43]
	v_mfma_f32_16x16x32_bf16 v[44:47], v[128:131], v[24:27], v[66:69]
	v_mfma_f32_16x16x32_bf16 v[50:53], v[124:127], v[24:27], v[50:53]
	v_mfma_f32_16x16x32_bf16 v[66:69], v[120:123], v[24:27], v[72:75]
	s_nop 2
	ds_read_b128 v[72:75], v49 offset:33792
	ds_read_b128 v[120:123], v49 offset:35840
	ds_read_b128 v[124:127], v49 offset:37888
	ds_read_b128 v[128:131], v49 offset:39936
	v_mfma_f32_16x16x32_bf16 v[76:79], v[112:115], v[24:27], v[76:79]
	ds_read_b128 v[112:115], v49 offset:41984
	ds_read_b128 v[132:135], v49 offset:44032
	ds_read_b128 v[136:139], v49 offset:46080
	ds_read_b128 v[140:143], v49 offset:48128
	v_mfma_f32_16x16x32_bf16 v[104:107], v[104:107], v[24:27], v[108:111]
	s_add_u32 s100, s10, 0x11400380
	s_addc_u32 s101, s11, 0
	s_mov_b32 m0, s12
	s_nop 0
	global_load_lds_dwordx4 v240, s[100:101]
	s_waitcnt lgkmcnt(0)
	v_mfma_f32_16x16x32_bf16 v[72:75], v[72:75], v[24:27], v[80:83]
	v_mfma_f32_16x16x32_bf16 v[80:83], v[120:123], v[24:27], v[84:87]
	v_mfma_f32_16x16x32_bf16 v[84:87], v[124:127], v[24:27], v[88:91]
	v_mfma_f32_16x16x32_bf16 v[88:91], v[128:131], v[24:27], v[92:95]
	v_mfma_f32_16x16x32_bf16 v[92:95], v[112:115], v[24:27], v[96:99]
	v_mfma_f32_16x16x32_bf16 v[96:99], v[132:135], v[24:27], v[100:103]
	s_nop 2
	ds_read_b128 v[100:103], v49 offset:30720
	ds_read_b128 v[108:111], v49 offset:28672
	ds_read_b128 v[112:115], v49 offset:26624
	ds_read_b128 v[120:123], v49 offset:24576
	v_mfma_f32_16x16x32_bf16 v[116:119], v[136:139], v[24:27], v[116:119]
	ds_read_b128 v[124:127], v49 offset:22528
	ds_read_b128 v[128:131], v49 offset:20480
	ds_read_b128 v[132:135], v49 offset:18432
	ds_read_b128 v[136:139], v49 offset:16384
	v_mfma_f32_16x16x32_bf16 v[24:27], v[140:143], v[24:27], v[28:31]
	s_add_u32 s100, s10, 0x11410380
	s_addc_u32 s101, s11, 0
	s_mov_b32 m0, s14
	s_nop 0
	global_load_lds_dwordx4 v240, s[100:101]
	s_waitcnt lgkmcnt(0)
	v_mfma_f32_16x16x32_bf16 v[28:31], v[136:139], v[20:23], v[32:35]
	v_mfma_f32_16x16x32_bf16 v[32:35], v[132:135], v[20:23], v[36:39]
	v_mfma_f32_16x16x32_bf16 v[36:39], v[128:131], v[20:23], v[40:43]
	v_mfma_f32_16x16x32_bf16 v[40:43], v[124:127], v[20:23], v[44:47]
	v_mfma_f32_16x16x32_bf16 v[44:47], v[120:123], v[20:23], v[50:53]
	v_mfma_f32_16x16x32_bf16 v[50:53], v[112:115], v[20:23], v[66:69]
	s_nop 2
	ds_read_b128 v[66:69], v49 offset:49152
	ds_read_b128 v[112:115], v49 offset:51200
	ds_read_b128 v[120:123], v49 offset:53248
	ds_read_b128 v[124:127], v49 offset:55296
	v_mfma_f32_16x16x32_bf16 v[76:79], v[108:111], v[20:23], v[76:79]
	ds_read_b128 v[108:111], v49 offset:57344
	ds_read_b128 v[128:131], v49 offset:59392
	ds_read_b128 v[132:135], v49 offset:61440
	ds_read_b128 v[136:139], v49 offset:63488
	v_mfma_f32_16x16x32_bf16 v[100:103], v[100:103], v[20:23], v[104:107]
	s_add_u32 s100, s10, 0x11420300
	s_addc_u32 s101, s11, 0
	s_mov_b32 m0, s15
	s_nop 0
	global_load_lds_dwordx4 v240, s[100:101]
	s_waitcnt lgkmcnt(0)
	v_mfma_f32_16x16x32_bf16 v[66:69], v[66:69], v[20:23], v[72:75]
	v_mfma_f32_16x16x32_bf16 v[72:75], v[112:115], v[20:23], v[80:83]
	v_mfma_f32_16x16x32_bf16 v[80:83], v[120:123], v[20:23], v[84:87]
	v_mfma_f32_16x16x32_bf16 v[84:87], v[124:127], v[20:23], v[88:91]
	v_mfma_f32_16x16x32_bf16 v[88:91], v[108:111], v[20:23], v[92:95]
	v_mfma_f32_16x16x32_bf16 v[92:95], v[128:131], v[20:23], v[96:99]
	s_nop 2
	ds_read_b128 v[96:99], v49 offset:31744
	ds_read_b128 v[104:107], v49 offset:29696
	ds_read_b128 v[108:111], v49 offset:27648
	ds_read_b128 v[112:115], v49 offset:25600
	v_mfma_f32_16x16x32_bf16 v[116:119], v[132:135], v[20:23], v[116:119]
	ds_read_b128 v[120:123], v49 offset:23552
	ds_read_b128 v[124:127], v49 offset:21504
	ds_read_b128 v[128:131], v49 offset:19456
	ds_read_b128 v[132:135], v49 offset:17408
	v_mfma_f32_16x16x32_bf16 v[20:23], v[136:139], v[20:23], v[24:27]
	s_add_u32 s100, s10, 0x11430300
	s_addc_u32 s101, s11, 0
	s_mov_b32 m0, s16
	s_nop 0
	global_load_lds_dwordx4 v240, s[100:101]
	s_waitcnt lgkmcnt(0)
	v_mfma_f32_16x16x32_bf16 v[24:27], v[132:135], v[16:19], v[28:31]
	v_mfma_f32_16x16x32_bf16 v[28:31], v[128:131], v[16:19], v[32:35]
	v_mfma_f32_16x16x32_bf16 v[32:35], v[124:127], v[16:19], v[36:39]
	v_mfma_f32_16x16x32_bf16 v[36:39], v[120:123], v[16:19], v[40:43]
	v_mfma_f32_16x16x32_bf16 v[40:43], v[112:115], v[16:19], v[44:47]
	v_mfma_f32_16x16x32_bf16 v[50:53], v[108:111], v[16:19], v[50:53]
	s_nop 1
	ds_read_b128 v[44:47], v49 offset:50176
	ds_read_b128 v[108:111], v49 offset:52224
	ds_read_b128 v[112:115], v49 offset:54272
	ds_read_b128 v[120:123], v49 offset:56320
	v_mfma_f32_16x16x32_bf16 v[76:79], v[104:107], v[16:19], v[76:79]
	ds_read_b128 v[104:107], v49 offset:58368
	ds_read_b128 v[124:127], v49 offset:60416
	ds_read_b128 v[128:131], v49 offset:62464
	ds_read_b128 v[132:135], v49 offset:64512
	v_mfma_f32_16x16x32_bf16 v[96:99], v[96:99], v[16:19], v[100:103]
	s_add_u32 s100, s10, 0x11420380
	s_addc_u32 s101, s11, 0
	s_mov_b32 m0, s17
	s_nop 0
	global_load_lds_dwordx4 v240, s[100:101]
	s_waitcnt lgkmcnt(0)
	v_mfma_f32_16x16x32_bf16 v[66:69], v[44:47], v[16:19], v[66:69]
	v_mfma_f32_16x16x32_bf16 v[72:75], v[108:111], v[16:19], v[72:75]
	v_mfma_f32_16x16x32_bf16 v[80:83], v[112:115], v[16:19], v[80:83]
	v_mfma_f32_16x16x32_bf16 v[84:87], v[120:123], v[16:19], v[84:87]
	v_mfma_f32_16x16x32_bf16 v[88:91], v[104:107], v[16:19], v[88:91]
	v_mfma_f32_16x16x32_bf16 v[92:95], v[124:127], v[16:19], v[92:95]
	v_mfma_f32_16x16x32_bf16 v[100:103], v[128:131], v[16:19], v[116:119]
	v_mfma_f32_16x16x32_bf16 v[16:19], v[132:135], v[16:19], v[20:23]
	s_add_u32 s100, s10, 0x11430380
	s_addc_u32 s101, s11, 0
	s_mov_b32 m0, s18
	s_nop 0
	global_load_lds_dwordx4 v240, s[100:101]
	s_waitcnt vmcnt(0)
	s_waitcnt vmcnt(0)
	s_barrier
	v_mov_b32_e32 v49, v48
	ds_read_b128 v[20:23], v49
	ds_read_b128 v[104:107], v49 offset:2048
	s_waitcnt lgkmcnt(0)
	v_mfma_f32_16x16x32_bf16 v[20:23], v[20:23], v[12:15], v[24:27]
	s_nop 2
	ds_read_b128 v[24:27], v49 offset:4096
	v_mfma_f32_16x16x32_bf16 v[28:31], v[104:107], v[12:15], v[28:31]
	ds_read_b128 v[104:107], v49 offset:6144
	s_waitcnt lgkmcnt(0)
	v_mfma_f32_16x16x32_bf16 v[24:27], v[24:27], v[12:15], v[32:35]
	s_nop 2
	ds_read_b128 v[32:35], v49 offset:8192
	v_mfma_f32_16x16x32_bf16 v[36:39], v[104:107], v[12:15], v[36:39]
	ds_read_b128 v[104:107], v49 offset:10240
	s_waitcnt lgkmcnt(0)
	v_mfma_f32_16x16x32_bf16 v[32:35], v[32:35], v[12:15], v[40:43]
	s_nop 2
	ds_read_b128 v[40:43], v49 offset:12288
	ds_read_b128 v[108:111], v49 offset:14336
	v_mfma_f32_16x16x32_bf16 v[50:53], v[104:107], v[12:15], v[50:53]
	ds_read_b128 v[104:107], v49 offset:32768
	ds_read_b128 v[112:115], v49 offset:34816
	ds_read_b128 v[116:119], v49 offset:36864
	ds_read_b128 v[120:123], v49 offset:38912
	s_waitcnt lgkmcnt(0)
	v_mfma_f32_16x16x32_bf16 v[40:43], v[40:43], v[12:15], v[76:79]
	s_nop 2
	ds_read_b128 v[76:79], v49 offset:40960
	ds_read_b128 v[124:127], v49 offset:43008
	ds_read_b128 v[128:131], v49 offset:45056
	ds_read_b128 v[132:135], v49 offset:47104
	v_mfma_f32_16x16x32_bf16 v[96:99], v[108:111], v[12:15], v[96:99]
	s_add_u32 s100, s10, 0x11c00000
	s_addc_u32 s101, s11, 0
	s_mov_b32 m0, s22
	s_nop 0
	global_load_lds_dwordx4 v241, s[100:101]
	v_mfma_f32_16x16x32_bf16 v[66:69], v[104:107], v[12:15], v[66:69]
	v_mfma_f32_16x16x32_bf16 v[72:75], v[112:115], v[12:15], v[72:75]
	v_mfma_f32_16x16x32_bf16 v[80:83], v[116:119], v[12:15], v[80:83]
	v_mfma_f32_16x16x32_bf16 v[84:87], v[120:123], v[12:15], v[84:87]
	s_waitcnt lgkmcnt(0)
	v_mfma_f32_16x16x32_bf16 v[76:79], v[76:79], v[12:15], v[88:91]
	v_mfma_f32_16x16x32_bf16 v[88:91], v[124:127], v[12:15], v[92:95]
	s_nop 2
	ds_read_b128 v[92:95], v49 offset:15360
	ds_read_b128 v[104:107], v49 offset:13312
	ds_read_b128 v[108:111], v49 offset:11264
	ds_read_b128 v[112:115], v49 offset:9216
	v_mfma_f32_16x16x32_bf16 v[100:103], v[128:131], v[12:15], v[100:103]
	ds_read_b128 v[116:119], v49 offset:7168
	ds_read_b128 v[120:123], v49 offset:5120
	ds_read_b128 v[124:127], v49 offset:3072
	ds_read_b128 v[128:131], v49 offset:1024
	v_mfma_f32_16x16x32_bf16 v[12:15], v[132:135], v[12:15], v[16:19]
	s_add_u32 s100, s10, 0x11c08000
	s_addc_u32 s101, s11, 0
	s_mov_b32 m0, s21
	s_nop 0
	global_load_lds_dwordx4 v241, s[100:101]
	s_waitcnt lgkmcnt(0)
	v_mfma_f32_16x16x32_bf16 v[16:19], v[128:131], v[8:11], v[20:23]
	v_mfma_f32_16x16x32_bf16 v[20:23], v[124:127], v[8:11], v[28:31]
	v_mfma_f32_16x16x32_bf16 v[24:27], v[120:123], v[8:11], v[24:27]
	v_mfma_f32_16x16x32_bf16 v[28:31], v[116:119], v[8:11], v[36:39]
	v_mfma_f32_16x16x32_bf16 v[32:35], v[112:115], v[8:11], v[32:35]
	v_mfma_f32_16x16x32_bf16 v[36:39], v[108:111], v[8:11], v[50:53]
	s_nop 2
	ds_read_b128 v[50:53], v49 offset:33792
	ds_read_b128 v[108:111], v49 offset:35840
	ds_read_b128 v[112:115], v49 offset:37888
	ds_read_b128 v[116:119], v49 offset:39936
	v_mfma_f32_16x16x32_bf16 v[40:43], v[104:107], v[8:11], v[40:43]
	ds_read_b128 v[104:107], v49 offset:41984
	ds_read_b128 v[120:123], v49 offset:44032
	ds_read_b128 v[124:127], v49 offset:46080
	ds_read_b128 v[128:131], v49 offset:48128
	v_mfma_f32_16x16x32_bf16 v[92:95], v[92:95], v[8:11], v[96:99]
	s_add_u32 s100, s10, 0x11c00080
	s_addc_u32 s101, s11, 0
	s_mov_b32 m0, s20
	s_nop 0
	global_load_lds_dwordx4 v241, s[100:101]
	s_waitcnt lgkmcnt(0)
	v_mfma_f32_16x16x32_bf16 v[50:53], v[50:53], v[8:11], v[66:69]
	v_mfma_f32_16x16x32_bf16 v[66:69], v[108:111], v[8:11], v[72:75]
	v_mfma_f32_16x16x32_bf16 v[72:75], v[112:115], v[8:11], v[80:83]
	v_mfma_f32_16x16x32_bf16 v[80:83], v[116:119], v[8:11], v[84:87]
	v_mfma_f32_16x16x32_bf16 v[76:79], v[104:107], v[8:11], v[76:79]
	v_mfma_f32_16x16x32_bf16 v[84:87], v[120:123], v[8:11], v[88:91]
	s_nop 2
	ds_read_b128 v[88:91], v49 offset:30720
	ds_read_b128 v[96:99], v49 offset:28672
	ds_read_b128 v[104:107], v49 offset:26624
	ds_read_b128 v[108:111], v49 offset:24576
	v_mfma_f32_16x16x32_bf16 v[100:103], v[124:127], v[8:11], v[100:103]
	ds_read_b128 v[112:115], v49 offset:22528
	ds_read_b128 v[116:119], v49 offset:20480
	ds_read_b128 v[120:123], v49 offset:18432
	ds_read_b128 v[124:127], v49 offset:16384
	v_mfma_f32_16x16x32_bf16 v[8:11], v[128:131], v[8:11], v[12:15]
	s_add_u32 s100, s10, 0x11c08080
	s_addc_u32 s101, s11, 0
	s_mov_b32 m0, s23
	s_nop 0
	global_load_lds_dwordx4 v241, s[100:101]
	s_waitcnt lgkmcnt(0)
	v_mfma_f32_16x16x32_bf16 v[12:15], v[124:127], v[4:7], v[16:19]
	v_mfma_f32_16x16x32_bf16 v[16:19], v[120:123], v[4:7], v[20:23]
	v_mfma_f32_16x16x32_bf16 v[20:23], v[116:119], v[4:7], v[24:27]
	v_mfma_f32_16x16x32_bf16 v[24:27], v[112:115], v[4:7], v[28:31]
	v_mfma_f32_16x16x32_bf16 v[28:31], v[108:111], v[4:7], v[32:35]
	v_mfma_f32_16x16x32_bf16 v[32:35], v[104:107], v[4:7], v[36:39]
	s_nop 2
	ds_read_b128 v[36:39], v49 offset:49152
	ds_read_b128 v[104:107], v49 offset:51200
	ds_read_b128 v[108:111], v49 offset:53248
	ds_read_b128 v[112:115], v49 offset:55296
	v_mfma_f32_16x16x32_bf16 v[96:99], v[96:99], v[4:7], v[40:43]
	s_nop 2
	ds_read_b128 v[40:43], v49 offset:57344
	ds_read_b128 v[116:119], v49 offset:59392
	ds_read_b128 v[120:123], v49 offset:61440
	ds_read_b128 v[124:127], v49 offset:63488
	v_mfma_f32_16x16x32_bf16 v[88:91], v[88:91], v[4:7], v[92:95]
	s_add_u32 s100, s10, 0x11c10000
	s_addc_u32 s101, s11, 0
	s_mov_b32 m0, s24
	s_nop 0
	global_load_lds_dwordx4 v241, s[100:101]
	s_waitcnt lgkmcnt(0)
	v_mfma_f32_16x16x32_bf16 v[50:53], v[36:39], v[4:7], v[50:53]
	v_mfma_f32_16x16x32_bf16 v[66:69], v[104:107], v[4:7], v[66:69]
	v_mfma_f32_16x16x32_bf16 v[72:75], v[108:111], v[4:7], v[72:75]
	v_mfma_f32_16x16x32_bf16 v[80:83], v[112:115], v[4:7], v[80:83]
	v_mfma_f32_16x16x32_bf16 v[76:79], v[40:43], v[4:7], v[76:79]
	ds_read_b128 v[92:95], v49 offset:31744
	ds_read_b128 v[36:39], v49 offset:29696
	ds_read_b128 v[40:43], v49 offset:27648
	ds_read_b128 v[104:107], v49 offset:25600
	v_mfma_f32_16x16x32_bf16 v[84:87], v[116:119], v[4:7], v[84:87]
	v_mfma_f32_16x16x32_bf16 v[100:103], v[120:123], v[4:7], v[100:103]
	ds_read_b128 v[108:111], v49 offset:23552
	ds_read_b128 v[112:115], v49 offset:21504
	ds_read_b128 v[116:119], v49 offset:19456
	ds_read_b128 v[120:123], v49 offset:17408
	v_mfma_f32_16x16x32_bf16 v[124:127], v[124:127], v[4:7], v[8:11]
	s_add_u32 s100, s10, 0x11c18000
	s_addc_u32 s101, s11, 0
	s_mov_b32 m0, s25
	s_nop 0
	global_load_lds_dwordx4 v241, s[100:101]
	s_waitcnt lgkmcnt(0)
	v_mfma_f32_16x16x32_bf16 v[120:123], v[120:123], v[0:3], v[12:15]
	v_mfma_f32_16x16x32_bf16 v[116:119], v[116:119], v[0:3], v[16:19]
	ds_read_b128 v[4:7], v49 offset:50176
	ds_read_b128 v[8:11], v49 offset:52224
	ds_read_b128 v[12:15], v49 offset:54272
	ds_read_b128 v[16:19], v49 offset:56320
	v_mfma_f32_16x16x32_bf16 v[36:39], v[36:39], v[0:3], v[96:99]
	s_nop 2
	ds_read_b128 v[96:99], v49 offset:58368
	ds_read_b128 v[128:131], v49 offset:60416
	ds_read_b128 v[132:135], v49 offset:62464
	ds_read_b128 v[136:139], v49 offset:64512
	v_mfma_f32_16x16x32_bf16 v[112:115], v[112:115], v[0:3], v[20:23]
	v_mfma_f32_16x16x32_bf16 v[108:111], v[108:111], v[0:3], v[24:27]
	v_mfma_f32_16x16x32_bf16 v[104:107], v[104:107], v[0:3], v[28:31]
	v_mfma_f32_16x16x32_bf16 v[40:43], v[40:43], v[0:3], v[32:35]
	v_mfma_f32_16x16x32_bf16 v[32:35], v[92:95], v[0:3], v[88:91]
	s_add_u32 s100, s10, 0x11c10080
	s_addc_u32 s101, s11, 0
	s_mov_b32 m0, s26
	s_nop 0
	global_load_lds_dwordx4 v241, s[100:101]
	s_waitcnt lgkmcnt(0)
	v_mfma_f32_16x16x32_bf16 v[28:31], v[4:7], v[0:3], v[50:53]
	v_mfma_f32_16x16x32_bf16 v[24:27], v[8:11], v[0:3], v[66:69]
	v_mfma_f32_16x16x32_bf16 v[20:23], v[12:15], v[0:3], v[72:75]
	v_mfma_f32_16x16x32_bf16 v[16:19], v[16:19], v[0:3], v[80:83]
	v_mfma_f32_16x16x32_bf16 v[12:15], v[96:99], v[0:3], v[76:79]
	v_mfma_f32_16x16x32_bf16 v[8:11], v[128:131], v[0:3], v[84:87]
	v_mfma_f32_16x16x32_bf16 v[4:7], v[132:135], v[0:3], v[100:103]
	v_mfma_f32_16x16x32_bf16 v[0:3], v[136:139], v[0:3], v[124:127]
	s_add_u32 s100, s10, 0x11c18080
	s_addc_u32 s101, s11, 0
	s_mov_b32 m0, s27
	s_nop 0
	global_load_lds_dwordx4 v241, s[100:101]
	v_max_f32_e32 v49, v123, v123
	v_max_f32_e32 v50, v122, v122
	v_max_f32_e32 v49, v50, v49
	v_max_f32_e32 v50, v117, v117
	v_max_f32_e32 v51, v116, v116
	v_max_f32_e32 v50, v51, v50
	v_max_f32_e32 v51, v119, v119
	v_max_f32_e32 v52, v118, v118
	v_max3_f32 v49, v120, v121, v49
	v_max_f32_e32 v51, v52, v51
	v_max3_f32 v49, v49, v50, v51
	v_max_f32_e32 v50, v113, v113
	v_max_f32_e32 v51, v112, v112
	v_max_f32_e32 v50, v51, v50
	v_max_f32_e32 v51, v115, v115
	v_max_f32_e32 v52, v114, v114
	v_max_f32_e32 v51, v52, v51
	v_max3_f32 v49, v49, v50, v51
	v_max_f32_e32 v50, v109, v109
	v_max_f32_e32 v51, v108, v108
	v_max_f32_e32 v50, v51, v50
	v_max_f32_e32 v51, v111, v111
	v_max_f32_e32 v52, v110, v110
	v_max_f32_e32 v51, v52, v51
	v_max3_f32 v49, v49, v50, v51
	v_max_f32_e32 v50, v105, v105
	v_max_f32_e32 v51, v104, v104
	v_max_f32_e32 v50, v51, v50
	v_max_f32_e32 v51, v107, v107
	v_max_f32_e32 v52, v106, v106
	v_max_f32_e32 v51, v52, v51
	v_max3_f32 v49, v49, v50, v51
	v_max_f32_e32 v50, v41, v41
	v_max_f32_e32 v51, v40, v40
	v_max_f32_e32 v50, v51, v50
	v_max_f32_e32 v51, v43, v43
	v_max_f32_e32 v52, v42, v42
	v_max_f32_e32 v51, v52, v51
	v_max3_f32 v49, v49, v50, v51
	v_max_f32_e32 v50, v37, v37
	v_max_f32_e32 v51, v36, v36
	v_max_f32_e32 v50, v51, v50
	v_max_f32_e32 v51, v39, v39
	v_max_f32_e32 v52, v38, v38
	v_max_f32_e32 v51, v52, v51
	v_max3_f32 v49, v49, v50, v51
	v_max_f32_e32 v50, v33, v33
	v_max_f32_e32 v51, v32, v32
	v_max_f32_e32 v50, v51, v50
	v_max_f32_e32 v51, v35, v35
	v_max_f32_e32 v52, v34, v34
	v_max_f32_e32 v51, v52, v51
	v_max3_f32 v49, v49, v50, v51
	v_max_f32_e32 v50, v29, v29
	v_max_f32_e32 v51, v28, v28
	v_max_f32_e32 v50, v51, v50
	v_max_f32_e32 v51, v31, v31
	v_max_f32_e32 v52, v30, v30
	v_max_f32_e32 v51, v52, v51
	v_max3_f32 v49, v49, v50, v51
	v_max_f32_e32 v50, v25, v25
	v_max_f32_e32 v51, v24, v24
	v_max_f32_e32 v50, v51, v50
	v_max_f32_e32 v51, v27, v27
	v_max_f32_e32 v52, v26, v26
	v_max_f32_e32 v51, v52, v51
	v_max3_f32 v49, v49, v50, v51
	v_max_f32_e32 v50, v21, v21
	v_max_f32_e32 v51, v20, v20
	v_max_f32_e32 v50, v51, v50
	v_max_f32_e32 v51, v23, v23
	v_max_f32_e32 v52, v22, v22
	v_max_f32_e32 v51, v52, v51
	v_max3_f32 v49, v49, v50, v51
	v_max_f32_e32 v50, v17, v17
	v_max_f32_e32 v51, v16, v16
	v_max_f32_e32 v50, v51, v50
	v_max_f32_e32 v51, v19, v19
	v_max_f32_e32 v52, v18, v18
	v_max_f32_e32 v51, v52, v51
	v_max3_f32 v49, v49, v50, v51
	v_max_f32_e32 v50, v13, v13
	v_max_f32_e32 v51, v12, v12
	v_max_f32_e32 v50, v51, v50
	v_max_f32_e32 v51, v15, v15
	v_max_f32_e32 v52, v14, v14
	v_max_f32_e32 v51, v52, v51
	v_max3_f32 v49, v49, v50, v51
	v_max_f32_e32 v50, v9, v9
	v_max_f32_e32 v51, v8, v8
	v_max_f32_e32 v50, v51, v50
	v_max_f32_e32 v51, v11, v11
	v_max_f32_e32 v52, v10, v10
	v_max_f32_e32 v51, v52, v51
	v_max3_f32 v49, v49, v50, v51
	v_max_f32_e32 v50, v5, v5
	v_max_f32_e32 v51, v4, v4
	v_max_f32_e32 v50, v51, v50
	v_max_f32_e32 v51, v7, v7
	v_max_f32_e32 v52, v6, v6
	v_max_f32_e32 v51, v52, v51
	v_max3_f32 v49, v49, v50, v51
	v_max_f32_e32 v50, v1, v1
	v_max_f32_e32 v51, v0, v0
	v_max_f32_e32 v50, v51, v50
	v_max_f32_e32 v51, v3, v3
	v_max_f32_e32 v52, v2, v2
	v_max_f32_e32 v51, v52, v51
	v_max3_f32 v49, v49, v50, v51
	v_mbcnt_lo_u32_b32 v50, -1, 0
	v_mbcnt_hi_u32_b32 v50, -1, v50
	v_and_b32_e32 v52, 64, v50
	v_xor_b32_e32 v51, 16, v50
	v_add_u32_e32 v52, 64, v52
	v_cmp_lt_i32_e32 vcc, v51, v52
	s_nop 1
	v_cndmask_b32_e32 v51, v50, v51, vcc
	v_lshlrev_b32_e32 v51, 2, v51
	v_mov_b32_e32 v53, v49
	s_nop 1
	v_permlane16_swap_b32_e32 v53, v49
	s_waitcnt lgkmcnt(0)
	v_max_f32_e32 v53, v53, v53
	v_max_f32_e32 v49, v49, v53
	v_xor_b32_e32 v53, 32, v50
	v_cmp_lt_i32_e32 vcc, v53, v52
	s_nop 1
	v_cndmask_b32_e32 v50, v50, v53, vcc
	v_lshlrev_b32_e32 v50, 2, v50
	v_mov_b32_e32 v52, v49
	s_nop 1
	v_permlane32_swap_b32_e32 v52, v49
	s_waitcnt lgkmcnt(0)
	v_max_f32_e32 v52, v52, v52
	v_max_f32_e32 v49, v49, v52
	v_sub_f32_e32 v52, v120, v49
	v_exp_f32_e32 v52, v52
	v_sub_f32_e32 v53, v121, v49
	v_exp_f32_e32 v53, v53
	v_sub_f32_e32 v54, v122, v49
	v_exp_f32_e32 v54, v54
	v_sub_f32_e32 v55, v123, v49
	v_exp_f32_e32 v55, v55
	v_sub_f32_e32 v59, v116, v49
	v_add_f32_e32 v57, 0, v52
	v_exp_f32_e32 v59, v59
	v_sub_f32_e32 v62, v117, v49
	v_add_f32_e32 v57, v53, v57
	v_exp_f32_e32 v62, v62
	v_sub_f32_e32 v63, v118, v49
	v_add_f32_e32 v57, v54, v57
	v_exp_f32_e32 v63, v63
	v_sub_f32_e32 v64, v119, v49
	v_add_f32_e32 v57, v55, v57
	v_exp_f32_e32 v64, v64
	v_sub_f32_e32 v66, v112, v49
	v_add_f32_e32 v57, v59, v57
	v_exp_f32_e32 v66, v66
	v_sub_f32_e32 v67, v113, v49
	v_add_f32_e32 v57, v62, v57
	v_exp_f32_e32 v67, v67
	v_sub_f32_e32 v68, v114, v49
	v_add_f32_e32 v57, v63, v57
	v_exp_f32_e32 v68, v68
	v_sub_f32_e32 v69, v115, v49
	v_add_f32_e32 v57, v64, v57
	v_exp_f32_e32 v69, v69
	v_sub_f32_e32 v71, v108, v49
	v_add_f32_e32 v57, v66, v57
	v_exp_f32_e32 v71, v71
	v_sub_f32_e32 v72, v109, v49
	v_add_f32_e32 v57, v67, v57
	v_exp_f32_e32 v72, v72
	v_sub_f32_e32 v73, v110, v49
	v_add_f32_e32 v57, v68, v57
	v_exp_f32_e32 v73, v73
	v_sub_f32_e32 v74, v111, v49
	v_add_f32_e32 v57, v69, v57
	v_exp_f32_e32 v74, v74
	v_sub_f32_e32 v75, v104, v49
	v_add_f32_e32 v57, v71, v57
	v_exp_f32_e32 v75, v75
	v_sub_f32_e32 v76, v105, v49
	v_add_f32_e32 v57, v72, v57
	v_exp_f32_e32 v76, v76
	v_sub_f32_e32 v77, v106, v49
	v_add_f32_e32 v57, v73, v57
	v_exp_f32_e32 v77, v77
	v_sub_f32_e32 v78, v107, v49
	v_add_f32_e32 v57, v74, v57
	v_exp_f32_e32 v78, v78
	v_sub_f32_e32 v40, v40, v49
	v_add_f32_e32 v57, v75, v57
	v_exp_f32_e32 v40, v40
	v_sub_f32_e32 v41, v41, v49
	v_add_f32_e32 v57, v76, v57
	v_exp_f32_e32 v41, v41
	v_sub_f32_e32 v42, v42, v49
	v_add_f32_e32 v57, v77, v57
	v_exp_f32_e32 v42, v42
	v_sub_f32_e32 v43, v43, v49
	v_add_f32_e32 v57, v78, v57
	v_exp_f32_e32 v43, v43
	v_sub_f32_e32 v36, v36, v49
	v_add_f32_e32 v57, v40, v57
	v_exp_f32_e32 v36, v36
	v_sub_f32_e32 v37, v37, v49
	v_add_f32_e32 v57, v41, v57
	v_exp_f32_e32 v37, v37
	v_sub_f32_e32 v38, v38, v49
	v_add_f32_e32 v57, v42, v57
	v_exp_f32_e32 v38, v38
	v_sub_f32_e32 v39, v39, v49
	v_add_f32_e32 v57, v43, v57
	v_exp_f32_e32 v39, v39
	v_sub_f32_e32 v32, v32, v49
	v_add_f32_e32 v57, v36, v57
	v_exp_f32_e32 v32, v32
	v_sub_f32_e32 v33, v33, v49
	v_add_f32_e32 v57, v37, v57
	v_exp_f32_e32 v33, v33
	v_sub_f32_e32 v34, v34, v49
	v_add_f32_e32 v57, v38, v57
	v_exp_f32_e32 v34, v34
	v_sub_f32_e32 v35, v35, v49
	v_add_f32_e32 v57, v39, v57
	v_exp_f32_e32 v35, v35
	v_sub_f32_e32 v28, v28, v49
	v_add_f32_e32 v57, v32, v57
	v_exp_f32_e32 v79, v28
	v_sub_f32_e32 v28, v29, v49
	v_add_f32_e32 v57, v33, v57
	v_exp_f32_e32 v80, v28
	v_sub_f32_e32 v28, v30, v49
	v_add_f32_e32 v57, v34, v57
	v_exp_f32_e32 v81, v28
	v_sub_f32_e32 v28, v31, v49
	v_add_f32_e32 v57, v35, v57
	v_exp_f32_e32 v82, v28
	v_sub_f32_e32 v24, v24, v49
	v_add_f32_e32 v28, v79, v57
	v_exp_f32_e32 v57, v24
	v_sub_f32_e32 v24, v25, v49
	v_add_f32_e32 v28, v80, v28
	v_exp_f32_e32 v83, v24
	v_sub_f32_e32 v24, v26, v49
	v_add_f32_e32 v28, v81, v28
	v_exp_f32_e32 v84, v24
	v_sub_f32_e32 v24, v27, v49
	v_add_f32_e32 v28, v82, v28
	v_exp_f32_e32 v85, v24
	v_sub_f32_e32 v20, v20, v49
	v_add_f32_e32 v24, v57, v28
	v_exp_f32_e32 v86, v20
	v_sub_f32_e32 v20, v21, v49
	v_add_f32_e32 v24, v83, v24
	v_exp_f32_e32 v87, v20
	v_sub_f32_e32 v20, v22, v49
	v_add_f32_e32 v24, v84, v24
	v_exp_f32_e32 v88, v20
	v_sub_f32_e32 v20, v23, v49
	v_add_f32_e32 v24, v85, v24
	v_exp_f32_e32 v89, v20
	v_sub_f32_e32 v16, v16, v49
	v_add_f32_e32 v20, v86, v24
	v_exp_f32_e32 v90, v16
	v_sub_f32_e32 v16, v17, v49
	v_add_f32_e32 v20, v87, v20
	v_exp_f32_e32 v91, v16
	v_sub_f32_e32 v16, v18, v49
	v_add_f32_e32 v20, v88, v20
	v_exp_f32_e32 v92, v16
	v_sub_f32_e32 v16, v19, v49
	v_add_f32_e32 v20, v89, v20
	v_exp_f32_e32 v93, v16
	v_sub_f32_e32 v12, v12, v49
	v_add_f32_e32 v16, v90, v20
	v_exp_f32_e32 v94, v12
	v_sub_f32_e32 v12, v13, v49
	v_add_f32_e32 v16, v91, v16
	v_exp_f32_e32 v95, v12
	v_sub_f32_e32 v12, v14, v49
	v_add_f32_e32 v16, v92, v16
	v_exp_f32_e32 v96, v12
	v_sub_f32_e32 v12, v15, v49
	v_add_f32_e32 v16, v93, v16
	v_exp_f32_e32 v97, v12
	v_sub_f32_e32 v8, v8, v49
	v_add_f32_e32 v12, v94, v16
	v_exp_f32_e32 v98, v8
	v_sub_f32_e32 v8, v9, v49
	v_add_f32_e32 v12, v95, v12
	v_exp_f32_e32 v99, v8
	v_sub_f32_e32 v8, v10, v49
	v_add_f32_e32 v12, v96, v12
	v_exp_f32_e32 v100, v8
	v_sub_f32_e32 v8, v11, v49
	v_add_f32_e32 v12, v97, v12
	v_exp_f32_e32 v11, v8
	v_sub_f32_e32 v4, v4, v49
	v_add_f32_e32 v8, v98, v12
	v_exp_f32_e32 v101, v4
	v_sub_f32_e32 v4, v5, v49
	v_add_f32_e32 v8, v99, v8
	v_exp_f32_e32 v102, v4
	v_sub_f32_e32 v4, v6, v49
	v_add_f32_e32 v8, v100, v8
	v_exp_f32_e32 v103, v4
	v_sub_f32_e32 v4, v7, v49
	v_add_f32_e32 v8, v11, v8
	v_exp_f32_e32 v104, v4
	v_sub_f32_e32 v0, v0, v49
	v_add_f32_e32 v4, v101, v8
	v_exp_f32_e32 v105, v0
	v_sub_f32_e32 v0, v1, v49
	v_add_f32_e32 v4, v102, v4
	v_exp_f32_e32 v106, v0
	v_sub_f32_e32 v0, v2, v49
	v_add_f32_e32 v4, v103, v4
	v_exp_f32_e32 v107, v0
	v_sub_f32_e32 v0, v3, v49
	v_add_f32_e32 v4, v104, v4
	v_exp_f32_e32 v3, v0
	v_add_f32_e32 v0, v105, v4
	v_add_f32_e32 v0, v106, v0
	v_add_f32_e32 v0, v107, v0
	v_add_f32_e32 v0, v3, v0
	v_mov_b32_e32 v1, v0
	s_nop 1
	v_permlane16_swap_b32_e32 v1, v0
	v_cvt_pk_bf16_f32 v28, v52, v53
	v_cvt_pk_bf16_f32 v29, v54, v55
	v_cvt_pk_bf16_f32 v30, v59, v62
	v_cvt_pk_bf16_f32 v31, v63, v64
	s_waitcnt lgkmcnt(0)
	v_add_f32_e32 v0, v0, v1
	v_mov_b32_e32 v1, v0
	s_nop 1
	v_permlane32_swap_b32_e32 v1, v0
	v_cvt_pk_bf16_f32 v20, v66, v67
	v_cvt_pk_bf16_f32 v21, v68, v69
	v_cvt_pk_bf16_f32 v22, v71, v72
	v_cvt_pk_bf16_f32 v23, v73, v74
	s_waitcnt lgkmcnt(0)
	v_add_f32_e32 v49, v0, v1
	v_cvt_pk_bf16_f32 v24, v75, v76
	v_cvt_pk_bf16_f32 v25, v77, v78
	v_cvt_pk_bf16_f32 v26, v40, v41
	v_cvt_pk_bf16_f32 v27, v42, v43
	v_cvt_pk_bf16_f32 v16, v36, v37
	v_cvt_pk_bf16_f32 v17, v38, v39
	v_cvt_pk_bf16_f32 v18, v32, v33
	v_cvt_pk_bf16_f32 v19, v34, v35
	v_cvt_pk_bf16_f32 v12, v79, v80
	v_cvt_pk_bf16_f32 v13, v81, v82
	v_cvt_pk_bf16_f32 v14, v57, v83
	v_cvt_pk_bf16_f32 v15, v84, v85
	v_cvt_pk_bf16_f32 v4, v86, v87
	v_cvt_pk_bf16_f32 v5, v88, v89
	v_cvt_pk_bf16_f32 v6, v90, v91
	v_cvt_pk_bf16_f32 v7, v92, v93
	v_cvt_pk_bf16_f32 v8, v94, v95
	v_cvt_pk_bf16_f32 v9, v96, v97
	v_cvt_pk_bf16_f32 v10, v98, v99
	v_cvt_pk_bf16_f32 v11, v100, v11
	v_cvt_pk_bf16_f32 v0, v101, v102
	v_cvt_pk_bf16_f32 v1, v103, v104
	v_cvt_pk_bf16_f32 v2, v105, v106
	v_cvt_pk_bf16_f32 v3, v107, v3
	s_waitcnt vmcnt(0)
	s_waitcnt vmcnt(0)
	s_barrier
	v_mov_b32_e32 v64, v65
	v_div_scale_f32 v62, vcc, 1.0, v49, 1.0
	v_lshlrev_b32_e32 v54, 2, v70
	v_ashrrev_i32_e32 v55, 31, v54
	ds_read_b128 v[32:35], v64
	ds_read_b128 v[36:39], v64 offset:2048
	v_div_scale_f32 v57, s[0:1], v49, v49, 1.0
	v_rcp_f32_e32 v59, v57
	s_waitcnt lgkmcnt(0)
	v_mfma_f32_16x16x32_bf16 v[44:47], v[32:35], v[28:31], 0
	v_fma_f32 v40, -v57, v59, 1.0
	v_fmac_f32_e32 v59, v40, v59
	ds_read_b128 v[40:43], v64 offset:4096
	ds_read_b128 v[32:35], v64 offset:6144
	v_mul_f32_e32 v63, v62, v59
	v_fma_f32 v66, -v57, v63, v62
	v_fmac_f32_e32 v63, v66, v59
	v_mfma_f32_16x16x32_bf16 v[50:53], v[36:39], v[28:31], 0
	v_fma_f32 v36, -v57, v63, v62
	ds_read_b128 v[66:69], v64 offset:8192
	ds_read_b128 v[70:73], v64 offset:10240
	v_div_fmas_f32 v36, v36, v59, v63
	s_waitcnt lgkmcnt(0)
	v_mfma_f32_16x16x32_bf16 v[74:77], v[32:35], v[28:31], 0
	v_lshl_add_u64 v[34:35], v[54:55], 1, v[60:61]
	ds_read_b128 v[60:63], v64 offset:12288
	ds_read_b128 v[78:81], v64 offset:14336
	ds_read_b128 v[82:85], v64 offset:32768
	ds_read_b128 v[86:89], v64 offset:34816
	ds_read_b128 v[90:93], v64 offset:36864
	ds_read_b128 v[94:97], v64 offset:38912
	ds_read_b128 v[98:101], v64 offset:40960
	ds_read_b128 v[102:105], v64 offset:43008
	ds_read_b128 v[106:109], v64 offset:45056
	ds_read_b128 v[110:113], v64 offset:47104
	s_mov_b64 s[0:1], 0x1000000
	v_mfma_f32_16x16x32_bf16 v[38:41], v[40:43], v[28:31], 0
	v_div_fixup_f32 v36, v36, v49, 1.0
	v_lshl_add_u64 v[32:33], v[34:35], 0, s[0:1]
	v_mfma_f32_16x16x32_bf16 v[66:69], v[66:69], v[28:31], 0
	v_mfma_f32_16x16x32_bf16 v[70:73], v[70:73], v[28:31], 0
	s_waitcnt lgkmcnt(0)
	v_mfma_f32_16x16x32_bf16 v[60:63], v[60:63], v[28:31], 0
	v_mfma_f32_16x16x32_bf16 v[78:81], v[78:81], v[28:31], 0
	s_add_u32 s100, s10, 0x11c00100
	s_addc_u32 s101, s11, 0
	s_mov_b32 m0, s19
	s_nop 0
	global_load_lds_dwordx4 v241, s[100:101]
	ds_read_b128 v[114:117], v64 offset:30720
	ds_read_b128 v[118:121], v64 offset:28672
	ds_read_b128 v[122:125], v64 offset:26624
	ds_read_b128 v[126:129], v64 offset:24576
	ds_read_b128 v[130:133], v64 offset:22528
	ds_read_b128 v[134:137], v64 offset:20480
	ds_read_b128 v[138:141], v64 offset:18432
	ds_read_b128 v[142:145], v64 offset:16384
	v_mfma_f32_16x16x32_bf16 v[82:85], v[82:85], v[28:31], 0
	v_mfma_f32_16x16x32_bf16 v[86:89], v[86:89], v[28:31], 0
	v_mfma_f32_16x16x32_bf16 v[90:93], v[90:93], v[28:31], 0
	v_mfma_f32_16x16x32_bf16 v[94:97], v[94:97], v[28:31], 0
	v_mfma_f32_16x16x32_bf16 v[98:101], v[98:101], v[28:31], 0
	v_mfma_f32_16x16x32_bf16 v[102:105], v[102:105], v[28:31], 0
	v_mfma_f32_16x16x32_bf16 v[106:109], v[106:109], v[28:31], 0
	v_mfma_f32_16x16x32_bf16 v[110:113], v[110:113], v[28:31], 0
	s_add_u32 s100, s10, 0x11c08100
	s_addc_u32 s101, s11, 0
	s_mov_b32 m0, s13
	s_nop 0
	global_load_lds_dwordx4 v241, s[100:101]
	s_waitcnt lgkmcnt(0)
	v_mfma_f32_16x16x32_bf16 v[42:45], v[142:145], v[24:27], v[44:47]
	v_mfma_f32_16x16x32_bf16 v[50:53], v[138:141], v[24:27], v[50:53]
	v_mfma_f32_16x16x32_bf16 v[38:41], v[134:137], v[24:27], v[38:41]
	v_mfma_f32_16x16x32_bf16 v[74:77], v[130:133], v[24:27], v[74:77]
	v_mfma_f32_16x16x32_bf16 v[66:69], v[126:129], v[24:27], v[66:69]
	v_mfma_f32_16x16x32_bf16 v[70:73], v[122:125], v[24:27], v[70:73]
	ds_read_b128 v[122:125], v64 offset:49152
	ds_read_b128 v[126:129], v64 offset:51200
	ds_read_b128 v[130:133], v64 offset:53248
	ds_read_b128 v[134:137], v64 offset:55296
	v_mfma_f32_16x16x32_bf16 v[60:63], v[118:121], v[24:27], v[60:63]
	ds_read_b128 v[118:121], v64 offset:57344
	ds_read_b128 v[138:141], v64 offset:59392
	ds_read_b128 v[142:145], v64 offset:61440
	ds_read_b128 v[146:149], v64 offset:63488
	v_mfma_f32_16x16x32_bf16 v[78:81], v[114:117], v[24:27], v[78:81]
	s_add_u32 s100, s10, 0x11c00180
	s_addc_u32 s101, s11, 0
	s_mov_b32 m0, s12
	s_nop 0
	global_load_lds_dwordx4 v241, s[100:101]
	s_waitcnt lgkmcnt(0)
	v_mfma_f32_16x16x32_bf16 v[82:85], v[122:125], v[24:27], v[82:85]
	v_mfma_f32_16x16x32_bf16 v[86:89], v[126:129], v[24:27], v[86:89]
	v_mfma_f32_16x16x32_bf16 v[90:93], v[130:133], v[24:27], v[90:93]
	v_mfma_f32_16x16x32_bf16 v[94:97], v[134:137], v[24:27], v[94:97]
	v_mfma_f32_16x16x32_bf16 v[98:101], v[118:121], v[24:27], v[98:101]
	ds_read_b128 v[114:117], v64 offset:15360
	ds_read_b128 v[118:121], v64 offset:13312
	ds_read_b128 v[122:125], v64 offset:11264
	ds_read_b128 v[126:129], v64 offset:9216
	v_mfma_f32_16x16x32_bf16 v[102:105], v[138:141], v[24:27], v[102:105]
	v_mfma_f32_16x16x32_bf16 v[106:109], v[142:145], v[24:27], v[106:109]
	ds_read_b128 v[130:133], v64 offset:7168
	ds_read_b128 v[134:137], v64 offset:5120
	ds_read_b128 v[138:141], v64 offset:3072
	ds_read_b128 v[142:145], v64 offset:1024
	v_mfma_f32_16x16x32_bf16 v[110:113], v[146:149], v[24:27], v[110:113]
	s_add_u32 s100, s10, 0x11c08180
	s_addc_u32 s101, s11, 0
	s_mov_b32 m0, s14
	s_nop 0
	global_load_lds_dwordx4 v241, s[100:101]
	s_waitcnt lgkmcnt(0)
	v_mfma_f32_16x16x32_bf16 v[42:45], v[142:145], v[20:23], v[42:45]
	v_mfma_f32_16x16x32_bf16 v[50:53], v[138:141], v[20:23], v[50:53]
	v_mfma_f32_16x16x32_bf16 v[38:41], v[134:137], v[20:23], v[38:41]
	v_mfma_f32_16x16x32_bf16 v[74:77], v[130:133], v[20:23], v[74:77]
	v_mfma_f32_16x16x32_bf16 v[66:69], v[126:129], v[20:23], v[66:69]
	v_mfma_f32_16x16x32_bf16 v[70:73], v[122:125], v[20:23], v[70:73]
	ds_read_b128 v[122:125], v64 offset:33792
	ds_read_b128 v[126:129], v64 offset:35840
	ds_read_b128 v[130:133], v64 offset:37888
	ds_read_b128 v[134:137], v64 offset:39936
	v_mfma_f32_16x16x32_bf16 v[60:63], v[118:121], v[20:23], v[60:63]
	ds_read_b128 v[118:121], v64 offset:41984
	ds_read_b128 v[138:141], v64 offset:44032
	ds_read_b128 v[142:145], v64 offset:46080
	ds_read_b128 v[146:149], v64 offset:48128
	v_mfma_f32_16x16x32_bf16 v[78:81], v[114:117], v[20:23], v[78:81]
	s_add_u32 s100, s10, 0x11c10100
	s_addc_u32 s101, s11, 0
	s_mov_b32 m0, s15
	s_nop 0
	global_load_lds_dwordx4 v241, s[100:101]
	s_waitcnt lgkmcnt(0)
	v_mfma_f32_16x16x32_bf16 v[82:85], v[122:125], v[20:23], v[82:85]
	v_mfma_f32_16x16x32_bf16 v[86:89], v[126:129], v[20:23], v[86:89]
	v_mfma_f32_16x16x32_bf16 v[90:93], v[130:133], v[20:23], v[90:93]
	v_mfma_f32_16x16x32_bf16 v[94:97], v[134:137], v[20:23], v[94:97]
	v_mfma_f32_16x16x32_bf16 v[98:101], v[118:121], v[20:23], v[98:101]
	ds_read_b128 v[114:117], v64 offset:31744
	ds_read_b128 v[118:121], v64 offset:29696
	ds_read_b128 v[122:125], v64 offset:27648
	ds_read_b128 v[126:129], v64 offset:25600
	v_mfma_f32_16x16x32_bf16 v[102:105], v[138:141], v[20:23], v[102:105]
	v_mfma_f32_16x16x32_bf16 v[106:109], v[142:145], v[20:23], v[106:109]
	ds_read_b128 v[130:133], v64 offset:23552
	ds_read_b128 v[134:137], v64 offset:21504
	ds_read_b128 v[138:141], v64 offset:19456
	ds_read_b128 v[142:145], v64 offset:17408
	v_mfma_f32_16x16x32_bf16 v[110:113], v[146:149], v[20:23], v[110:113]
	s_add_u32 s100, s10, 0x11c18100
	s_addc_u32 s101, s11, 0
	s_mov_b32 m0, s16
	s_nop 0
	global_load_lds_dwordx4 v241, s[100:101]
	s_waitcnt lgkmcnt(0)
	v_mfma_f32_16x16x32_bf16 v[42:45], v[142:145], v[16:19], v[42:45]
	v_mfma_f32_16x16x32_bf16 v[50:53], v[138:141], v[16:19], v[50:53]
	v_mfma_f32_16x16x32_bf16 v[38:41], v[134:137], v[16:19], v[38:41]
	v_mfma_f32_16x16x32_bf16 v[74:77], v[130:133], v[16:19], v[74:77]
	v_mfma_f32_16x16x32_bf16 v[66:69], v[126:129], v[16:19], v[66:69]
	v_mfma_f32_16x16x32_bf16 v[70:73], v[122:125], v[16:19], v[70:73]
	ds_read_b128 v[122:125], v64 offset:50176
	ds_read_b128 v[126:129], v64 offset:52224
	ds_read_b128 v[130:133], v64 offset:54272
	ds_read_b128 v[134:137], v64 offset:56320
	v_mfma_f32_16x16x32_bf16 v[60:63], v[118:121], v[16:19], v[60:63]
	ds_read_b128 v[118:121], v64 offset:58368
	ds_read_b128 v[138:141], v64 offset:60416
	ds_read_b128 v[142:145], v64 offset:62464
	ds_read_b128 v[146:149], v64 offset:64512
	v_mfma_f32_16x16x32_bf16 v[78:81], v[114:117], v[16:19], v[78:81]
	s_add_u32 s100, s10, 0x11c10180
	s_addc_u32 s101, s11, 0
	s_mov_b32 m0, s17
	s_nop 0
	global_load_lds_dwordx4 v241, s[100:101]
	s_waitcnt lgkmcnt(0)
	v_mfma_f32_16x16x32_bf16 v[82:85], v[122:125], v[16:19], v[82:85]
	v_mfma_f32_16x16x32_bf16 v[86:89], v[126:129], v[16:19], v[86:89]
	v_mfma_f32_16x16x32_bf16 v[90:93], v[130:133], v[16:19], v[90:93]
	v_mfma_f32_16x16x32_bf16 v[94:97], v[134:137], v[16:19], v[94:97]
	v_mfma_f32_16x16x32_bf16 v[98:101], v[118:121], v[16:19], v[98:101]
	v_mfma_f32_16x16x32_bf16 v[102:105], v[138:141], v[16:19], v[102:105]
	v_mfma_f32_16x16x32_bf16 v[106:109], v[142:145], v[16:19], v[106:109]
	v_mfma_f32_16x16x32_bf16 v[110:113], v[146:149], v[16:19], v[110:113]
	s_add_u32 s100, s10, 0x11c18180
	s_addc_u32 s101, s11, 0
	s_mov_b32 m0, s18
	s_nop 0
	global_load_lds_dwordx4 v241, s[100:101]
	s_waitcnt vmcnt(0)
	s_waitcnt vmcnt(0)
	s_barrier
	v_mov_b32_e32 v37, v48
	ds_read_b128 v[114:117], v37
	ds_read_b128 v[118:121], v37 offset:2048
	s_waitcnt lgkmcnt(0)
	v_mfma_f32_16x16x32_bf16 v[42:45], v[114:117], v[12:15], v[42:45]
	ds_read_b128 v[114:117], v37 offset:4096
	v_mfma_f32_16x16x32_bf16 v[50:53], v[118:121], v[12:15], v[50:53]
	ds_read_b128 v[118:121], v37 offset:6144
	s_waitcnt lgkmcnt(0)
	v_mfma_f32_16x16x32_bf16 v[38:41], v[114:117], v[12:15], v[38:41]
	ds_read_b128 v[114:117], v37 offset:8192
	v_mfma_f32_16x16x32_bf16 v[74:77], v[118:121], v[12:15], v[74:77]
	ds_read_b128 v[118:121], v37 offset:10240
	s_waitcnt lgkmcnt(0)
	v_mfma_f32_16x16x32_bf16 v[66:69], v[114:117], v[12:15], v[66:69]
	ds_read_b128 v[114:117], v37 offset:12288
	ds_read_b128 v[122:125], v37 offset:14336
	v_mfma_f32_16x16x32_bf16 v[70:73], v[118:121], v[12:15], v[70:73]
	ds_read_b128 v[118:121], v37 offset:32768
	ds_read_b128 v[126:129], v37 offset:34816
	ds_read_b128 v[130:133], v37 offset:36864
	ds_read_b128 v[134:137], v37 offset:38912
	s_waitcnt lgkmcnt(0)
	v_mfma_f32_16x16x32_bf16 v[60:63], v[114:117], v[12:15], v[60:63]
	ds_read_b128 v[114:117], v37 offset:40960
	ds_read_b128 v[138:141], v37 offset:43008
	ds_read_b128 v[142:145], v37 offset:45056
	ds_read_b128 v[146:149], v37 offset:47104
	v_mfma_f32_16x16x32_bf16 v[78:81], v[122:125], v[12:15], v[78:81]
	s_add_u32 s100, s10, 0x11c20000
	s_addc_u32 s101, s11, 0
	s_mov_b32 m0, s22
	s_nop 0
	global_load_lds_dwordx4 v241, s[100:101]
	v_mfma_f32_16x16x32_bf16 v[82:85], v[118:121], v[12:15], v[82:85]
	v_mfma_f32_16x16x32_bf16 v[86:89], v[126:129], v[12:15], v[86:89]
	v_mfma_f32_16x16x32_bf16 v[90:93], v[130:133], v[12:15], v[90:93]
	v_mfma_f32_16x16x32_bf16 v[94:97], v[134:137], v[12:15], v[94:97]
	s_waitcnt lgkmcnt(0)
	v_mfma_f32_16x16x32_bf16 v[98:101], v[114:117], v[12:15], v[98:101]
	ds_read_b128 v[114:117], v37 offset:30720
	ds_read_b128 v[118:121], v37 offset:28672
	ds_read_b128 v[122:125], v37 offset:26624
	ds_read_b128 v[126:129], v37 offset:24576
	v_mfma_f32_16x16x32_bf16 v[102:105], v[138:141], v[12:15], v[102:105]
	v_mfma_f32_16x16x32_bf16 v[106:109], v[142:145], v[12:15], v[106:109]
	ds_read_b128 v[130:133], v37 offset:22528
	ds_read_b128 v[134:137], v37 offset:20480
	ds_read_b128 v[138:141], v37 offset:18432
	ds_read_b128 v[142:145], v37 offset:16384
	v_mfma_f32_16x16x32_bf16 v[110:113], v[146:149], v[12:15], v[110:113]
	s_add_u32 s100, s10, 0x11c28000
	s_addc_u32 s101, s11, 0
	s_mov_b32 m0, s21
	s_nop 0
	global_load_lds_dwordx4 v241, s[100:101]
	s_waitcnt lgkmcnt(0)
	v_mfma_f32_16x16x32_bf16 v[42:45], v[142:145], v[8:11], v[42:45]
	v_mfma_f32_16x16x32_bf16 v[50:53], v[138:141], v[8:11], v[50:53]
	v_mfma_f32_16x16x32_bf16 v[38:41], v[134:137], v[8:11], v[38:41]
	v_mfma_f32_16x16x32_bf16 v[74:77], v[130:133], v[8:11], v[74:77]
	v_mfma_f32_16x16x32_bf16 v[66:69], v[126:129], v[8:11], v[66:69]
	v_mfma_f32_16x16x32_bf16 v[70:73], v[122:125], v[8:11], v[70:73]
	ds_read_b128 v[122:125], v37 offset:49152
	ds_read_b128 v[126:129], v37 offset:51200
	ds_read_b128 v[130:133], v37 offset:53248
	ds_read_b128 v[134:137], v37 offset:55296
	v_mfma_f32_16x16x32_bf16 v[60:63], v[118:121], v[8:11], v[60:63]
	ds_read_b128 v[118:121], v37 offset:57344
	ds_read_b128 v[138:141], v37 offset:59392
	ds_read_b128 v[142:145], v37 offset:61440
	ds_read_b128 v[146:149], v37 offset:63488
	v_mfma_f32_16x16x32_bf16 v[78:81], v[114:117], v[8:11], v[78:81]
	s_add_u32 s100, s10, 0x11c20080
	s_addc_u32 s101, s11, 0
	s_mov_b32 m0, s20
	s_nop 0
	global_load_lds_dwordx4 v241, s[100:101]
	s_waitcnt lgkmcnt(0)
	v_mfma_f32_16x16x32_bf16 v[82:85], v[122:125], v[8:11], v[82:85]
	v_mfma_f32_16x16x32_bf16 v[86:89], v[126:129], v[8:11], v[86:89]
	v_mfma_f32_16x16x32_bf16 v[90:93], v[130:133], v[8:11], v[90:93]
	v_mfma_f32_16x16x32_bf16 v[94:97], v[134:137], v[8:11], v[94:97]
	v_mfma_f32_16x16x32_bf16 v[98:101], v[118:121], v[8:11], v[98:101]
	ds_read_b128 v[114:117], v37 offset:15360
	ds_read_b128 v[118:121], v37 offset:13312
	ds_read_b128 v[122:125], v37 offset:11264
	ds_read_b128 v[126:129], v37 offset:9216
	v_mfma_f32_16x16x32_bf16 v[102:105], v[138:141], v[8:11], v[102:105]
	v_mfma_f32_16x16x32_bf16 v[106:109], v[142:145], v[8:11], v[106:109]
	ds_read_b128 v[130:133], v37 offset:7168
	ds_read_b128 v[134:137], v37 offset:5120
	ds_read_b128 v[138:141], v37 offset:3072
	ds_read_b128 v[142:145], v37 offset:1024
	v_mfma_f32_16x16x32_bf16 v[110:113], v[146:149], v[8:11], v[110:113]
	s_add_u32 s100, s10, 0x11c28080
	s_addc_u32 s101, s11, 0
	s_mov_b32 m0, s23
	s_nop 0
	global_load_lds_dwordx4 v241, s[100:101]
	s_waitcnt lgkmcnt(0)
	v_mfma_f32_16x16x32_bf16 v[42:45], v[142:145], v[4:7], v[42:45]
	v_mfma_f32_16x16x32_bf16 v[50:53], v[138:141], v[4:7], v[50:53]
	v_mfma_f32_16x16x32_bf16 v[38:41], v[134:137], v[4:7], v[38:41]
	v_mfma_f32_16x16x32_bf16 v[74:77], v[130:133], v[4:7], v[74:77]
	v_mfma_f32_16x16x32_bf16 v[66:69], v[126:129], v[4:7], v[66:69]
	v_mfma_f32_16x16x32_bf16 v[70:73], v[122:125], v[4:7], v[70:73]
	ds_read_b128 v[122:125], v37 offset:33792
	ds_read_b128 v[126:129], v37 offset:35840
	ds_read_b128 v[130:133], v37 offset:37888
	ds_read_b128 v[134:137], v37 offset:39936
	v_mfma_f32_16x16x32_bf16 v[60:63], v[118:121], v[4:7], v[60:63]
	ds_read_b128 v[118:121], v37 offset:41984
	ds_read_b128 v[138:141], v37 offset:44032
	ds_read_b128 v[142:145], v37 offset:46080
	ds_read_b128 v[146:149], v37 offset:48128
	v_mfma_f32_16x16x32_bf16 v[78:81], v[114:117], v[4:7], v[78:81]
	s_add_u32 s100, s10, 0x11c30000
	s_addc_u32 s101, s11, 0
	s_mov_b32 m0, s24
	s_nop 0
	global_load_lds_dwordx4 v241, s[100:101]
	s_waitcnt lgkmcnt(0)
	v_mfma_f32_16x16x32_bf16 v[82:85], v[122:125], v[4:7], v[82:85]
	v_mfma_f32_16x16x32_bf16 v[86:89], v[126:129], v[4:7], v[86:89]
	v_mfma_f32_16x16x32_bf16 v[90:93], v[130:133], v[4:7], v[90:93]
	v_mfma_f32_16x16x32_bf16 v[94:97], v[134:137], v[4:7], v[94:97]
	v_mfma_f32_16x16x32_bf16 v[98:101], v[118:121], v[4:7], v[98:101]
	ds_read_b128 v[114:117], v37 offset:31744
	ds_read_b128 v[118:121], v37 offset:29696
	ds_read_b128 v[122:125], v37 offset:27648
	ds_read_b128 v[126:129], v37 offset:25600
	v_mfma_f32_16x16x32_bf16 v[102:105], v[138:141], v[4:7], v[102:105]
	v_mfma_f32_16x16x32_bf16 v[106:109], v[142:145], v[4:7], v[106:109]
	ds_read_b128 v[130:133], v37 offset:23552
	ds_read_b128 v[134:137], v37 offset:21504
	ds_read_b128 v[138:141], v37 offset:19456
	ds_read_b128 v[142:145], v37 offset:17408
	v_mfma_f32_16x16x32_bf16 v[110:113], v[146:149], v[4:7], v[110:113]
	s_add_u32 s100, s10, 0x11c38000
	s_addc_u32 s101, s11, 0
	s_mov_b32 m0, s25
	s_nop 0
	global_load_lds_dwordx4 v241, s[100:101]
	s_waitcnt lgkmcnt(0)
	v_mfma_f32_16x16x32_bf16 v[42:45], v[142:145], v[0:3], v[42:45]
	v_mfma_f32_16x16x32_bf16 v[50:53], v[138:141], v[0:3], v[50:53]
	v_mfma_f32_16x16x32_bf16 v[38:41], v[134:137], v[0:3], v[38:41]
	v_mfma_f32_16x16x32_bf16 v[74:77], v[130:133], v[0:3], v[74:77]
	v_mfma_f32_16x16x32_bf16 v[66:69], v[126:129], v[0:3], v[66:69]
	v_mfma_f32_16x16x32_bf16 v[70:73], v[122:125], v[0:3], v[70:73]
	ds_read_b128 v[122:125], v37 offset:50176
	ds_read_b128 v[126:129], v37 offset:52224
	ds_read_b128 v[130:133], v37 offset:54272
	ds_read_b128 v[134:137], v37 offset:56320
	v_mfma_f32_16x16x32_bf16 v[60:63], v[118:121], v[0:3], v[60:63]
	ds_read_b128 v[118:121], v37 offset:58368
	ds_read_b128 v[138:141], v37 offset:60416
	ds_read_b128 v[142:145], v37 offset:62464
	ds_read_b128 v[146:149], v37 offset:64512
	v_mfma_f32_16x16x32_bf16 v[78:81], v[114:117], v[0:3], v[78:81]
	s_add_u32 s100, s10, 0x11c30080
	s_addc_u32 s101, s11, 0
	s_mov_b32 m0, s26
	s_nop 0
	global_load_lds_dwordx4 v241, s[100:101]
	s_waitcnt lgkmcnt(0)
	v_mfma_f32_16x16x32_bf16 v[82:85], v[122:125], v[0:3], v[82:85]
	v_mfma_f32_16x16x32_bf16 v[86:89], v[126:129], v[0:3], v[86:89]
	v_mfma_f32_16x16x32_bf16 v[90:93], v[130:133], v[0:3], v[90:93]
	v_mfma_f32_16x16x32_bf16 v[94:97], v[134:137], v[0:3], v[94:97]
	v_mfma_f32_16x16x32_bf16 v[98:101], v[118:121], v[0:3], v[98:101]
	v_mfma_f32_16x16x32_bf16 v[102:105], v[138:141], v[0:3], v[102:105]
	v_mfma_f32_16x16x32_bf16 v[106:109], v[142:145], v[0:3], v[106:109]
	v_mfma_f32_16x16x32_bf16 v[110:113], v[146:149], v[0:3], v[110:113]
	s_add_u32 s100, s10, 0x11c38080
	s_addc_u32 s101, s11, 0
	s_mov_b32 m0, s27
	s_nop 0
	global_load_lds_dwordx4 v241, s[100:101]
	s_mov_b32 s0, 0x1000000
	v_add_co_u32_e32 v34, vcc, s0, v34
	v_addc_co_u32_e32 v35, vcc, 0, v35, vcc
	v_mbcnt_lo_u32_b32 v212, -1, 0
	v_mbcnt_hi_u32_b32 v212, -1, v212
	v_lshrrev_b32_e32 v212, 4, v212
	v_and_b32_e32 v212, 1, v212
	v_mul_u32_u24_e32 v212, 24, v212
	v_mov_b32_e32 v213, 0
	v_lshl_add_u64 v[214:215], v[32:33], 0, v[212:213]
	v_mul_f32_e32 v200, v36, v42
	v_mul_f32_e32 v204, v36, v43
	v_cvt_pk_bf16_f32 v200, v200, v204
	v_mul_f32_e32 v201, v36, v44
	v_mul_f32_e32 v204, v36, v45
	v_cvt_pk_bf16_f32 v201, v201, v204
	v_mul_f32_e32 v202, v36, v50
	v_mul_f32_e32 v204, v36, v51
	v_cvt_pk_bf16_f32 v202, v202, v204
	v_mul_f32_e32 v203, v36, v52
	v_mul_f32_e32 v204, v36, v53
	v_cvt_pk_bf16_f32 v203, v203, v204
	s_nop 1
	v_permlane16_swap_b32_e32 v200, v202
	v_permlane16_swap_b32_e32 v201, v203
	global_store_dwordx4 v[214:215], v[200:203], off offset:0
	v_mul_f32_e32 v206, v36, v38
	v_mul_f32_e32 v210, v36, v39
	v_cvt_pk_bf16_f32 v206, v206, v210
	v_mul_f32_e32 v207, v36, v40
	v_mul_f32_e32 v210, v36, v41
	v_cvt_pk_bf16_f32 v207, v207, v210
	v_mul_f32_e32 v208, v36, v74
	v_mul_f32_e32 v210, v36, v75
	v_cvt_pk_bf16_f32 v208, v208, v210
	v_mul_f32_e32 v209, v36, v76
	v_mul_f32_e32 v210, v36, v77
	v_cvt_pk_bf16_f32 v209, v209, v210
	s_nop 1
	v_permlane16_swap_b32_e32 v206, v208
	v_permlane16_swap_b32_e32 v207, v209
	global_store_dwordx4 v[214:215], v[206:209], off offset:64
	v_mul_f32_e32 v200, v36, v66
	v_mul_f32_e32 v204, v36, v67
	v_cvt_pk_bf16_f32 v200, v200, v204
	v_mul_f32_e32 v201, v36, v68
	v_mul_f32_e32 v204, v36, v69
	v_cvt_pk_bf16_f32 v201, v201, v204
	v_mul_f32_e32 v202, v36, v70
	v_mul_f32_e32 v204, v36, v71
	v_cvt_pk_bf16_f32 v202, v202, v204
	v_mul_f32_e32 v203, v36, v72
	v_mul_f32_e32 v204, v36, v73
	v_cvt_pk_bf16_f32 v203, v203, v204
	s_nop 1
	v_permlane16_swap_b32_e32 v200, v202
	v_permlane16_swap_b32_e32 v201, v203
	global_store_dwordx4 v[214:215], v[200:203], off offset:128
	v_mul_f32_e32 v206, v36, v60
	v_mul_f32_e32 v210, v36, v61
	v_cvt_pk_bf16_f32 v206, v206, v210
	v_mul_f32_e32 v207, v36, v62
	v_mul_f32_e32 v210, v36, v63
	v_cvt_pk_bf16_f32 v207, v207, v210
	v_mul_f32_e32 v208, v36, v78
	v_mul_f32_e32 v210, v36, v79
	v_cvt_pk_bf16_f32 v208, v208, v210
	v_mul_f32_e32 v209, v36, v80
	v_mul_f32_e32 v210, v36, v81
	v_cvt_pk_bf16_f32 v209, v209, v210
	s_nop 1
	v_permlane16_swap_b32_e32 v206, v208
	v_permlane16_swap_b32_e32 v207, v209
	global_store_dwordx4 v[214:215], v[206:209], off offset:192
	v_mul_f32_e32 v200, v36, v82
	v_mul_f32_e32 v204, v36, v83
	v_cvt_pk_bf16_f32 v200, v200, v204
	v_mul_f32_e32 v201, v36, v84
	v_mul_f32_e32 v204, v36, v85
	v_cvt_pk_bf16_f32 v201, v201, v204
	v_mul_f32_e32 v202, v36, v86
	v_mul_f32_e32 v204, v36, v87
	v_cvt_pk_bf16_f32 v202, v202, v204
	v_mul_f32_e32 v203, v36, v88
	v_mul_f32_e32 v204, v36, v89
	v_cvt_pk_bf16_f32 v203, v203, v204
	s_nop 1
	v_permlane16_swap_b32_e32 v200, v202
	v_permlane16_swap_b32_e32 v201, v203
	global_store_dwordx4 v[214:215], v[200:203], off offset:256
	v_mul_f32_e32 v206, v36, v90
	v_mul_f32_e32 v210, v36, v91
	v_cvt_pk_bf16_f32 v206, v206, v210
	v_mul_f32_e32 v207, v36, v92
	v_mul_f32_e32 v210, v36, v93
	v_cvt_pk_bf16_f32 v207, v207, v210
	v_mul_f32_e32 v208, v36, v94
	v_mul_f32_e32 v210, v36, v95
	v_cvt_pk_bf16_f32 v208, v208, v210
	v_mul_f32_e32 v209, v36, v96
	v_mul_f32_e32 v210, v36, v97
	v_cvt_pk_bf16_f32 v209, v209, v210
	s_nop 1
	v_permlane16_swap_b32_e32 v206, v208
	v_permlane16_swap_b32_e32 v207, v209
	global_store_dwordx4 v[214:215], v[206:209], off offset:320
	v_mul_f32_e32 v200, v36, v98
	v_mul_f32_e32 v204, v36, v99
	v_cvt_pk_bf16_f32 v200, v200, v204
	v_mul_f32_e32 v201, v36, v100
	v_mul_f32_e32 v204, v36, v101
	v_cvt_pk_bf16_f32 v201, v201, v204
	v_mul_f32_e32 v202, v36, v102
	v_mul_f32_e32 v204, v36, v103
	v_cvt_pk_bf16_f32 v202, v202, v204
	v_mul_f32_e32 v203, v36, v104
	v_mul_f32_e32 v204, v36, v105
	v_cvt_pk_bf16_f32 v203, v203, v204
	s_nop 1
	v_permlane16_swap_b32_e32 v200, v202
	v_permlane16_swap_b32_e32 v201, v203
	global_store_dwordx4 v[214:215], v[200:203], off offset:384
	v_mul_f32_e32 v206, v36, v106
	v_mul_f32_e32 v210, v36, v107
	v_cvt_pk_bf16_f32 v206, v206, v210
	v_mul_f32_e32 v207, v36, v108
	v_mul_f32_e32 v210, v36, v109
	v_cvt_pk_bf16_f32 v207, v207, v210
	v_mul_f32_e32 v208, v36, v110
	v_mul_f32_e32 v210, v36, v111
	v_cvt_pk_bf16_f32 v208, v208, v210
	v_mul_f32_e32 v209, v36, v112
	v_mul_f32_e32 v210, v36, v113
	v_cvt_pk_bf16_f32 v209, v209, v210
	s_nop 1
	v_permlane16_swap_b32_e32 v206, v208
	v_permlane16_swap_b32_e32 v207, v209
	global_store_dwordx4 v[214:215], v[206:209], off offset:448
	s_waitcnt vmcnt(8)
	s_waitcnt vmcnt(8)
	s_barrier
	ds_read_b128 v[38:41], v65
	ds_read_b128 v[42:45], v65 offset:2048
	ds_read_b128 v[50:53], v65 offset:4096
	ds_read_b128 v[54:57], v65 offset:6144
	ds_read_b128 v[58:61], v65 offset:8192
	ds_read_b128 v[66:69], v65 offset:10240
	ds_read_b128 v[70:73], v65 offset:12288
	ds_read_b128 v[74:77], v65 offset:14336
	ds_read_b128 v[78:81], v65 offset:32768
	ds_read_b128 v[82:85], v65 offset:34816
	ds_read_b128 v[86:89], v65 offset:36864
	ds_read_b128 v[90:93], v65 offset:38912
	ds_read_b128 v[94:97], v65 offset:40960
	ds_read_b128 v[98:101], v65 offset:43008
	ds_read_b128 v[102:105], v65 offset:45056
	ds_read_b128 v[106:109], v65 offset:47104
	s_waitcnt lgkmcnt(0)
	v_mfma_f32_16x16x32_bf16 v[38:41], v[38:41], v[28:31], 0
	v_mfma_f32_16x16x32_bf16 v[42:45], v[42:45], v[28:31], 0
	v_mfma_f32_16x16x32_bf16 v[50:53], v[50:53], v[28:31], 0
	v_mfma_f32_16x16x32_bf16 v[54:57], v[54:57], v[28:31], 0
	v_mfma_f32_16x16x32_bf16 v[58:61], v[58:61], v[28:31], 0
	v_mfma_f32_16x16x32_bf16 v[66:69], v[66:69], v[28:31], 0
	v_mfma_f32_16x16x32_bf16 v[70:73], v[70:73], v[28:31], 0
	v_mfma_f32_16x16x32_bf16 v[74:77], v[74:77], v[28:31], 0
	s_add_u32 s100, s10, 0x11c20100
	s_addc_u32 s101, s11, 0
	s_mov_b32 m0, s19
	s_nop 0
	global_load_lds_dwordx4 v241, s[100:101]
	ds_read_b128 v[110:113], v65 offset:30720
	ds_read_b128 v[114:117], v65 offset:28672
	ds_read_b128 v[118:121], v65 offset:26624
	ds_read_b128 v[122:125], v65 offset:24576
	ds_read_b128 v[126:129], v65 offset:22528
	ds_read_b128 v[130:133], v65 offset:20480
	ds_read_b128 v[134:137], v65 offset:18432
	ds_read_b128 v[138:141], v65 offset:16384
	v_mfma_f32_16x16x32_bf16 v[78:81], v[78:81], v[28:31], 0
	v_mfma_f32_16x16x32_bf16 v[82:85], v[82:85], v[28:31], 0
	v_mfma_f32_16x16x32_bf16 v[86:89], v[86:89], v[28:31], 0
	v_mfma_f32_16x16x32_bf16 v[90:93], v[90:93], v[28:31], 0
	v_mfma_f32_16x16x32_bf16 v[94:97], v[94:97], v[28:31], 0
	v_mfma_f32_16x16x32_bf16 v[98:101], v[98:101], v[28:31], 0
	v_mfma_f32_16x16x32_bf16 v[102:105], v[102:105], v[28:31], 0
	v_mfma_f32_16x16x32_bf16 v[28:31], v[106:109], v[28:31], 0
	s_add_u32 s100, s10, 0x11c28100
	s_addc_u32 s101, s11, 0
	s_mov_b32 m0, s13
	s_nop 0
	global_load_lds_dwordx4 v241, s[100:101]
	s_waitcnt lgkmcnt(0)
	v_mfma_f32_16x16x32_bf16 v[38:41], v[138:141], v[24:27], v[38:41]
	v_mfma_f32_16x16x32_bf16 v[42:45], v[134:137], v[24:27], v[42:45]
	v_mfma_f32_16x16x32_bf16 v[50:53], v[130:133], v[24:27], v[50:53]
	v_mfma_f32_16x16x32_bf16 v[54:57], v[126:129], v[24:27], v[54:57]
	v_mfma_f32_16x16x32_bf16 v[58:61], v[122:125], v[24:27], v[58:61]
	v_mfma_f32_16x16x32_bf16 v[66:69], v[118:121], v[24:27], v[66:69]
	ds_read_b128 v[106:109], v65 offset:49152
	ds_read_b128 v[118:121], v65 offset:51200
	ds_read_b128 v[122:125], v65 offset:53248
	ds_read_b128 v[126:129], v65 offset:55296
	v_mfma_f32_16x16x32_bf16 v[70:73], v[114:117], v[24:27], v[70:73]
	ds_read_b128 v[114:117], v65 offset:57344
	ds_read_b128 v[130:133], v65 offset:59392
	ds_read_b128 v[134:137], v65 offset:61440
	ds_read_b128 v[138:141], v65 offset:63488
	v_mfma_f32_16x16x32_bf16 v[74:77], v[110:113], v[24:27], v[74:77]
	s_add_u32 s100, s10, 0x11c20180
	s_addc_u32 s101, s11, 0
	s_mov_b32 m0, s12
	s_nop 0
	global_load_lds_dwordx4 v241, s[100:101]
	s_waitcnt lgkmcnt(0)
	v_mfma_f32_16x16x32_bf16 v[78:81], v[106:109], v[24:27], v[78:81]
	v_mfma_f32_16x16x32_bf16 v[82:85], v[118:121], v[24:27], v[82:85]
	v_mfma_f32_16x16x32_bf16 v[86:89], v[122:125], v[24:27], v[86:89]
	v_mfma_f32_16x16x32_bf16 v[90:93], v[126:129], v[24:27], v[90:93]
	v_mfma_f32_16x16x32_bf16 v[94:97], v[114:117], v[24:27], v[94:97]
	ds_read_b128 v[106:109], v65 offset:15360
	ds_read_b128 v[110:113], v65 offset:13312
	ds_read_b128 v[114:117], v65 offset:11264
	ds_read_b128 v[118:121], v65 offset:9216
	v_mfma_f32_16x16x32_bf16 v[98:101], v[130:133], v[24:27], v[98:101]
	v_mfma_f32_16x16x32_bf16 v[102:105], v[134:137], v[24:27], v[102:105]
	ds_read_b128 v[122:125], v65 offset:7168
	ds_read_b128 v[126:129], v65 offset:5120
	ds_read_b128 v[130:133], v65 offset:3072
	ds_read_b128 v[134:137], v65 offset:1024
	v_mfma_f32_16x16x32_bf16 v[24:27], v[138:141], v[24:27], v[28:31]
	s_add_u32 s100, s10, 0x11c28180
	s_addc_u32 s101, s11, 0
	s_mov_b32 m0, s14
	s_nop 0
	global_load_lds_dwordx4 v241, s[100:101]
	s_waitcnt lgkmcnt(0)
	v_mfma_f32_16x16x32_bf16 v[28:31], v[134:137], v[20:23], v[38:41]
	v_mfma_f32_16x16x32_bf16 v[38:41], v[130:133], v[20:23], v[42:45]
	v_mfma_f32_16x16x32_bf16 v[42:45], v[126:129], v[20:23], v[50:53]
	v_mfma_f32_16x16x32_bf16 v[50:53], v[122:125], v[20:23], v[54:57]
	v_mfma_f32_16x16x32_bf16 v[54:57], v[118:121], v[20:23], v[58:61]
	v_mfma_f32_16x16x32_bf16 v[58:61], v[114:117], v[20:23], v[66:69]
	s_nop 2
	ds_read_b128 v[66:69], v65 offset:33792
	ds_read_b128 v[114:117], v65 offset:35840
	ds_read_b128 v[118:121], v65 offset:37888
	ds_read_b128 v[122:125], v65 offset:39936
	v_mfma_f32_16x16x32_bf16 v[70:73], v[110:113], v[20:23], v[70:73]
	ds_read_b128 v[110:113], v65 offset:41984
	ds_read_b128 v[126:129], v65 offset:44032
	ds_read_b128 v[130:133], v65 offset:46080
	ds_read_b128 v[134:137], v65 offset:48128
	v_mfma_f32_16x16x32_bf16 v[74:77], v[106:109], v[20:23], v[74:77]
	s_add_u32 s100, s10, 0x11c30100
	s_addc_u32 s101, s11, 0
	s_mov_b32 m0, s15
	s_nop 0
	global_load_lds_dwordx4 v241, s[100:101]
	s_waitcnt lgkmcnt(0)
	v_mfma_f32_16x16x32_bf16 v[66:69], v[66:69], v[20:23], v[78:81]
	v_mfma_f32_16x16x32_bf16 v[78:81], v[114:117], v[20:23], v[82:85]
	v_mfma_f32_16x16x32_bf16 v[82:85], v[118:121], v[20:23], v[86:89]
	v_mfma_f32_16x16x32_bf16 v[86:89], v[122:125], v[20:23], v[90:93]
	v_mfma_f32_16x16x32_bf16 v[90:93], v[110:113], v[20:23], v[94:97]
	v_mfma_f32_16x16x32_bf16 v[94:97], v[126:129], v[20:23], v[98:101]
	s_nop 2
	ds_read_b128 v[98:101], v65 offset:31744
	ds_read_b128 v[106:109], v65 offset:29696
	ds_read_b128 v[110:113], v65 offset:27648
	ds_read_b128 v[114:117], v65 offset:25600
	v_mfma_f32_16x16x32_bf16 v[102:105], v[130:133], v[20:23], v[102:105]
	ds_read_b128 v[118:121], v65 offset:23552
	ds_read_b128 v[122:125], v65 offset:21504
	ds_read_b128 v[126:129], v65 offset:19456
	ds_read_b128 v[130:133], v65 offset:17408
	v_mfma_f32_16x16x32_bf16 v[20:23], v[134:137], v[20:23], v[24:27]
	s_add_u32 s100, s10, 0x11c38100
	s_addc_u32 s101, s11, 0
	s_mov_b32 m0, s16
	s_nop 0
	global_load_lds_dwordx4 v241, s[100:101]
	s_waitcnt lgkmcnt(0)
	v_mfma_f32_16x16x32_bf16 v[24:27], v[130:133], v[16:19], v[28:31]
	v_mfma_f32_16x16x32_bf16 v[28:31], v[126:129], v[16:19], v[38:41]
	v_mfma_f32_16x16x32_bf16 v[38:41], v[122:125], v[16:19], v[42:45]
	v_mfma_f32_16x16x32_bf16 v[42:45], v[118:121], v[16:19], v[50:53]
	v_mfma_f32_16x16x32_bf16 v[50:53], v[114:117], v[16:19], v[54:57]
	v_mfma_f32_16x16x32_bf16 v[54:57], v[110:113], v[16:19], v[58:61]
	s_nop 2
	ds_read_b128 v[58:61], v65 offset:50176
	ds_read_b128 v[110:113], v65 offset:52224
	ds_read_b128 v[114:117], v65 offset:54272
	ds_read_b128 v[118:121], v65 offset:56320
	v_mfma_f32_16x16x32_bf16 v[70:73], v[106:109], v[16:19], v[70:73]
	ds_read_b128 v[106:109], v65 offset:58368
	ds_read_b128 v[122:125], v65 offset:60416
	ds_read_b128 v[126:129], v65 offset:62464
	ds_read_b128 v[62:65], v65 offset:64512
	v_mfma_f32_16x16x32_bf16 v[74:77], v[98:101], v[16:19], v[74:77]
	s_add_u32 s100, s10, 0x11c30180
	s_addc_u32 s101, s11, 0
	s_mov_b32 m0, s17
	s_nop 0
	global_load_lds_dwordx4 v241, s[100:101]
	s_waitcnt lgkmcnt(0)
	v_mfma_f32_16x16x32_bf16 v[58:61], v[58:61], v[16:19], v[66:69]
	v_mfma_f32_16x16x32_bf16 v[66:69], v[110:113], v[16:19], v[78:81]
	v_mfma_f32_16x16x32_bf16 v[78:81], v[114:117], v[16:19], v[82:85]
	v_mfma_f32_16x16x32_bf16 v[82:85], v[118:121], v[16:19], v[86:89]
	v_mfma_f32_16x16x32_bf16 v[86:89], v[106:109], v[16:19], v[90:93]
	v_mfma_f32_16x16x32_bf16 v[90:93], v[122:125], v[16:19], v[94:97]
	v_mfma_f32_16x16x32_bf16 v[94:97], v[126:129], v[16:19], v[102:105]
	v_mfma_f32_16x16x32_bf16 v[16:19], v[62:65], v[16:19], v[20:23]
	s_add_u32 s100, s10, 0x11c38180
	s_addc_u32 s101, s11, 0
	s_mov_b32 m0, s18
	s_nop 0
	global_load_lds_dwordx4 v241, s[100:101]
	s_waitcnt vmcnt(0)
	s_waitcnt vmcnt(0)
	s_barrier
	s_nop 0
	ds_read_b128 v[20:23], v48
	ds_read_b128 v[62:65], v48 offset:2048
	s_waitcnt lgkmcnt(1)
	v_mfma_f32_16x16x32_bf16 v[20:23], v[20:23], v[12:15], v[24:27]
	s_nop 2
	ds_read_b128 v[24:27], v48 offset:4096
	s_waitcnt lgkmcnt(1)
	v_mfma_f32_16x16x32_bf16 v[28:31], v[62:65], v[12:15], v[28:31]
	ds_read_b128 v[62:65], v48 offset:6144
	s_waitcnt lgkmcnt(1)
	v_mfma_f32_16x16x32_bf16 v[24:27], v[24:27], v[12:15], v[38:41]
	s_nop 2
	ds_read_b128 v[38:41], v48 offset:8192
	s_waitcnt lgkmcnt(1)
	v_mfma_f32_16x16x32_bf16 v[42:45], v[62:65], v[12:15], v[42:45]
	ds_read_b128 v[62:65], v48 offset:10240
	s_waitcnt lgkmcnt(1)
	v_mfma_f32_16x16x32_bf16 v[38:41], v[38:41], v[12:15], v[50:53]
	s_nop 2
	ds_read_b128 v[50:53], v48 offset:12288
	ds_read_b128 v[98:101], v48 offset:14336
	s_waitcnt lgkmcnt(2)
	v_mfma_f32_16x16x32_bf16 v[54:57], v[62:65], v[12:15], v[54:57]
	ds_read_b128 v[62:65], v48 offset:32768
	ds_read_b128 v[102:105], v48 offset:34816
	ds_read_b128 v[106:109], v48 offset:36864
	ds_read_b128 v[110:113], v48 offset:38912
	s_waitcnt lgkmcnt(5)
	v_mfma_f32_16x16x32_bf16 v[50:53], v[50:53], v[12:15], v[70:73]
	s_nop 2
	ds_read_b128 v[70:73], v48 offset:40960
	ds_read_b128 v[114:117], v48 offset:43008
	ds_read_b128 v[118:121], v48 offset:45056
	ds_read_b128 v[122:125], v48 offset:47104
	s_waitcnt lgkmcnt(8)
	v_mfma_f32_16x16x32_bf16 v[74:77], v[98:101], v[12:15], v[74:77]
	s_waitcnt lgkmcnt(7)
	v_mfma_f32_16x16x32_bf16 v[58:61], v[62:65], v[12:15], v[58:61]
	s_waitcnt lgkmcnt(6)
	v_mfma_f32_16x16x32_bf16 v[62:65], v[102:105], v[12:15], v[66:69]
	s_waitcnt lgkmcnt(5)
	v_mfma_f32_16x16x32_bf16 v[66:69], v[106:109], v[12:15], v[78:81]
	s_waitcnt lgkmcnt(4)
	v_mfma_f32_16x16x32_bf16 v[78:81], v[110:113], v[12:15], v[82:85]
	s_waitcnt lgkmcnt(3)
	v_mfma_f32_16x16x32_bf16 v[70:73], v[70:73], v[12:15], v[86:89]
	s_waitcnt lgkmcnt(2)
	v_mfma_f32_16x16x32_bf16 v[82:85], v[114:117], v[12:15], v[90:93]
	s_nop 0
	ds_read_b128 v[86:89], v48 offset:30720
	s_nop 0
	ds_read_b128 v[90:93], v48 offset:28672
	ds_read_b128 v[98:101], v48 offset:26624
	ds_read_b128 v[102:105], v48 offset:24576
	s_waitcnt lgkmcnt(5)
	v_mfma_f32_16x16x32_bf16 v[94:97], v[118:121], v[12:15], v[94:97]
	ds_read_b128 v[106:109], v48 offset:22528
	ds_read_b128 v[110:113], v48 offset:20480
	ds_read_b128 v[114:117], v48 offset:18432
	ds_read_b128 v[118:121], v48 offset:16384
	s_waitcnt lgkmcnt(8)
	v_mfma_f32_16x16x32_bf16 v[12:15], v[122:125], v[12:15], v[16:19]
	s_waitcnt lgkmcnt(0)
	v_mfma_f32_16x16x32_bf16 v[16:19], v[118:121], v[8:11], v[20:23]
	v_mfma_f32_16x16x32_bf16 v[20:23], v[114:117], v[8:11], v[28:31]
	v_mfma_f32_16x16x32_bf16 v[24:27], v[110:113], v[8:11], v[24:27]
	v_mfma_f32_16x16x32_bf16 v[28:31], v[106:109], v[8:11], v[42:45]
	v_mfma_f32_16x16x32_bf16 v[38:41], v[102:105], v[8:11], v[38:41]
	v_mfma_f32_16x16x32_bf16 v[42:45], v[98:101], v[8:11], v[54:57]
	s_nop 2
	ds_read_b128 v[54:57], v48 offset:49152
	ds_read_b128 v[98:101], v48 offset:51200
	ds_read_b128 v[102:105], v48 offset:53248
	ds_read_b128 v[106:109], v48 offset:55296
	v_mfma_f32_16x16x32_bf16 v[50:53], v[90:93], v[8:11], v[50:53]
	ds_read_b128 v[90:93], v48 offset:57344
	ds_read_b128 v[110:113], v48 offset:59392
	ds_read_b128 v[114:117], v48 offset:61440
	ds_read_b128 v[118:121], v48 offset:63488
	v_mfma_f32_16x16x32_bf16 v[74:77], v[86:89], v[8:11], v[74:77]
	s_waitcnt lgkmcnt(7)
	v_mfma_f32_16x16x32_bf16 v[54:57], v[54:57], v[8:11], v[58:61]
	s_waitcnt lgkmcnt(6)
	v_mfma_f32_16x16x32_bf16 v[58:61], v[98:101], v[8:11], v[62:65]
	s_waitcnt lgkmcnt(5)
	v_mfma_f32_16x16x32_bf16 v[62:65], v[102:105], v[8:11], v[66:69]
	s_waitcnt lgkmcnt(4)
	v_mfma_f32_16x16x32_bf16 v[66:69], v[106:109], v[8:11], v[78:81]
	s_waitcnt lgkmcnt(3)
	v_mfma_f32_16x16x32_bf16 v[70:73], v[90:93], v[8:11], v[70:73]
	s_waitcnt lgkmcnt(2)
	v_mfma_f32_16x16x32_bf16 v[78:81], v[110:113], v[8:11], v[82:85]
	s_nop 2
	ds_read_b128 v[82:85], v48 offset:15360
	ds_read_b128 v[86:89], v48 offset:13312
	ds_read_b128 v[90:93], v48 offset:11264
	ds_read_b128 v[98:101], v48 offset:9216
	s_waitcnt lgkmcnt(5)
	v_mfma_f32_16x16x32_bf16 v[94:97], v[114:117], v[8:11], v[94:97]
	ds_read_b128 v[102:105], v48 offset:7168
	ds_read_b128 v[106:109], v48 offset:5120
	ds_read_b128 v[110:113], v48 offset:3072
	ds_read_b128 v[114:117], v48 offset:1024
	s_waitcnt lgkmcnt(8)
	v_mfma_f32_16x16x32_bf16 v[8:11], v[118:121], v[8:11], v[12:15]
	s_waitcnt lgkmcnt(0)
	v_mfma_f32_16x16x32_bf16 v[12:15], v[114:117], v[4:7], v[16:19]
	v_mfma_f32_16x16x32_bf16 v[16:19], v[110:113], v[4:7], v[20:23]
	v_mfma_f32_16x16x32_bf16 v[20:23], v[106:109], v[4:7], v[24:27]
	v_mfma_f32_16x16x32_bf16 v[24:27], v[102:105], v[4:7], v[28:31]
	v_mfma_f32_16x16x32_bf16 v[28:31], v[98:101], v[4:7], v[38:41]
	v_mfma_f32_16x16x32_bf16 v[38:41], v[90:93], v[4:7], v[42:45]
	s_nop 2
	ds_read_b128 v[42:45], v48 offset:33792
	ds_read_b128 v[90:93], v48 offset:35840
	ds_read_b128 v[98:101], v48 offset:37888
	ds_read_b128 v[102:105], v48 offset:39936
	v_mfma_f32_16x16x32_bf16 v[50:53], v[86:89], v[4:7], v[50:53]
	ds_read_b128 v[86:89], v48 offset:41984
	ds_read_b128 v[106:109], v48 offset:44032
	ds_read_b128 v[110:113], v48 offset:46080
	ds_read_b128 v[114:117], v48 offset:48128
	v_mfma_f32_16x16x32_bf16 v[74:77], v[82:85], v[4:7], v[74:77]
	s_waitcnt lgkmcnt(7)
	v_mfma_f32_16x16x32_bf16 v[42:45], v[42:45], v[4:7], v[54:57]
	s_waitcnt lgkmcnt(6)
	v_mfma_f32_16x16x32_bf16 v[54:57], v[90:93], v[4:7], v[58:61]
	s_waitcnt lgkmcnt(5)
	v_mfma_f32_16x16x32_bf16 v[58:61], v[98:101], v[4:7], v[62:65]
	s_waitcnt lgkmcnt(4)
	v_mfma_f32_16x16x32_bf16 v[62:65], v[102:105], v[4:7], v[66:69]
	s_waitcnt lgkmcnt(3)
	v_mfma_f32_16x16x32_bf16 v[66:69], v[86:89], v[4:7], v[70:73]
	s_waitcnt lgkmcnt(2)
	v_mfma_f32_16x16x32_bf16 v[70:73], v[106:109], v[4:7], v[78:81]
	s_nop 2
	ds_read_b128 v[78:81], v48 offset:31744
	ds_read_b128 v[82:85], v48 offset:29696
	ds_read_b128 v[86:89], v48 offset:27648
	ds_read_b128 v[90:93], v48 offset:25600
	s_waitcnt lgkmcnt(5)
	v_mfma_f32_16x16x32_bf16 v[94:97], v[110:113], v[4:7], v[94:97]
	ds_read_b128 v[98:101], v48 offset:23552
	ds_read_b128 v[102:105], v48 offset:21504
	ds_read_b128 v[106:109], v48 offset:19456
	ds_read_b128 v[110:113], v48 offset:17408
	s_waitcnt lgkmcnt(8)
	v_mfma_f32_16x16x32_bf16 v[4:7], v[114:117], v[4:7], v[8:11]
	s_waitcnt lgkmcnt(0)
	v_mfma_f32_16x16x32_bf16 v[8:11], v[110:113], v[0:3], v[12:15]
	v_mfma_f32_16x16x32_bf16 v[12:15], v[106:109], v[0:3], v[16:19]
	v_mfma_f32_16x16x32_bf16 v[16:19], v[102:105], v[0:3], v[20:23]
	v_mfma_f32_16x16x32_bf16 v[20:23], v[98:101], v[0:3], v[24:27]
	v_mfma_f32_16x16x32_bf16 v[24:27], v[90:93], v[0:3], v[28:31]
	v_mfma_f32_16x16x32_bf16 v[28:31], v[86:89], v[0:3], v[38:41]
	s_nop 2
	ds_read_b128 v[38:41], v48 offset:50176
	ds_read_b128 v[86:89], v48 offset:52224
	ds_read_b128 v[90:93], v48 offset:54272
	ds_read_b128 v[98:101], v48 offset:56320
	v_mfma_f32_16x16x32_bf16 v[50:53], v[82:85], v[0:3], v[50:53]
	ds_read_b128 v[82:85], v48 offset:58368
	ds_read_b128 v[102:105], v48 offset:60416
	ds_read_b128 v[106:109], v48 offset:62464
	ds_read_b128 v[46:49], v48 offset:64512
	v_mfma_f32_16x16x32_bf16 v[74:77], v[78:81], v[0:3], v[74:77]
	s_waitcnt lgkmcnt(7)
	v_mfma_f32_16x16x32_bf16 v[38:41], v[38:41], v[0:3], v[42:45]
	s_waitcnt lgkmcnt(6)
	v_mfma_f32_16x16x32_bf16 v[42:45], v[86:89], v[0:3], v[54:57]
	s_waitcnt lgkmcnt(5)
	v_mfma_f32_16x16x32_bf16 v[54:57], v[90:93], v[0:3], v[58:61]
	s_waitcnt lgkmcnt(4)
	v_mfma_f32_16x16x32_bf16 v[58:61], v[98:101], v[0:3], v[62:65]
	s_waitcnt lgkmcnt(3)
	v_mfma_f32_16x16x32_bf16 v[62:65], v[82:85], v[0:3], v[66:69]
	s_waitcnt lgkmcnt(2)
	v_mfma_f32_16x16x32_bf16 v[66:69], v[102:105], v[0:3], v[70:73]
	s_waitcnt lgkmcnt(1)
	v_mfma_f32_16x16x32_bf16 v[70:73], v[106:109], v[0:3], v[94:97]
	s_waitcnt lgkmcnt(0)
	v_mfma_f32_16x16x32_bf16 v[0:3], v[46:49], v[0:3], v[4:7]
	s_nop 2
	v_mul_f32_e32 v200, v36, v8
	v_mul_f32_e32 v204, v36, v9
	v_cvt_pk_bf16_f32 v200, v200, v204
	v_mul_f32_e32 v201, v36, v10
	v_mul_f32_e32 v204, v36, v11
	v_cvt_pk_bf16_f32 v201, v201, v204
	v_mul_f32_e32 v202, v36, v12
	v_mul_f32_e32 v204, v36, v13
	v_cvt_pk_bf16_f32 v202, v202, v204
	v_mul_f32_e32 v203, v36, v14
	v_mul_f32_e32 v204, v36, v15
	v_cvt_pk_bf16_f32 v203, v203, v204
	s_nop 1
	v_permlane16_swap_b32_e32 v200, v202
	v_permlane16_swap_b32_e32 v201, v203
	global_store_dwordx4 v[214:215], v[200:203], off offset:512
	v_mul_f32_e32 v206, v36, v16
	v_mul_f32_e32 v210, v36, v17
	v_cvt_pk_bf16_f32 v206, v206, v210
	v_mul_f32_e32 v207, v36, v18
	v_mul_f32_e32 v210, v36, v19
	v_cvt_pk_bf16_f32 v207, v207, v210
	v_mul_f32_e32 v208, v36, v20
	v_mul_f32_e32 v210, v36, v21
	v_cvt_pk_bf16_f32 v208, v208, v210
	v_mul_f32_e32 v209, v36, v22
	v_mul_f32_e32 v210, v36, v23
	v_cvt_pk_bf16_f32 v209, v209, v210
	s_nop 1
	v_permlane16_swap_b32_e32 v206, v208
	v_permlane16_swap_b32_e32 v207, v209
	global_store_dwordx4 v[214:215], v[206:209], off offset:576
	v_mul_f32_e32 v200, v36, v24
	v_mul_f32_e32 v204, v36, v25
	v_cvt_pk_bf16_f32 v200, v200, v204
	v_mul_f32_e32 v201, v36, v26
	v_mul_f32_e32 v204, v36, v27
	v_cvt_pk_bf16_f32 v201, v201, v204
	v_mul_f32_e32 v202, v36, v28
	v_mul_f32_e32 v204, v36, v29
	v_cvt_pk_bf16_f32 v202, v202, v204
	v_mul_f32_e32 v203, v36, v30
	v_mul_f32_e32 v204, v36, v31
	v_cvt_pk_bf16_f32 v203, v203, v204
	s_nop 1
	v_permlane16_swap_b32_e32 v200, v202
	v_permlane16_swap_b32_e32 v201, v203
	global_store_dwordx4 v[214:215], v[200:203], off offset:640
	v_mul_f32_e32 v206, v36, v50
	v_mul_f32_e32 v210, v36, v51
	v_cvt_pk_bf16_f32 v206, v206, v210
	v_mul_f32_e32 v207, v36, v52
	v_mul_f32_e32 v210, v36, v53
	v_cvt_pk_bf16_f32 v207, v207, v210
	v_mul_f32_e32 v208, v36, v74
	v_mul_f32_e32 v210, v36, v75
	v_cvt_pk_bf16_f32 v208, v208, v210
	v_mul_f32_e32 v209, v36, v76
	v_mul_f32_e32 v210, v36, v77
	v_cvt_pk_bf16_f32 v209, v209, v210
	s_nop 1
	v_permlane16_swap_b32_e32 v206, v208
	v_permlane16_swap_b32_e32 v207, v209
	global_store_dwordx4 v[214:215], v[206:209], off offset:704
	v_mul_f32_e32 v200, v36, v38
	v_mul_f32_e32 v204, v36, v39
	v_cvt_pk_bf16_f32 v200, v200, v204
	v_mul_f32_e32 v201, v36, v40
	v_mul_f32_e32 v204, v36, v41
	v_cvt_pk_bf16_f32 v201, v201, v204
	v_mul_f32_e32 v202, v36, v42
	v_mul_f32_e32 v204, v36, v43
	v_cvt_pk_bf16_f32 v202, v202, v204
	v_mul_f32_e32 v203, v36, v44
	v_mul_f32_e32 v204, v36, v45
	v_cvt_pk_bf16_f32 v203, v203, v204
	s_nop 1
	v_permlane16_swap_b32_e32 v200, v202
	v_permlane16_swap_b32_e32 v201, v203
	global_store_dwordx4 v[214:215], v[200:203], off offset:768
	v_mul_f32_e32 v206, v36, v54
	v_mul_f32_e32 v210, v36, v55
	v_cvt_pk_bf16_f32 v206, v206, v210
	v_mul_f32_e32 v207, v36, v56
	v_mul_f32_e32 v210, v36, v57
	v_cvt_pk_bf16_f32 v207, v207, v210
	v_mul_f32_e32 v208, v36, v58
	v_mul_f32_e32 v210, v36, v59
	v_cvt_pk_bf16_f32 v208, v208, v210
	v_mul_f32_e32 v209, v36, v60
	v_mul_f32_e32 v210, v36, v61
	v_cvt_pk_bf16_f32 v209, v209, v210
	s_nop 1
	v_permlane16_swap_b32_e32 v206, v208
	v_permlane16_swap_b32_e32 v207, v209
	global_store_dwordx4 v[214:215], v[206:209], off offset:832
	v_mul_f32_e32 v200, v36, v62
	v_mul_f32_e32 v204, v36, v63
	v_cvt_pk_bf16_f32 v200, v200, v204
	v_mul_f32_e32 v201, v36, v64
	v_mul_f32_e32 v204, v36, v65
	v_cvt_pk_bf16_f32 v201, v201, v204
	v_mul_f32_e32 v202, v36, v66
	v_mul_f32_e32 v204, v36, v67
	v_cvt_pk_bf16_f32 v202, v202, v204
	v_mul_f32_e32 v203, v36, v68
	v_mul_f32_e32 v204, v36, v69
	v_cvt_pk_bf16_f32 v203, v203, v204
	s_nop 1
	v_permlane16_swap_b32_e32 v200, v202
	v_permlane16_swap_b32_e32 v201, v203
	global_store_dwordx4 v[214:215], v[200:203], off offset:896
	v_mul_f32_e32 v206, v36, v70
	v_mul_f32_e32 v210, v36, v71
	v_cvt_pk_bf16_f32 v206, v206, v210
	v_mul_f32_e32 v207, v36, v72
	v_mul_f32_e32 v210, v36, v73
	v_cvt_pk_bf16_f32 v207, v207, v210
	v_mul_f32_e32 v208, v36, v0
	v_mul_f32_e32 v210, v36, v1
	v_cvt_pk_bf16_f32 v208, v208, v210
	v_mul_f32_e32 v209, v36, v2
	v_mul_f32_e32 v210, v36, v3
	v_cvt_pk_bf16_f32 v209, v209, v210
	s_nop 1
	v_permlane16_swap_b32_e32 v206, v208
	v_permlane16_swap_b32_e32 v207, v209
	global_store_dwordx4 v[214:215], v[206:209], off offset:960
	s_waitcnt vmcnt(0)
	s_barrier

.LBB0_1392:
	s_add_i32 s3, s3, 1
	s_and_b32 s4, s3, 3
	s_or_b32 s4, s4, s81
	s_mul_i32 s4, s4, 20
	s_ashr_i32 s5, s4, 31
	s_lshl_b64 s[4:5], s[4:5], 20
	s_barrier
	s_waitcnt vmcnt(7)
	ds_write_b128 v139, v[0:3] offset:33280
	s_waitcnt vmcnt(6)
	ds_write_b128 v139, v[4:7] offset:33792
	s_waitcnt vmcnt(5)
	ds_write_b128 v139, v[12:15] offset:34304
	s_waitcnt vmcnt(4)
	ds_write_b128 v139, v[16:19] offset:34816
	v_lshl_add_u64 v[12:13], v[104:105], 0, s[4:5]
	v_add_co_u32_e32 v4, vcc, s51, v12
	s_mov_b32 s4, 0
	s_nop 0
	v_addc_co_u32_e32 v5, vcc, 0, v13, vcc
	v_add_co_u32_e32 v14, vcc, 0x200000, v12
	global_load_dwordx4 v[0:3], v[12:13], off
	s_nop 0
	global_load_dwordx4 v[4:7], v[4:5], off
	v_addc_co_u32_e32 v15, vcc, 0, v13, vcc
	v_add_co_u32_e32 v16, vcc, 0x300000, v12
	v_mov_b32_e32 v84, v133
	s_nop 0
	v_addc_co_u32_e32 v17, vcc, 0, v13, vcc
	global_load_dwordx4 v[12:15], v[14:15], off
	s_nop 0
	global_load_dwordx4 v[16:19], v[16:17], off
	s_waitcnt lgkmcnt(0)
	s_barrier

.LBB0_1529:
	s_mov_b32 s0, s40
	s_lshl_b32 s1, s22, 7
	v_mov_b32_e32 v154, v182
	v_mov_b32_e32 v160, v183
	s_or_b32 s1, s1, s48
	s_lshl_b32 s0, s0, 8
	v_lshl_add_u32 v152, v160, 2, s1
	v_ashrrev_i32_e32 v153, 31, v152
	v_lshlrev_b64 v[80:81], 2, v[152:153]
	v_lshl_add_u64 v[82:83], s[12:13], 0, v[80:81]
	v_lshl_add_u64 v[84:85], s[26:27], 0, v[80:81]
	global_load_dwordx4 v[100:103], v[84:85], off
	global_load_dwordx4 v[92:95], v[82:83], off
	s_nop 0
	global_load_dwordx4 v[80:83], v[82:83], off offset:256
	s_nop 0
	global_load_dwordx4 v[84:87], v[84:85], off offset:256
	s_add_i32 s0, s0, s45
	v_add_u32_e32 v156, s0, v154
	v_lshlrev_b64 v[190:191], 1, v[152:153]
	v_ashrrev_i32_e32 v157, 31, v156
	v_lshl_add_u64 v[154:155], s[16:17], 0, v[190:191]
	v_lshlrev_b64 v[192:193], 12, v[156:157]
	v_lshl_add_u64 v[158:159], v[154:155], 0, v[192:193]
	v_mbcnt_lo_u32_b32 v214, -1, 0
	v_mbcnt_hi_u32_b32 v214, -1, v214
	v_lshrrev_b32_e32 v214, 4, v214
	v_and_b32_e32 v214, 1, v214
	v_mul_u32_u24_e32 v214, 0x78, v214
	v_mov_b32_e32 v215, 0
	global_load_dwordx2 v[194:195], v[158:159], off
	global_load_dwordx2 v[196:197], v[158:159], off offset:128
	v_add_u32_e32 v172, 16, v156
	v_add_u32_e32 v166, 32, v156
	v_add_u32_e32 v158, 48, v156
	v_ashrrev_i32_e32 v173, 31, v172
	v_ashrrev_i32_e32 v167, 31, v166
	v_ashrrev_i32_e32 v159, 31, v158
	v_lshlrev_b64 v[176:177], 12, v[172:173]
	v_lshlrev_b64 v[168:169], 12, v[166:167]
	v_cmp_eq_u32_e32 vcc, 0, v160
	v_lshlrev_b64 v[160:161], 12, v[158:159]
	v_lshl_add_u64 v[162:163], v[154:155], 0, v[176:177]
	v_lshl_add_u64 v[164:165], v[154:155], 0, v[168:169]
	v_lshl_add_u64 v[198:199], v[154:155], 0, v[160:161]
	global_load_dwordx2 v[180:181], v[162:163], off
	global_load_dwordx2 v[178:179], v[162:163], off offset:128
	global_load_dwordx2 v[174:175], v[164:165], off
	global_load_dwordx2 v[170:171], v[164:165], off offset:128
	s_nop 0
	global_load_dwordx2 v[164:165], v[198:199], off
	global_load_dwordx2 v[162:163], v[198:199], off offset:128
	v_add_u32_e32 v216, 0x80, v156
	v_ashrrev_i32_e32 v217, 31, v216
	v_lshlrev_b64 v[216:217], 12, v[216:217]
	v_lshl_add_u64 v[216:217], v[154:155], 0, v[216:217]
	v_add_u32_e32 v218, 0x90, v156
	v_ashrrev_i32_e32 v219, 31, v218
	v_lshlrev_b64 v[218:219], 12, v[218:219]
	v_lshl_add_u64 v[218:219], v[154:155], 0, v[218:219]
	v_add_u32_e32 v220, 0xa0, v156
	v_ashrrev_i32_e32 v221, 31, v220
	v_lshlrev_b64 v[220:221], 12, v[220:221]
	v_lshl_add_u64 v[220:221], v[154:155], 0, v[220:221]
	v_add_u32_e32 v240, 0xb0, v156
	v_ashrrev_i32_e32 v241, 31, v240
	v_lshlrev_b64 v[240:241], 12, v[240:241]
	v_lshl_add_u64 v[240:241], v[154:155], 0, v[240:241]
	global_load_dwordx2 v[224:225], v[216:217], off
	global_load_dwordx2 v[226:227], v[216:217], off offset:128
	global_load_dwordx2 v[228:229], v[218:219], off
	global_load_dwordx2 v[230:231], v[218:219], off offset:128
	global_load_dwordx2 v[232:233], v[220:221], off
	global_load_dwordx2 v[234:235], v[220:221], off offset:128
	global_load_dwordx2 v[236:237], v[240:241], off
	global_load_dwordx2 v[238:239], v[240:241], off offset:128
	s_lshl_b32 s0, s22, 2
	s_ashr_i32 s1, s0, 31
	s_waitcnt vmcnt(8)
	v_add_f32_e32 v141, v141, v101
	v_add_f32_e32 v143, v143, v103
	v_add_f32_e32 v140, v140, v100
	v_add_f32_e32 v142, v142, v102
	v_add_f32_e32 v132, v132, v84
	v_mul_f32_e32 v141, 0xbfb8aa3b, v141
	v_mul_f32_e32 v143, 0xbfb8aa3b, v143
	v_mul_f32_e32 v140, 0xbfb8aa3b, v140
	v_mul_f32_e32 v142, 0xbfb8aa3b, v142
	v_mul_f32_e32 v132, 0xbfb8aa3b, v132
	v_exp_f32_e32 v141, v141
	v_exp_f32_e32 v143, v143
	v_exp_f32_e32 v140, v140
	v_exp_f32_e32 v142, v142
	v_exp_f32_e32 v132, v132
	v_add_f32_e32 v141, 1.0, v141
	v_add_f32_e32 v143, 1.0, v143
	v_add_f32_e32 v140, 1.0, v140
	v_add_f32_e32 v142, 1.0, v142
	v_add_f32_e32 v132, 1.0, v132
	v_rcp_f32_e32 v141, v141
	v_rcp_f32_e32 v143, v143
	v_add_f32_e32 v133, v133, v85
	v_rcp_f32_e32 v140, v140
	v_rcp_f32_e32 v142, v142
	v_rcp_f32_e32 v132, v132
	v_mul_f32_e32 v133, 0xbfb8aa3b, v133
	v_add_f32_e32 v137, v137, v93
	v_add_f32_e32 v139, v139, v95
	v_lshlrev_b32_e32 v189, 16, v194
	v_and_b32_e32 v194, 0xffff0000, v194
	v_lshlrev_b32_e32 v198, 16, v195
	v_and_b32_e32 v195, 0xffff0000, v195
	v_exp_f32_e32 v133, v133
	v_add_f32_e32 v136, v136, v92
	v_add_f32_e32 v138, v138, v94
	v_add_f32_e32 v128, v128, v80
	v_lshlrev_b32_e32 v199, 16, v196
	v_fmac_f32_e32 v194, v137, v141
	v_fmac_f32_e32 v195, v139, v143
	v_fmac_f32_e32 v189, v136, v140
	v_fmac_f32_e32 v198, v138, v142
	v_fmac_f32_e32 v199, v128, v132
	v_mul_f32_e32 v128, v194, v194
	v_mul_f32_e32 v132, v195, v195
	v_add_f32_e32 v134, v134, v86
	v_fmac_f32_e32 v128, v189, v189
	v_fmac_f32_e32 v132, v198, v198
	v_add_f32_e32 v133, 1.0, v133
	v_add_f32_e32 v128, v128, v132
	v_mul_f32_e32 v132, 0xbfb8aa3b, v134
	v_add_f32_e32 v134, v135, v87
	v_rcp_f32_e32 v133, v133
	v_exp_f32_e32 v132, v132
	v_mul_f32_e32 v134, 0xbfb8aa3b, v134
	v_exp_f32_e32 v134, v134
	v_add_f32_e32 v129, v129, v81
	v_and_b32_e32 v196, 0xffff0000, v196
	v_fmac_f32_e32 v196, v129, v133
	v_add_f32_e32 v129, 1.0, v132
	v_rcp_f32_e32 v129, v129
	v_add_f32_e32 v132, 1.0, v134
	v_rcp_f32_e32 v132, v132
	v_lshlrev_b32_e32 v200, 16, v197
	v_add_f32_e32 v130, v130, v82
	v_and_b32_e32 v197, 0xffff0000, v197
	v_fmac_f32_e32 v200, v130, v129
	v_add_f32_e32 v129, v131, v83
	v_fmac_f32_e32 v197, v129, v132
	v_mul_f32_e32 v129, v196, v196
	v_mul_f32_e32 v130, v197, v197
	v_fmac_f32_e32 v129, v199, v199
	v_fmac_f32_e32 v130, v200, v200
	v_add_f32_e32 v129, v129, v130
	v_and_b32_e32 v130, 64, v188
	v_add_f32_e32 v129, v128, v129
	v_xor_b32_e32 v128, 16, v188
	v_add_u32_e32 v136, 64, v130
	v_cmp_lt_i32_e64 s[2:3], v128, v136
	v_lshl_add_u64 v[130:131], s[16:17], 0, v[192:193]
	v_lshl_add_u64 v[134:135], v[130:131], 0, v[190:191]
	v_cndmask_b32_e64 v128, v188, v128, s[2:3]
	v_lshlrev_b32_e32 v128, 2, v128
	v_mov_b32_e32 v137, v129
	s_nop 1
	v_permlane16_swap_b32_e32 v137, v129
	v_cvt_pk_bf16_f32 v132, v189, v194
	v_cvt_pk_bf16_f32 v133, v198, v195
	v_mov_b32_e32 v204, v132
	v_mov_b32_e32 v205, v133
	v_cvt_pk_bf16_f32 v132, v199, v196
	s_waitcnt lgkmcnt(0)
	v_add_f32_e32 v130, v129, v137
	v_xor_b32_e32 v129, 32, v188
	v_cmp_lt_i32_e64 s[2:3], v129, v136
	v_cvt_pk_bf16_f32 v133, v200, v197
	v_mov_b32_e32 v206, v132
	v_mov_b32_e32 v207, v133
	v_lshl_add_u64 v[212:213], v[134:135], 0, v[214:215]
	s_nop 0
	v_permlane16_swap_b32_e32 v204, v206
	v_permlane16_swap_b32_e32 v205, v207
	global_store_dwordx4 v[212:213], v[204:207], off
	s_nop 0
	v_cndmask_b32_e64 v129, v188, v129, s[2:3]
	v_lshlrev_b32_e32 v129, 2, v129
	v_mov_b32_e32 v131, v130
	s_nop 1
	v_permlane32_swap_b32_e32 v131, v130
	s_and_saveexec_b64 s[2:3], vcc
	s_cbranch_execz .LBB0_1531
	s_waitcnt lgkmcnt(0)
	v_add_f32_e32 v132, v130, v131
	v_lshlrev_b64 v[130:131], 8, v[156:157]
	v_lshl_add_u64 v[130:131], s[18:19], 0, v[130:131]
	v_lshl_add_u64 v[130:131], s[0:1], 2, v[130:131]
	s_lshl_b32 s22, s44, 2
	v_lshl_add_u64 v[130:131], v[130:131], 0, s[22:23]
	global_store_dword v[130:131], v132, off

.LBB0_1537:
	s_or_b64 exec, exec, s[2:3]
	v_add_u32_e32 v78, 0x80, v156
	v_ashrrev_i32_e32 v79, 31, v78
	v_lshlrev_b64 v[90:91], 12, v[78:79]
	s_waitcnt lgkmcnt(0)
	v_lshl_add_u64 v[64:65], v[154:155], 0, v[90:91]
	s_waitcnt vmcnt(8)
	v_mov_b32_e32 v96, v224
	v_mov_b32_e32 v97, v225
	v_mov_b32_e32 v98, v226
	v_mov_b32_e32 v99, v227
	v_add_u32_e32 v70, 0x90, v156
	v_add_u32_e32 v66, 0xa0, v156
	v_add_u32_e32 v64, 0xb0, v156
	v_ashrrev_i32_e32 v71, 31, v70
	v_ashrrev_i32_e32 v67, 31, v66
	v_add_f32_e32 v110, v62, v102
	v_add_f32_e32 v112, v63, v103
	v_ashrrev_i32_e32 v65, 31, v64
	v_lshlrev_b64 v[74:75], 12, v[70:71]
	v_lshlrev_b64 v[62:63], 12, v[66:67]
	v_add_f32_e32 v106, v60, v100
	v_add_f32_e32 v107, v56, v92
	v_add_f32_e32 v108, v61, v101
	v_add_f32_e32 v109, v57, v93
	v_add_f32_e32 v111, v58, v94
	v_add_f32_e32 v113, v59, v95
	v_lshlrev_b64 v[56:57], 12, v[64:65]
	v_lshl_add_u64 v[58:59], v[154:155], 0, v[74:75]
	v_lshl_add_u64 v[60:61], v[154:155], 0, v[62:63]
	v_lshl_add_u64 v[104:105], v[154:155], 0, v[56:57]
	v_mov_b32_e32 v88, v228
	v_mov_b32_e32 v89, v229
	v_mov_b32_e32 v76, v230
	v_mov_b32_e32 v77, v231
	v_mov_b32_e32 v72, v232
	v_mov_b32_e32 v73, v233
	v_mov_b32_e32 v68, v234
	v_mov_b32_e32 v69, v235
	s_nop 0
	v_mov_b32_e32 v60, v236
	v_mov_b32_e32 v61, v237
	v_mov_b32_e32 v58, v238
	v_mov_b32_e32 v59, v239
	v_add_f32_e32 v52, v52, v84
	v_add_f32_e32 v53, v53, v85
	v_mul_f32_e32 v105, 0xbfb8aa3b, v108
	v_mul_f32_e32 v108, 0xbfb8aa3b, v112
	v_mul_f32_e32 v104, 0xbfb8aa3b, v106
	v_mul_f32_e32 v106, 0xbfb8aa3b, v110
	v_mul_f32_e32 v52, 0xbfb8aa3b, v52
	v_mul_f32_e32 v53, 0xbfb8aa3b, v53
	v_exp_f32_e32 v105, v105
	v_exp_f32_e32 v108, v108
	v_exp_f32_e32 v104, v104
	v_exp_f32_e32 v106, v106
	v_exp_f32_e32 v52, v52
	v_exp_f32_e32 v53, v53
	v_add_f32_e32 v105, 1.0, v105
	v_add_f32_e32 v108, 1.0, v108
	v_add_f32_e32 v54, v54, v86
	v_add_f32_e32 v104, 1.0, v104
	v_add_f32_e32 v106, 1.0, v106
	v_add_f32_e32 v52, 1.0, v52
	v_add_f32_e32 v53, 1.0, v53
	v_rcp_f32_e32 v105, v105
	v_rcp_f32_e32 v108, v108
	v_add_f32_e32 v55, v55, v87
	v_mul_f32_e32 v54, 0xbfb8aa3b, v54
	v_rcp_f32_e32 v104, v104
	v_rcp_f32_e32 v106, v106
	v_rcp_f32_e32 v52, v52
	v_rcp_f32_e32 v53, v53
	v_mul_f32_e32 v55, 0xbfb8aa3b, v55
	v_exp_f32_e32 v54, v54
	v_exp_f32_e32 v55, v55
	v_add_f32_e32 v48, v48, v80
	v_add_f32_e32 v49, v49, v81
	v_add_f32_e32 v54, 1.0, v54
	v_rcp_f32_e32 v54, v54
	v_add_f32_e32 v50, v50, v82
	v_lshlrev_b32_e32 v110, 16, v96
	v_and_b32_e32 v96, 0xffff0000, v96
	v_lshlrev_b32_e32 v112, 16, v97
	v_and_b32_e32 v97, 0xffff0000, v97
	v_lshlrev_b32_e32 v114, 16, v98
	v_and_b32_e32 v98, 0xffff0000, v98
	v_fmac_f32_e32 v96, v109, v105
	v_fmac_f32_e32 v97, v113, v108
	v_fmac_f32_e32 v110, v107, v104
	v_fmac_f32_e32 v112, v111, v106
	v_fmac_f32_e32 v114, v48, v52
	v_fmac_f32_e32 v98, v49, v53
	v_mul_f32_e32 v48, v96, v96
	v_mul_f32_e32 v49, v97, v97
	v_fmac_f32_e32 v48, v110, v110
	v_fmac_f32_e32 v49, v112, v112
	v_add_f32_e32 v48, v48, v49
	v_add_f32_e32 v49, 1.0, v55
	v_rcp_f32_e32 v49, v49
	v_lshlrev_b32_e32 v115, 16, v99
	v_and_b32_e32 v99, 0xffff0000, v99
	v_fmac_f32_e32 v115, v50, v54
	v_add_f32_e32 v50, v51, v83
	v_fmac_f32_e32 v99, v50, v49
	v_mul_f32_e32 v49, v98, v98
	v_mul_f32_e32 v50, v99, v99
	v_fmac_f32_e32 v49, v114, v114
	v_fmac_f32_e32 v50, v115, v115
	v_add_f32_e32 v49, v49, v50
	v_add_f32_e32 v54, v48, v49
	v_mov_b32_e32 v55, v54
	s_nop 1
	v_permlane16_swap_b32_e32 v55, v54
	v_lshl_add_u64 v[48:49], s[16:17], 0, v[90:91]
	v_lshl_add_u64 v[52:53], v[152:153], 1, v[48:49]
	v_cvt_pk_bf16_f32 v50, v110, v96
	v_cvt_pk_bf16_f32 v51, v112, v97
	s_waitcnt lgkmcnt(0)
	v_add_f32_e32 v48, v54, v55
	v_mov_b32_e32 v49, v48
	s_nop 1
	v_permlane32_swap_b32_e32 v49, v48
	v_mov_b32_e32 v204, v50
	v_mov_b32_e32 v205, v51
	v_cvt_pk_bf16_f32 v50, v114, v98
	v_cvt_pk_bf16_f32 v51, v115, v99
	v_mov_b32_e32 v206, v50
	v_mov_b32_e32 v207, v51
	v_lshl_add_u64 v[212:213], v[52:53], 0, v[214:215]
	s_nop 0
	v_permlane16_swap_b32_e32 v204, v206
	v_permlane16_swap_b32_e32 v205, v207
	global_store_dwordx4 v[212:213], v[204:207], off
	s_and_saveexec_b64 s[2:3], vcc
	s_cbranch_execz .LBB0_1539
	s_waitcnt lgkmcnt(0)
	v_add_f32_e32 v50, v48, v49
	v_lshlrev_b64 v[48:49], 8, v[78:79]
	v_lshl_add_u64 v[48:49], s[18:19], 0, v[48:49]
	v_lshl_add_u64 v[48:49], s[0:1], 2, v[48:49]
	s_lshl_b32 s22, s44, 2
	v_lshl_add_u64 v[48:49], v[48:49], 0, s[22:23]
	global_store_dword v[48:49], v50, off
.LBB0_1539:
	s_or_b64 exec, exec, s[2:3]
	v_add_f32_e32 v44, v44, v100
	v_mul_f32_e32 v44, 0xbfb8aa3b, v44
	v_exp_f32_e32 v44, v44
	v_add_f32_e32 v45, v45, v101
	v_mul_f32_e32 v45, 0xbfb8aa3b, v45
	v_exp_f32_e32 v45, v45
	v_add_f32_e32 v44, 1.0, v44
	v_rcp_f32_e32 v44, v44
	v_lshlrev_b32_e32 v48, 16, v88
	v_add_f32_e32 v40, v40, v92
	s_waitcnt lgkmcnt(0)
	v_and_b32_e32 v49, 0xffff0000, v88
	v_fmac_f32_e32 v48, v40, v44
	v_add_f32_e32 v44, v46, v102
	v_add_f32_e32 v40, 1.0, v45
	v_mul_f32_e32 v44, 0xbfb8aa3b, v44
	v_add_f32_e32 v45, v47, v103
	v_rcp_f32_e32 v40, v40
	v_exp_f32_e32 v44, v44
	v_mul_f32_e32 v45, 0xbfb8aa3b, v45
	v_exp_f32_e32 v45, v45
	v_add_f32_e32 v41, v41, v93
	v_add_f32_e32 v36, v36, v84
	v_fmac_f32_e32 v49, v41, v40
	v_add_f32_e32 v40, 1.0, v44
	v_mul_f32_e32 v36, 0xbfb8aa3b, v36
	v_rcp_f32_e32 v40, v40
	v_add_f32_e32 v41, 1.0, v45
	v_exp_f32_e32 v36, v36
	v_rcp_f32_e32 v41, v41
	v_lshlrev_b32_e32 v50, 16, v89
	v_add_f32_e32 v42, v42, v94
	v_and_b32_e32 v51, 0xffff0000, v89
	v_fmac_f32_e32 v50, v42, v40
	v_add_f32_e32 v40, v43, v95
	v_add_f32_e32 v36, 1.0, v36
	v_add_f32_e32 v37, v37, v85
	v_fmac_f32_e32 v51, v40, v41
	v_rcp_f32_e32 v36, v36
	v_mul_f32_e32 v37, 0xbfb8aa3b, v37
	v_mul_f32_e32 v40, v49, v49
	v_mul_f32_e32 v41, v51, v51
	v_exp_f32_e32 v37, v37
	v_fmac_f32_e32 v40, v48, v48
	v_fmac_f32_e32 v41, v50, v50
	v_add_f32_e32 v40, v40, v41
	v_lshlrev_b32_e32 v41, 16, v76
	v_add_f32_e32 v32, v32, v80
	v_fmac_f32_e32 v41, v32, v36
	v_add_f32_e32 v36, v38, v86
	v_add_f32_e32 v32, 1.0, v37
	v_mul_f32_e32 v36, 0xbfb8aa3b, v36
	v_add_f32_e32 v37, v39, v87
	v_rcp_f32_e32 v32, v32
	v_exp_f32_e32 v36, v36
	v_mul_f32_e32 v37, 0xbfb8aa3b, v37
	v_exp_f32_e32 v37, v37
	v_and_b32_e32 v42, 0xffff0000, v76
	v_add_f32_e32 v33, v33, v81
	v_fmac_f32_e32 v42, v33, v32
	v_add_f32_e32 v32, 1.0, v36
	v_rcp_f32_e32 v32, v32
	v_add_f32_e32 v33, 1.0, v37
	v_rcp_f32_e32 v33, v33
	v_lshlrev_b32_e32 v43, 16, v77
	v_add_f32_e32 v34, v34, v82
	v_and_b32_e32 v44, 0xffff0000, v77
	v_fmac_f32_e32 v43, v34, v32
	v_add_f32_e32 v32, v35, v83
	v_fmac_f32_e32 v44, v32, v33
	v_mul_f32_e32 v32, v42, v42
	v_mul_f32_e32 v33, v44, v44
	v_fmac_f32_e32 v32, v41, v41
	v_fmac_f32_e32 v33, v43, v43
	v_add_f32_e32 v32, v32, v33
	v_add_f32_e32 v38, v40, v32
	v_mov_b32_e32 v39, v38
	s_nop 1
	v_permlane16_swap_b32_e32 v39, v38
	v_lshl_add_u64 v[32:33], s[16:17], 0, v[74:75]
	v_lshl_add_u64 v[36:37], v[152:153], 1, v[32:33]
	v_cvt_pk_bf16_f32 v34, v48, v49
	v_cvt_pk_bf16_f32 v35, v50, v51
	s_waitcnt lgkmcnt(0)
	v_add_f32_e32 v32, v38, v39
	v_mov_b32_e32 v33, v32
	s_nop 1
	v_permlane32_swap_b32_e32 v33, v32
	v_mov_b32_e32 v208, v34
	v_mov_b32_e32 v209, v35
	v_cvt_pk_bf16_f32 v34, v41, v42
	v_cvt_pk_bf16_f32 v35, v43, v44
	v_mov_b32_e32 v210, v34
	v_mov_b32_e32 v211, v35
	v_lshl_add_u64 v[212:213], v[36:37], 0, v[214:215]
	s_nop 0
	v_permlane16_swap_b32_e32 v208, v210
	v_permlane16_swap_b32_e32 v209, v211
	global_store_dwordx4 v[212:213], v[208:211], off
	s_and_saveexec_b64 s[2:3], vcc
	s_cbranch_execz .LBB0_1541
	s_waitcnt lgkmcnt(0)
	v_add_f32_e32 v34, v32, v33
	v_lshlrev_b64 v[32:33], 8, v[70:71]
	v_lshl_add_u64 v[32:33], s[18:19], 0, v[32:33]
	v_lshl_add_u64 v[32:33], s[0:1], 2, v[32:33]
	s_lshl_b32 s22, s44, 2
	v_lshl_add_u64 v[32:33], v[32:33], 0, s[22:23]
	global_store_dword v[32:33], v34, off
.LBB0_1541:
	s_or_b64 exec, exec, s[2:3]
	v_add_f32_e32 v28, v28, v100
	v_mul_f32_e32 v28, 0xbfb8aa3b, v28
	v_exp_f32_e32 v28, v28
	v_add_f32_e32 v29, v29, v101
	v_mul_f32_e32 v29, 0xbfb8aa3b, v29
	v_exp_f32_e32 v29, v29
	v_add_f32_e32 v28, 1.0, v28
	v_rcp_f32_e32 v28, v28
	v_lshlrev_b32_e32 v32, 16, v72
	v_add_f32_e32 v24, v24, v92
	s_waitcnt lgkmcnt(0)
	v_and_b32_e32 v33, 0xffff0000, v72
	v_fmac_f32_e32 v32, v24, v28
	v_add_f32_e32 v28, v30, v102
	v_add_f32_e32 v24, 1.0, v29
	v_mul_f32_e32 v28, 0xbfb8aa3b, v28
	v_add_f32_e32 v29, v31, v103
	v_rcp_f32_e32 v24, v24
	v_exp_f32_e32 v28, v28
	v_mul_f32_e32 v29, 0xbfb8aa3b, v29
	v_exp_f32_e32 v29, v29
	v_add_f32_e32 v25, v25, v93
	v_add_f32_e32 v20, v20, v84
	v_fmac_f32_e32 v33, v25, v24
	v_add_f32_e32 v24, 1.0, v28
	v_mul_f32_e32 v20, 0xbfb8aa3b, v20
	v_rcp_f32_e32 v24, v24
	v_add_f32_e32 v25, 1.0, v29
	v_exp_f32_e32 v20, v20
	v_rcp_f32_e32 v25, v25
	v_lshlrev_b32_e32 v34, 16, v73
	v_add_f32_e32 v26, v26, v94
	v_and_b32_e32 v35, 0xffff0000, v73
	v_fmac_f32_e32 v34, v26, v24
	v_add_f32_e32 v24, v27, v95
	v_add_f32_e32 v20, 1.0, v20
	v_add_f32_e32 v21, v21, v85
	v_fmac_f32_e32 v35, v24, v25
	v_rcp_f32_e32 v20, v20
	v_mul_f32_e32 v21, 0xbfb8aa3b, v21
	v_mul_f32_e32 v24, v33, v33
	v_mul_f32_e32 v25, v35, v35
	v_exp_f32_e32 v21, v21
	v_fmac_f32_e32 v24, v32, v32
	v_fmac_f32_e32 v25, v34, v34
	v_add_f32_e32 v24, v24, v25
	v_lshlrev_b32_e32 v25, 16, v68
	v_add_f32_e32 v16, v16, v80
	v_fmac_f32_e32 v25, v16, v20
	v_add_f32_e32 v20, v22, v86
	v_add_f32_e32 v16, 1.0, v21
	v_mul_f32_e32 v20, 0xbfb8aa3b, v20
	v_add_f32_e32 v21, v23, v87
	v_rcp_f32_e32 v16, v16
	v_exp_f32_e32 v20, v20
	v_mul_f32_e32 v21, 0xbfb8aa3b, v21
	v_exp_f32_e32 v21, v21
	v_and_b32_e32 v26, 0xffff0000, v68
	v_add_f32_e32 v17, v17, v81
	v_fmac_f32_e32 v26, v17, v16
	v_add_f32_e32 v16, 1.0, v20
	v_rcp_f32_e32 v16, v16
	v_add_f32_e32 v17, 1.0, v21
	v_rcp_f32_e32 v17, v17
	v_lshlrev_b32_e32 v27, 16, v69
	v_add_f32_e32 v18, v18, v82
	v_and_b32_e32 v28, 0xffff0000, v69
	v_fmac_f32_e32 v27, v18, v16
	v_add_f32_e32 v16, v19, v83
	v_fmac_f32_e32 v28, v16, v17
	v_mul_f32_e32 v16, v26, v26
	v_mul_f32_e32 v17, v28, v28
	v_fmac_f32_e32 v16, v25, v25
	v_fmac_f32_e32 v17, v27, v27
	v_add_f32_e32 v16, v16, v17
	v_add_f32_e32 v22, v24, v16
	v_mov_b32_e32 v23, v22
	s_nop 1
	v_permlane16_swap_b32_e32 v23, v22
	v_lshl_add_u64 v[16:17], s[16:17], 0, v[62:63]
	v_lshl_add_u64 v[20:21], v[152:153], 1, v[16:17]
	v_cvt_pk_bf16_f32 v18, v32, v33
	v_cvt_pk_bf16_f32 v19, v34, v35
	s_waitcnt lgkmcnt(0)
	v_add_f32_e32 v16, v22, v23
	v_mov_b32_e32 v17, v16
	s_nop 1
	v_permlane32_swap_b32_e32 v17, v16
	v_mov_b32_e32 v204, v18
	v_mov_b32_e32 v205, v19
	v_cvt_pk_bf16_f32 v18, v25, v26
	v_cvt_pk_bf16_f32 v19, v27, v28
	v_mov_b32_e32 v206, v18
	v_mov_b32_e32 v207, v19
	v_lshl_add_u64 v[212:213], v[20:21], 0, v[214:215]
	s_nop 0
	v_permlane16_swap_b32_e32 v204, v206
	v_permlane16_swap_b32_e32 v205, v207
	global_store_dwordx4 v[212:213], v[204:207], off
	s_and_saveexec_b64 s[2:3], vcc
	s_cbranch_execz .LBB0_1543
	s_waitcnt lgkmcnt(0)
	v_add_f32_e32 v18, v16, v17
	v_lshlrev_b64 v[16:17], 8, v[66:67]
	v_lshl_add_u64 v[16:17], s[18:19], 0, v[16:17]
	v_lshl_add_u64 v[16:17], s[0:1], 2, v[16:17]
	s_lshl_b32 s22, s44, 2
	v_lshl_add_u64 v[16:17], v[16:17], 0, s[22:23]
	global_store_dword v[16:17], v18, off
.LBB0_1543:
	s_or_b64 exec, exec, s[2:3]
	v_add_f32_e32 v12, v12, v100
	v_mul_f32_e32 v12, 0xbfb8aa3b, v12
	v_exp_f32_e32 v12, v12
	v_add_f32_e32 v13, v13, v101
	v_mul_f32_e32 v13, 0xbfb8aa3b, v13
	v_exp_f32_e32 v13, v13
	v_add_f32_e32 v12, 1.0, v12
	v_rcp_f32_e32 v12, v12
	v_lshlrev_b32_e32 v16, 16, v60
	v_add_f32_e32 v8, v8, v92
	s_waitcnt lgkmcnt(0)
	v_and_b32_e32 v17, 0xffff0000, v60
	v_fmac_f32_e32 v16, v8, v12
	v_add_f32_e32 v12, v14, v102
	v_add_f32_e32 v8, 1.0, v13
	v_mul_f32_e32 v12, 0xbfb8aa3b, v12
	v_add_f32_e32 v13, v15, v103
	v_rcp_f32_e32 v8, v8
	v_exp_f32_e32 v12, v12
	v_mul_f32_e32 v13, 0xbfb8aa3b, v13
	v_exp_f32_e32 v13, v13
	v_add_f32_e32 v9, v9, v93
	v_add_f32_e32 v4, v4, v84
	v_fmac_f32_e32 v17, v9, v8
	v_add_f32_e32 v8, 1.0, v12
	v_mul_f32_e32 v4, 0xbfb8aa3b, v4
	v_rcp_f32_e32 v8, v8
	v_add_f32_e32 v9, 1.0, v13
	v_exp_f32_e32 v4, v4
	v_rcp_f32_e32 v9, v9
	v_lshlrev_b32_e32 v18, 16, v61
	v_add_f32_e32 v10, v10, v94
	v_and_b32_e32 v19, 0xffff0000, v61
	v_fmac_f32_e32 v18, v10, v8
	v_add_f32_e32 v8, v11, v95
	v_add_f32_e32 v4, 1.0, v4
	v_add_f32_e32 v5, v5, v85
	v_fmac_f32_e32 v19, v8, v9
	v_rcp_f32_e32 v4, v4
	v_mul_f32_e32 v5, 0xbfb8aa3b, v5
	v_mul_f32_e32 v8, v17, v17
	v_mul_f32_e32 v9, v19, v19
	v_exp_f32_e32 v5, v5
	v_fmac_f32_e32 v8, v16, v16
	v_fmac_f32_e32 v9, v18, v18
	v_add_f32_e32 v8, v8, v9
	v_lshlrev_b32_e32 v9, 16, v58
	v_add_f32_e32 v0, v0, v80
	v_fmac_f32_e32 v9, v0, v4
	v_add_f32_e32 v4, v6, v86
	v_add_f32_e32 v0, 1.0, v5
	v_mul_f32_e32 v4, 0xbfb8aa3b, v4
	v_add_f32_e32 v5, v7, v87
	v_rcp_f32_e32 v0, v0
	v_exp_f32_e32 v4, v4
	v_mul_f32_e32 v5, 0xbfb8aa3b, v5
	v_exp_f32_e32 v5, v5
	v_and_b32_e32 v10, 0xffff0000, v58
	v_add_f32_e32 v1, v1, v81
	v_fmac_f32_e32 v10, v1, v0
	v_add_f32_e32 v0, 1.0, v4
	v_rcp_f32_e32 v0, v0
	v_add_f32_e32 v1, 1.0, v5
	v_rcp_f32_e32 v1, v1
	v_lshlrev_b32_e32 v11, 16, v59
	v_add_f32_e32 v2, v2, v82
	v_and_b32_e32 v12, 0xffff0000, v59
	v_fmac_f32_e32 v11, v2, v0
	v_add_f32_e32 v0, v3, v83
	v_fmac_f32_e32 v12, v0, v1
	v_mul_f32_e32 v0, v10, v10
	v_mul_f32_e32 v1, v12, v12
	v_fmac_f32_e32 v0, v9, v9
	v_fmac_f32_e32 v1, v11, v11
	v_add_f32_e32 v0, v0, v1
	v_add_f32_e32 v6, v8, v0
	v_mov_b32_e32 v7, v6
	s_nop 1
	v_permlane16_swap_b32_e32 v7, v6
	v_lshl_add_u64 v[0:1], s[16:17], 0, v[56:57]
	v_lshl_add_u64 v[4:5], v[152:153], 1, v[0:1]
	v_cvt_pk_bf16_f32 v2, v16, v17
	v_cvt_pk_bf16_f32 v3, v18, v19
	s_waitcnt lgkmcnt(0)
	v_add_f32_e32 v0, v6, v7
	v_mov_b32_e32 v1, v0
	s_nop 1
	v_permlane32_swap_b32_e32 v1, v0
	v_mov_b32_e32 v208, v2
	v_mov_b32_e32 v209, v3
	v_cvt_pk_bf16_f32 v2, v9, v10
	v_cvt_pk_bf16_f32 v3, v11, v12
	v_mov_b32_e32 v210, v2
	v_mov_b32_e32 v211, v3
	v_lshl_add_u64 v[212:213], v[4:5], 0, v[214:215]
	s_nop 0
	v_permlane16_swap_b32_e32 v208, v210
	v_permlane16_swap_b32_e32 v209, v211
	global_store_dwordx4 v[212:213], v[208:211], off
	s_and_saveexec_b64 s[2:3], vcc
	s_cbranch_execz .LBB0_1545
	s_waitcnt lgkmcnt(0)
	v_add_f32_e32 v2, v0, v1
	v_lshlrev_b64 v[0:1], 8, v[64:65]
	v_lshl_add_u64 v[0:1], s[18:19], 0, v[0:1]
	v_lshl_add_u64 v[0:1], s[0:1], 2, v[0:1]
	s_lshl_b32 s22, s44, 2
	v_lshl_add_u64 v[0:1], v[0:1], 0, s[22:23]
	global_store_dword v[0:1], v2, off

.LBB0_1739:
.LBB0_1740:
	s_add_i32 s0, 0, 0x23f94
	s_waitcnt vmcnt(0)
	v_mov_b32_e32 v0, s0
	v_mbcnt_lo_u32_b32 v58, -1, 0
	v_mbcnt_hi_u32_b32 v58, -1, v58
	ds_read_b32 v0, v0
	v_lshlrev_b32_e32 v71, 4, v58
	v_and_b32_e32 v59, 15, v58
	s_mov_b32 s1, 0
	v_ashrrev_i32_e32 v70, 4, v58
	s_waitcnt lgkmcnt(0)
	v_readfirstlane_b32 s0, v0
	s_and_b32 s4, s0, 7
	s_mul_i32 s5, s4, 0x1400000
	s_add_u32 s5, s94, s5
	s_addc_u32 s6, s95, 0
	s_lshl_b32 s4, s4, 22
	s_sub_u32 s4, 0, s4
	s_subb_u32 s7, 0, 0
	s_add_u32 s4, s5, s4
	s_addc_u32 s5, s6, s7
	s_lshl_b32 s8, s88, 10
	v_add_u32_e32 v0, s8, v71
	v_ashrrev_i32_e32 v1, 31, v0
	v_lshrrev_b32_e32 v1, 22, v1
	v_add_u32_e32 v1, v0, v1
	v_ashrrev_i32_e32 v1, 10, v1
	v_mul_i32_i24_e32 v2, 0x400, v1
	v_sub_u32_e32 v2, v0, v2
	v_lshrrev_b32_e32 v3, 4, v2
	v_bitop3_b32 v2, v3, v2, 32 bitop3:0x6c
	v_ashrrev_i32_e32 v4, 31, v2
	v_lshrrev_b32_e32 v4, 26, v4
	v_lshlrev_b32_e32 v3, 3, v1
	v_add_u32_e32 v4, v2, v4
	v_and_b32_e32 v3, -16, v3
	v_ashrrev_i32_e32 v5, 6, v4
	v_add_u32_e32 v104, v5, v3
	v_and_b32_e32 v3, 0xc0, v4
	v_lshlrev_b32_e32 v1, 5, v1
	v_sub_u32_e32 v2, v2, v3
	v_mov_b32_e32 v3, 1
	v_and_b32_e32 v1, 32, v1
	v_ashrrev_i16_sdwa v2, v3, sext(v2) dst_sel:DWORD dst_unused:UNUSED_PAD src0_sel:DWORD src1_sel:BYTE_0
	v_add_u32_sdwa v1, v1, sext(v2) dst_sel:DWORD dst_unused:UNUSED_PAD src0_sel:DWORD src1_sel:WORD_0
	v_lshlrev_b32_e32 v2, 10, v104
	v_add_u32_e32 v0, 0x2000, v0
	v_lshl_add_u32 v62, v1, 1, v2
	v_ashrrev_i32_e32 v1, 31, v0
	v_lshrrev_b32_e32 v1, 22, v1
	v_add_u32_e32 v1, v0, v1
	v_ashrrev_i32_e32 v1, 10, v1
	v_mul_i32_i24_e32 v2, 0x400, v1
	v_sub_u32_e32 v0, v0, v2
	v_lshrrev_b32_e32 v2, 4, v0
	s_lshl_b32 s6, s0, 3
	v_bitop3_b32 v0, v2, v0, 32 bitop3:0x6c
	s_and_b32 s6, s6, 56
	s_ashr_i32 s7, s0, 5
	v_ashrrev_i32_e32 v4, 31, v0
	s_add_i32 s9, s6, s7
	v_lshrrev_b32_e32 v4, 26, v4
	s_ashr_i32 s12, s9, 5
	v_lshlrev_b32_e32 v2, 3, v1
	v_add_u32_e32 v4, v0, v4
	s_bfe_u32 s0, s0, 0x20003
	s_lshl_b32 s6, s12, 2
	v_and_b32_e32 v2, -16, v2
	v_ashrrev_i32_e32 v5, 6, v4
	s_or_b32 s6, s6, s0
	v_add_u32_e32 v108, v5, v2
	v_and_b32_e32 v2, 0xffc0, v4
	s_ashr_i32 s7, s6, 31
	v_sub_u32_e32 v0, v0, v2
	s_lshl_b64 s[6:7], s[6:7], 18
	v_lshrrev_b16_e32 v2, 7, v0
	s_add_u32 s10, s94, s6
	v_and_b32_e32 v2, 1, v2
	s_addc_u32 s11, s95, s7
	v_lshlrev_b32_e32 v1, 5, v1
	v_add_u16_e32 v0, v0, v2
	s_add_u32 s6, s10, 0x11600000
	v_and_b32_e32 v1, 32, v1
	v_ashrrev_i16_sdwa v0, v3, sext(v0) dst_sel:DWORD dst_unused:UNUSED_PAD src0_sel:DWORD src1_sel:BYTE_0
	s_addc_u32 s7, s11, 0
	s_lshl_b32 s9, s9, 7
	v_add_u32_sdwa v0, v1, sext(v0) dst_sel:DWORD dst_unused:UNUSED_PAD src0_sel:DWORD src1_sel:WORD_0
	v_lshlrev_b32_e32 v1, 10, v108
	s_lshl_b32 s12, s12, 12
	s_and_b32 s9, s9, 0xf80
	v_lshl_add_u32 v64, v0, 1, v1
	v_lshl_or_b32 v1, s88, 4, v59
	s_or_b32 s9, s12, s9
	v_add_u32_e32 v2, s9, v1
	v_ashrrev_i32_e32 v3, 31, v2
	v_lshlrev_b64 v[2:3], 12, v[2:3]
	s_lshl_b32 s0, s0, 10
	v_lshl_add_u64 v[2:3], s[4:5], 0, v[2:3]
	v_lshlrev_b32_e32 v0, 3, v70
	v_lshl_add_u64 v[2:3], v[2:3], 0, s[0:1]
	s_mov_b64 s[0:1], 0x13000000
	v_ashrrev_i32_e32 v1, 31, v0
	v_lshl_add_u64 v[60:61], v[2:3], 0, s[0:1]
	v_lshl_add_u64 v[0:1], v[0:1], 1, v[60:61]
	s_mov_b64 s[0:1], 0xc00000
	v_lshl_add_u64 v[2:3], v[0:1], 0, s[0:1]
	s_mov_b32 s0, 0xc00000
	v_add_co_u32_e32 v0, vcc, s0, v0
	s_add_i32 s22, s8, 0
	s_nop 0
	v_addc_co_u32_e32 v1, vcc, 0, v1, vcc
	v_mov_b32_e32 v63, 0
	s_mov_b32 m0, s22
	s_add_i32 s21, s22, 0x2000
	global_load_dwordx4 v[72:75], v[2:3], off offset:64
	global_load_dwordx4 v[52:55], v[2:3], off offset:128
	global_load_dwordx4 v[48:51], v[2:3], off offset:192
	global_load_dwordx4 v[44:47], v[2:3], off offset:256
	global_load_dwordx4 v[40:43], v[2:3], off offset:320
	global_load_dwordx4 v[36:39], v[2:3], off offset:384
	global_load_dwordx4 v[32:35], v[2:3], off offset:448
	global_load_dwordx4 v[28:31], v[2:3], off offset:512
	global_load_dwordx4 v[24:27], v[2:3], off offset:576
	global_load_dwordx4 v[20:23], v[2:3], off offset:640
	global_load_dwordx4 v[16:19], v[2:3], off offset:704
	global_load_dwordx4 v[12:15], v[2:3], off offset:768
	global_load_dwordx4 v[8:11], v[2:3], off offset:832
	global_load_dwordx4 v[4:7], v[2:3], off offset:896
	global_load_dwordx4 v[76:79], v[0:1], off
	s_nop 0
	global_load_dwordx4 v[0:3], v[2:3], off offset:960
	v_mov_b32_e32 v65, v63
	global_load_lds_dwordx4 v62, s[6:7]
	v_mov_b32_e32 v240, v62
	s_mov_b32 m0, s21
	v_lshl_add_u64 v[66:67], s[6:7], 0, v[62:63]
	v_lshl_add_u64 v[68:69], s[6:7], 0, v[64:65]
	global_load_lds_dwordx4 v64, s[6:7]
	s_add_i32 s20, s22, 0x4000
	s_mov_b64 s[6:7], 0x80
	s_add_i32 s23, s22, 0x6000
	v_lshl_add_u64 v[56:57], v[66:67], 0, s[6:7]
	s_mov_b32 m0, s20
	s_add_u32 s0, s10, 0x11620000
	global_load_lds_dwordx4 v[56:57], off
	v_lshl_add_u64 v[56:57], v[68:69], 0, s[6:7]
	s_mov_b32 m0, s23
	s_addc_u32 s1, s11, 0
	s_add_i32 s24, s22, 0x8000
	global_load_lds_dwordx4 v[56:57], off
	s_mov_b32 m0, s24
	s_add_i32 s25, s22, 0xa000
	global_load_lds_dwordx4 v62, s[0:1]
	s_mov_b32 m0, s25
	s_mov_b64 s[4:5], 0x180
	global_load_lds_dwordx4 v64, s[0:1]
	s_add_u32 s0, s10, 0x11620080
	s_addc_u32 s1, s11, 0
	s_add_i32 s26, s22, 0xc000
	s_mov_b32 m0, s26
	s_add_i32 s27, s22, 0xe000
	global_load_lds_dwordx4 v62, s[0:1]
	s_mov_b32 m0, s27
	s_add_u32 s8, s10, 0x11e00000
	global_load_lds_dwordx4 v64, s[0:1]
	s_addc_u32 s9, s11, 0
	s_add_i32 s19, s22, 0x10000
	s_mov_b64 s[0:1], 0x100
	v_lshl_add_u64 v[56:57], v[66:67], 0, s[0:1]
	s_mov_b32 m0, s19
	s_add_i32 s13, s22, 0x12000
	s_waitcnt vmcnt(0)
	s_waitcnt vmcnt(0) lgkmcnt(0)
	s_barrier
	global_load_lds_dwordx4 v[56:57], off
	v_lshl_add_u64 v[56:57], v[68:69], 0, s[0:1]
	s_mov_b32 m0, s13
	s_add_i32 s12, s22, 0x14000
	s_add_i32 s14, s22, 0x16000
	global_load_lds_dwordx4 v[56:57], off
	v_lshl_add_u64 v[56:57], v[66:67], 0, s[4:5]
	s_mov_b32 m0, s12
	s_add_u32 s28, s10, 0x11620100
	global_load_lds_dwordx4 v[56:57], off
	v_lshl_add_u64 v[56:57], v[68:69], 0, s[4:5]
	s_mov_b32 m0, s14
	s_addc_u32 s29, s11, 0
	s_add_i32 s15, s22, 0x18000
	global_load_lds_dwordx4 v[56:57], off
	s_mov_b32 m0, s15
	s_add_i32 s16, s22, 0x1a000
	global_load_lds_dwordx4 v62, s[28:29]
	s_mov_b32 m0, s16
	v_and_b32_e32 v57, 48, v58
	global_load_lds_dwordx4 v64, s[28:29]
	s_add_u32 s28, s10, 0x11620180
	s_addc_u32 s29, s11, 0
	s_add_i32 s17, s22, 0x1c000
	s_mov_b32 m0, s17
	s_add_i32 s18, s22, 0x1e000
	global_load_lds_dwordx4 v62, s[28:29]
	s_mov_b32 m0, s18
	v_lshlrev_b32_e32 v58, 2, v58
	global_load_lds_dwordx4 v64, s[28:29]
	v_lshlrev_b32_e32 v56, 6, v59
	v_and_b32_e32 v58, 32, v58
	v_bitop3_b32 v56, v56, v58, v57 bitop3:0x36
	v_and_b32_e32 v57, 0xfffffc00, v71
	v_add3_u32 v65, 0, v56, v57
	v_mov_b32_e32 v71, v65
	ds_read_b128 v[56:59], v71
	ds_read_b128 v[80:83], v71 offset:2048
	s_waitcnt lgkmcnt(0)
	v_mfma_f32_16x16x32_bf16 v[84:87], v[56:59], v[76:79], 0
	ds_read_b128 v[56:59], v71 offset:4096
	ds_read_b128 v[88:91], v71 offset:6144
	ds_read_b128 v[96:99], v71 offset:8192
	ds_read_b128 v[100:103], v71 offset:10240
	s_waitcnt lgkmcnt(0)
	v_mfma_f32_16x16x32_bf16 v[92:95], v[56:59], v[76:79], 0
	v_lshlrev_b32_e32 v56, 9, v104
	ds_read_b128 v[104:107], v71 offset:12288
	v_lshlrev_b32_e32 v57, 9, v108
	ds_read_b128 v[108:111], v71 offset:14336
	ds_read_b128 v[112:115], v71 offset:32768
	ds_read_b128 v[116:119], v71 offset:34816
	ds_read_b128 v[120:123], v71 offset:36864
	ds_read_b128 v[124:127], v71 offset:38912
	ds_read_b128 v[128:131], v71 offset:40960
	ds_read_b128 v[132:135], v71 offset:43008
	ds_read_b128 v[136:139], v71 offset:45056
	ds_read_b128 v[140:143], v71 offset:47104
	v_mfma_f32_16x16x32_bf16 v[80:83], v[80:83], v[76:79], 0
	v_sub_u32_e32 v56, v62, v56
	v_mov_b32_e32 v241, v56
	v_sub_u32_e32 v58, v64, v57
	v_mfma_f32_16x16x32_bf16 v[88:91], v[88:91], v[76:79], 0
	v_mfma_f32_16x16x32_bf16 v[96:99], v[96:99], v[76:79], 0
	v_mfma_f32_16x16x32_bf16 v[100:103], v[100:103], v[76:79], 0
	s_waitcnt lgkmcnt(0)
	v_mfma_f32_16x16x32_bf16 v[104:107], v[104:107], v[76:79], 0
	v_mfma_f32_16x16x32_bf16 v[108:111], v[108:111], v[76:79], 0
	ds_read_b128 v[144:147], v71 offset:15360
	ds_read_b128 v[148:151], v71 offset:13312
	ds_read_b128 v[152:155], v71 offset:11264
	ds_read_b128 v[156:159], v71 offset:9216
	ds_read_b128 v[160:163], v71 offset:7168
	ds_read_b128 v[164:167], v71 offset:5120
	ds_read_b128 v[168:171], v71 offset:3072
	ds_read_b128 v[172:175], v71 offset:1024
	v_mfma_f32_16x16x32_bf16 v[112:115], v[112:115], v[76:79], 0
	v_mfma_f32_16x16x32_bf16 v[116:119], v[116:119], v[76:79], 0
	v_mfma_f32_16x16x32_bf16 v[120:123], v[120:123], v[76:79], 0
	v_mfma_f32_16x16x32_bf16 v[124:127], v[124:127], v[76:79], 0
	v_mfma_f32_16x16x32_bf16 v[128:131], v[128:131], v[76:79], 0
	v_mfma_f32_16x16x32_bf16 v[132:135], v[132:135], v[76:79], 0
	v_mfma_f32_16x16x32_bf16 v[136:139], v[136:139], v[76:79], 0
	v_mfma_f32_16x16x32_bf16 v[76:79], v[140:143], v[76:79], 0
	s_waitcnt lgkmcnt(0)
	v_mfma_f32_16x16x32_bf16 v[84:87], v[172:175], v[72:75], v[84:87]
	v_mfma_f32_16x16x32_bf16 v[80:83], v[168:171], v[72:75], v[80:83]
	v_mfma_f32_16x16x32_bf16 v[92:95], v[164:167], v[72:75], v[92:95]
	v_mfma_f32_16x16x32_bf16 v[88:91], v[160:163], v[72:75], v[88:91]
	v_mfma_f32_16x16x32_bf16 v[96:99], v[156:159], v[72:75], v[96:99]
	v_mfma_f32_16x16x32_bf16 v[100:103], v[152:155], v[72:75], v[100:103]
	ds_read_b128 v[140:143], v71 offset:33792
	ds_read_b128 v[152:155], v71 offset:35840
	ds_read_b128 v[156:159], v71 offset:37888
	ds_read_b128 v[160:163], v71 offset:39936
	v_mfma_f32_16x16x32_bf16 v[104:107], v[148:151], v[72:75], v[104:107]
	ds_read_b128 v[148:151], v71 offset:41984
	ds_read_b128 v[164:167], v71 offset:44032
	ds_read_b128 v[168:171], v71 offset:46080
	ds_read_b128 v[172:175], v71 offset:48128
	v_mfma_f32_16x16x32_bf16 v[108:111], v[144:147], v[72:75], v[108:111]
	s_waitcnt lgkmcnt(0)
	v_mfma_f32_16x16x32_bf16 v[112:115], v[140:143], v[72:75], v[112:115]
	v_mfma_f32_16x16x32_bf16 v[116:119], v[152:155], v[72:75], v[116:119]
	v_mfma_f32_16x16x32_bf16 v[120:123], v[156:159], v[72:75], v[120:123]
	v_mfma_f32_16x16x32_bf16 v[124:127], v[160:163], v[72:75], v[124:127]
	v_mfma_f32_16x16x32_bf16 v[128:131], v[148:151], v[72:75], v[128:131]
	ds_read_b128 v[140:143], v71 offset:30720
	ds_read_b128 v[144:147], v71 offset:28672
	ds_read_b128 v[148:151], v71 offset:26624
	ds_read_b128 v[152:155], v71 offset:24576
	v_mfma_f32_16x16x32_bf16 v[132:135], v[164:167], v[72:75], v[132:135]
	v_mfma_f32_16x16x32_bf16 v[136:139], v[168:171], v[72:75], v[136:139]
	ds_read_b128 v[156:159], v71 offset:22528
	ds_read_b128 v[160:163], v71 offset:20480
	ds_read_b128 v[164:167], v71 offset:18432
	ds_read_b128 v[168:171], v71 offset:16384
	v_mfma_f32_16x16x32_bf16 v[72:75], v[172:175], v[72:75], v[76:79]
	s_waitcnt lgkmcnt(0)
	v_mfma_f32_16x16x32_bf16 v[76:79], v[168:171], v[52:55], v[84:87]
	v_mfma_f32_16x16x32_bf16 v[80:83], v[164:167], v[52:55], v[80:83]
	v_mfma_f32_16x16x32_bf16 v[84:87], v[160:163], v[52:55], v[92:95]
	v_mfma_f32_16x16x32_bf16 v[88:91], v[156:159], v[52:55], v[88:91]
	v_mfma_f32_16x16x32_bf16 v[92:95], v[152:155], v[52:55], v[96:99]
	v_mfma_f32_16x16x32_bf16 v[96:99], v[148:151], v[52:55], v[100:103]
	s_nop 2
	ds_read_b128 v[100:103], v71 offset:49152
	ds_read_b128 v[148:151], v71 offset:51200
	ds_read_b128 v[152:155], v71 offset:53248
	ds_read_b128 v[156:159], v71 offset:55296
	v_mfma_f32_16x16x32_bf16 v[104:107], v[144:147], v[52:55], v[104:107]
	ds_read_b128 v[144:147], v71 offset:57344
	ds_read_b128 v[160:163], v71 offset:59392
	ds_read_b128 v[164:167], v71 offset:61440
	ds_read_b128 v[168:171], v71 offset:63488
	v_mfma_f32_16x16x32_bf16 v[108:111], v[140:143], v[52:55], v[108:111]
	s_waitcnt lgkmcnt(0)
	v_mfma_f32_16x16x32_bf16 v[100:103], v[100:103], v[52:55], v[112:115]
	v_mfma_f32_16x16x32_bf16 v[112:115], v[148:151], v[52:55], v[116:119]
	v_mfma_f32_16x16x32_bf16 v[116:119], v[152:155], v[52:55], v[120:123]
	v_mfma_f32_16x16x32_bf16 v[120:123], v[156:159], v[52:55], v[124:127]
	v_mfma_f32_16x16x32_bf16 v[124:127], v[144:147], v[52:55], v[128:131]
	v_mfma_f32_16x16x32_bf16 v[128:131], v[160:163], v[52:55], v[132:135]
	s_nop 2
	ds_read_b128 v[132:135], v71 offset:31744
	ds_read_b128 v[140:143], v71 offset:29696
	ds_read_b128 v[144:147], v71 offset:27648
	ds_read_b128 v[148:151], v71 offset:25600
	v_mfma_f32_16x16x32_bf16 v[136:139], v[164:167], v[52:55], v[136:139]
	ds_read_b128 v[152:155], v71 offset:23552
	ds_read_b128 v[156:159], v71 offset:21504
	ds_read_b128 v[160:163], v71 offset:19456
	ds_read_b128 v[164:167], v71 offset:17408
	v_mfma_f32_16x16x32_bf16 v[52:55], v[168:171], v[52:55], v[72:75]
	s_waitcnt lgkmcnt(0)
	v_mfma_f32_16x16x32_bf16 v[72:75], v[164:167], v[48:51], v[76:79]
	v_mfma_f32_16x16x32_bf16 v[76:79], v[160:163], v[48:51], v[80:83]
	v_mfma_f32_16x16x32_bf16 v[80:83], v[156:159], v[48:51], v[84:87]
	v_mfma_f32_16x16x32_bf16 v[84:87], v[152:155], v[48:51], v[88:91]
	v_mfma_f32_16x16x32_bf16 v[88:91], v[148:151], v[48:51], v[92:95]
	v_mfma_f32_16x16x32_bf16 v[92:95], v[144:147], v[48:51], v[96:99]
	s_nop 2
	ds_read_b128 v[96:99], v71 offset:50176
	ds_read_b128 v[144:147], v71 offset:52224
	ds_read_b128 v[148:151], v71 offset:54272
	ds_read_b128 v[152:155], v71 offset:56320
	v_mfma_f32_16x16x32_bf16 v[104:107], v[140:143], v[48:51], v[104:107]
	ds_read_b128 v[140:143], v71 offset:58368
	ds_read_b128 v[156:159], v71 offset:60416
	ds_read_b128 v[160:163], v71 offset:62464
	ds_read_b128 v[164:167], v71 offset:64512
	v_mfma_f32_16x16x32_bf16 v[108:111], v[132:135], v[48:51], v[108:111]
	s_waitcnt lgkmcnt(0)
	v_mfma_f32_16x16x32_bf16 v[96:99], v[96:99], v[48:51], v[100:103]
	v_mfma_f32_16x16x32_bf16 v[100:103], v[144:147], v[48:51], v[112:115]
	v_mfma_f32_16x16x32_bf16 v[112:115], v[148:151], v[48:51], v[116:119]
	v_mfma_f32_16x16x32_bf16 v[116:119], v[152:155], v[48:51], v[120:123]
	v_mfma_f32_16x16x32_bf16 v[120:123], v[140:143], v[48:51], v[124:127]
	v_mfma_f32_16x16x32_bf16 v[124:127], v[156:159], v[48:51], v[128:131]
	v_mfma_f32_16x16x32_bf16 v[128:131], v[160:163], v[48:51], v[136:139]
	v_mfma_f32_16x16x32_bf16 v[50:53], v[164:167], v[48:51], v[52:55]
	s_waitcnt vmcnt(0)
	s_waitcnt vmcnt(0)
	s_barrier
	v_add_u32_e32 v48, 0x10000, v65
	v_mov_b32_e32 v49, v48
	ds_read_b128 v[132:135], v49
	ds_read_b128 v[136:139], v49 offset:2048
	s_waitcnt lgkmcnt(0)
	v_mfma_f32_16x16x32_bf16 v[72:75], v[132:135], v[44:47], v[72:75]
	ds_read_b128 v[132:135], v49 offset:4096
	v_mfma_f32_16x16x32_bf16 v[76:79], v[136:139], v[44:47], v[76:79]
	ds_read_b128 v[136:139], v49 offset:6144
	s_waitcnt lgkmcnt(0)
	v_mfma_f32_16x16x32_bf16 v[80:83], v[132:135], v[44:47], v[80:83]
	ds_read_b128 v[132:135], v49 offset:8192
	v_mfma_f32_16x16x32_bf16 v[84:87], v[136:139], v[44:47], v[84:87]
	ds_read_b128 v[136:139], v49 offset:10240
	s_waitcnt lgkmcnt(0)
	v_mfma_f32_16x16x32_bf16 v[88:91], v[132:135], v[44:47], v[88:91]
	ds_read_b128 v[132:135], v49 offset:12288
	ds_read_b128 v[140:143], v49 offset:14336
	v_mfma_f32_16x16x32_bf16 v[92:95], v[136:139], v[44:47], v[92:95]
	ds_read_b128 v[136:139], v49 offset:32768
	ds_read_b128 v[144:147], v49 offset:34816
	ds_read_b128 v[148:151], v49 offset:36864
	ds_read_b128 v[152:155], v49 offset:38912
	s_waitcnt lgkmcnt(0)
	v_mfma_f32_16x16x32_bf16 v[104:107], v[132:135], v[44:47], v[104:107]
	ds_read_b128 v[132:135], v49 offset:40960
	ds_read_b128 v[156:159], v49 offset:43008
	ds_read_b128 v[160:163], v49 offset:45056
	ds_read_b128 v[164:167], v49 offset:47104
	v_mfma_f32_16x16x32_bf16 v[108:111], v[140:143], v[44:47], v[108:111]
	s_add_u32 s100, s10, 0x11600200
	s_addc_u32 s101, s11, 0
	s_mov_b32 m0, s22
	s_nop 0
	global_load_lds_dwordx4 v240, s[100:101]
	v_mfma_f32_16x16x32_bf16 v[96:99], v[136:139], v[44:47], v[96:99]
	v_mfma_f32_16x16x32_bf16 v[100:103], v[144:147], v[44:47], v[100:103]
	v_mfma_f32_16x16x32_bf16 v[112:115], v[148:151], v[44:47], v[112:115]
	v_mfma_f32_16x16x32_bf16 v[116:119], v[152:155], v[44:47], v[116:119]
	s_waitcnt lgkmcnt(0)
	v_mfma_f32_16x16x32_bf16 v[120:123], v[132:135], v[44:47], v[120:123]
	ds_read_b128 v[132:135], v49 offset:15360
	ds_read_b128 v[136:139], v49 offset:13312
	ds_read_b128 v[140:143], v49 offset:11264
	ds_read_b128 v[144:147], v49 offset:9216
	v_mfma_f32_16x16x32_bf16 v[124:127], v[156:159], v[44:47], v[124:127]
	v_mfma_f32_16x16x32_bf16 v[128:131], v[160:163], v[44:47], v[128:131]
	ds_read_b128 v[148:151], v49 offset:7168
	ds_read_b128 v[152:155], v49 offset:5120
	ds_read_b128 v[156:159], v49 offset:3072
	ds_read_b128 v[160:163], v49 offset:1024
	v_mfma_f32_16x16x32_bf16 v[44:47], v[164:167], v[44:47], v[50:53]
	s_add_u32 s100, s10, 0x11610200
	s_addc_u32 s101, s11, 0
	s_mov_b32 m0, s21
	s_nop 0
	global_load_lds_dwordx4 v240, s[100:101]
	s_waitcnt lgkmcnt(0)
	v_mfma_f32_16x16x32_bf16 v[50:53], v[160:163], v[40:43], v[72:75]
	v_mfma_f32_16x16x32_bf16 v[72:75], v[156:159], v[40:43], v[76:79]
	v_mfma_f32_16x16x32_bf16 v[76:79], v[152:155], v[40:43], v[80:83]
	v_mfma_f32_16x16x32_bf16 v[80:83], v[148:151], v[40:43], v[84:87]
	v_mfma_f32_16x16x32_bf16 v[84:87], v[144:147], v[40:43], v[88:91]
	v_mfma_f32_16x16x32_bf16 v[88:91], v[140:143], v[40:43], v[92:95]
	s_nop 2
	ds_read_b128 v[92:95], v49 offset:33792
	ds_read_b128 v[140:143], v49 offset:35840
	ds_read_b128 v[144:147], v49 offset:37888
	ds_read_b128 v[148:151], v49 offset:39936
	v_mfma_f32_16x16x32_bf16 v[104:107], v[136:139], v[40:43], v[104:107]
	ds_read_b128 v[136:139], v49 offset:41984
	ds_read_b128 v[152:155], v49 offset:44032
	ds_read_b128 v[156:159], v49 offset:46080
	ds_read_b128 v[160:163], v49 offset:48128
	v_mfma_f32_16x16x32_bf16 v[108:111], v[132:135], v[40:43], v[108:111]
	s_add_u32 s100, s10, 0x11600280
	s_addc_u32 s101, s11, 0
	s_mov_b32 m0, s20
	s_nop 0
	global_load_lds_dwordx4 v240, s[100:101]
	s_waitcnt lgkmcnt(0)
	v_mfma_f32_16x16x32_bf16 v[92:95], v[92:95], v[40:43], v[96:99]
	v_mfma_f32_16x16x32_bf16 v[96:99], v[140:143], v[40:43], v[100:103]
	v_mfma_f32_16x16x32_bf16 v[100:103], v[144:147], v[40:43], v[112:115]
	v_mfma_f32_16x16x32_bf16 v[112:115], v[148:151], v[40:43], v[116:119]
	v_mfma_f32_16x16x32_bf16 v[116:119], v[136:139], v[40:43], v[120:123]
	v_mfma_f32_16x16x32_bf16 v[120:123], v[152:155], v[40:43], v[124:127]
	s_nop 2
	ds_read_b128 v[124:127], v49 offset:30720
	ds_read_b128 v[132:135], v49 offset:28672
	ds_read_b128 v[136:139], v49 offset:26624
	ds_read_b128 v[140:143], v49 offset:24576
	v_mfma_f32_16x16x32_bf16 v[128:131], v[156:159], v[40:43], v[128:131]
	ds_read_b128 v[144:147], v49 offset:22528
	ds_read_b128 v[148:151], v49 offset:20480
	ds_read_b128 v[152:155], v49 offset:18432
	ds_read_b128 v[156:159], v49 offset:16384
	v_mfma_f32_16x16x32_bf16 v[40:43], v[160:163], v[40:43], v[44:47]
	s_add_u32 s100, s10, 0x11610280
	s_addc_u32 s101, s11, 0
	s_mov_b32 m0, s23
	s_nop 0
	global_load_lds_dwordx4 v240, s[100:101]
	s_waitcnt lgkmcnt(0)
	v_mfma_f32_16x16x32_bf16 v[44:47], v[156:159], v[36:39], v[50:53]
	v_mfma_f32_16x16x32_bf16 v[50:53], v[152:155], v[36:39], v[72:75]
	v_mfma_f32_16x16x32_bf16 v[72:75], v[148:151], v[36:39], v[76:79]
	v_mfma_f32_16x16x32_bf16 v[76:79], v[144:147], v[36:39], v[80:83]
	v_mfma_f32_16x16x32_bf16 v[80:83], v[140:143], v[36:39], v[84:87]
	v_mfma_f32_16x16x32_bf16 v[84:87], v[136:139], v[36:39], v[88:91]
	s_nop 2
	ds_read_b128 v[88:91], v49 offset:49152
	ds_read_b128 v[136:139], v49 offset:51200
	ds_read_b128 v[140:143], v49 offset:53248
	ds_read_b128 v[144:147], v49 offset:55296
	v_mfma_f32_16x16x32_bf16 v[104:107], v[132:135], v[36:39], v[104:107]
	ds_read_b128 v[132:135], v49 offset:57344
	ds_read_b128 v[148:151], v49 offset:59392
	ds_read_b128 v[152:155], v49 offset:61440
	ds_read_b128 v[156:159], v49 offset:63488
	v_mfma_f32_16x16x32_bf16 v[108:111], v[124:127], v[36:39], v[108:111]
	s_add_u32 s100, s10, 0x11620200
	s_addc_u32 s101, s11, 0
	s_mov_b32 m0, s24
	s_nop 0
	global_load_lds_dwordx4 v240, s[100:101]
	s_waitcnt lgkmcnt(0)
	v_mfma_f32_16x16x32_bf16 v[88:91], v[88:91], v[36:39], v[92:95]
	v_mfma_f32_16x16x32_bf16 v[92:95], v[136:139], v[36:39], v[96:99]
	v_mfma_f32_16x16x32_bf16 v[96:99], v[140:143], v[36:39], v[100:103]
	v_mfma_f32_16x16x32_bf16 v[100:103], v[144:147], v[36:39], v[112:115]
	v_mfma_f32_16x16x32_bf16 v[112:115], v[132:135], v[36:39], v[116:119]
	v_mfma_f32_16x16x32_bf16 v[116:119], v[148:151], v[36:39], v[120:123]
	s_nop 2
	ds_read_b128 v[120:123], v49 offset:31744
	ds_read_b128 v[124:127], v49 offset:29696
	ds_read_b128 v[132:135], v49 offset:27648
	ds_read_b128 v[136:139], v49 offset:25600
	v_mfma_f32_16x16x32_bf16 v[128:131], v[152:155], v[36:39], v[128:131]
	ds_read_b128 v[140:143], v49 offset:23552
	ds_read_b128 v[144:147], v49 offset:21504
	ds_read_b128 v[148:151], v49 offset:19456
	ds_read_b128 v[152:155], v49 offset:17408
	v_mfma_f32_16x16x32_bf16 v[36:39], v[156:159], v[36:39], v[40:43]
	s_add_u32 s100, s10, 0x11630200
	s_addc_u32 s101, s11, 0
	s_mov_b32 m0, s25
	s_nop 0
	global_load_lds_dwordx4 v240, s[100:101]
	s_waitcnt lgkmcnt(0)
	v_mfma_f32_16x16x32_bf16 v[40:43], v[152:155], v[32:35], v[44:47]
	v_mfma_f32_16x16x32_bf16 v[44:47], v[148:151], v[32:35], v[50:53]
	v_mfma_f32_16x16x32_bf16 v[50:53], v[144:147], v[32:35], v[72:75]
	v_mfma_f32_16x16x32_bf16 v[72:75], v[140:143], v[32:35], v[76:79]
	v_mfma_f32_16x16x32_bf16 v[76:79], v[136:139], v[32:35], v[80:83]
	v_mfma_f32_16x16x32_bf16 v[80:83], v[132:135], v[32:35], v[84:87]
	s_nop 2
	ds_read_b128 v[84:87], v49 offset:50176
	ds_read_b128 v[132:135], v49 offset:52224
	ds_read_b128 v[136:139], v49 offset:54272
	ds_read_b128 v[140:143], v49 offset:56320
	v_mfma_f32_16x16x32_bf16 v[104:107], v[124:127], v[32:35], v[104:107]
	ds_read_b128 v[124:127], v49 offset:58368
	ds_read_b128 v[144:147], v49 offset:60416
	ds_read_b128 v[148:151], v49 offset:62464
	ds_read_b128 v[152:155], v49 offset:64512
	v_mfma_f32_16x16x32_bf16 v[108:111], v[120:123], v[32:35], v[108:111]
	s_add_u32 s100, s10, 0x11620280
	s_addc_u32 s101, s11, 0
	s_mov_b32 m0, s26
	s_nop 0
	global_load_lds_dwordx4 v240, s[100:101]
	s_waitcnt lgkmcnt(0)
	v_mfma_f32_16x16x32_bf16 v[84:87], v[84:87], v[32:35], v[88:91]
	v_mfma_f32_16x16x32_bf16 v[88:91], v[132:135], v[32:35], v[92:95]
	v_mfma_f32_16x16x32_bf16 v[92:95], v[136:139], v[32:35], v[96:99]
	v_mfma_f32_16x16x32_bf16 v[96:99], v[140:143], v[32:35], v[100:103]
	v_mfma_f32_16x16x32_bf16 v[100:103], v[124:127], v[32:35], v[112:115]
	v_mfma_f32_16x16x32_bf16 v[112:115], v[144:147], v[32:35], v[116:119]
	v_mfma_f32_16x16x32_bf16 v[116:119], v[148:151], v[32:35], v[128:131]
	v_mfma_f32_16x16x32_bf16 v[32:35], v[152:155], v[32:35], v[36:39]
	s_add_u32 s100, s10, 0x11630280
	s_addc_u32 s101, s11, 0
	s_mov_b32 m0, s27
	s_nop 0
	global_load_lds_dwordx4 v240, s[100:101]
	s_nop 0
	s_waitcnt vmcnt(0)
	s_waitcnt vmcnt(0)
	s_barrier
	v_mov_b32_e32 v49, v65
	ds_read_b128 v[36:39], v49
	ds_read_b128 v[66:69], v49 offset:2048
	s_waitcnt lgkmcnt(0)
	v_mfma_f32_16x16x32_bf16 v[36:39], v[36:39], v[28:31], v[40:43]
	s_nop 2
	ds_read_b128 v[40:43], v49 offset:4096
	v_mfma_f32_16x16x32_bf16 v[44:47], v[66:69], v[28:31], v[44:47]
	ds_read_b128 v[66:69], v49 offset:6144
	s_waitcnt lgkmcnt(0)
	v_mfma_f32_16x16x32_bf16 v[40:43], v[40:43], v[28:31], v[50:53]
	s_nop 2
	ds_read_b128 v[50:53], v49 offset:8192
	v_mfma_f32_16x16x32_bf16 v[66:69], v[66:69], v[28:31], v[72:75]
	s_nop 2
	ds_read_b128 v[72:75], v49 offset:10240
	s_waitcnt lgkmcnt(0)
	v_mfma_f32_16x16x32_bf16 v[50:53], v[50:53], v[28:31], v[76:79]
	s_nop 2
	ds_read_b128 v[76:79], v49 offset:12288
	ds_read_b128 v[120:123], v49 offset:14336
	v_mfma_f32_16x16x32_bf16 v[72:75], v[72:75], v[28:31], v[80:83]
	s_nop 2
	ds_read_b128 v[80:83], v49 offset:32768
	ds_read_b128 v[124:127], v49 offset:34816
	ds_read_b128 v[128:131], v49 offset:36864
	ds_read_b128 v[132:135], v49 offset:38912
	s_waitcnt lgkmcnt(0)
	v_mfma_f32_16x16x32_bf16 v[76:79], v[76:79], v[28:31], v[104:107]
	s_nop 2
	ds_read_b128 v[104:107], v49 offset:40960
	ds_read_b128 v[136:139], v49 offset:43008
	ds_read_b128 v[140:143], v49 offset:45056
	ds_read_b128 v[144:147], v49 offset:47104
	v_mfma_f32_16x16x32_bf16 v[108:111], v[120:123], v[28:31], v[108:111]
	s_add_u32 s100, s10, 0x11600300
	s_addc_u32 s101, s11, 0
	s_mov_b32 m0, s19
	s_nop 0
	global_load_lds_dwordx4 v240, s[100:101]
	v_mfma_f32_16x16x32_bf16 v[80:83], v[80:83], v[28:31], v[84:87]
	v_mfma_f32_16x16x32_bf16 v[84:87], v[124:127], v[28:31], v[88:91]
	v_mfma_f32_16x16x32_bf16 v[88:91], v[128:131], v[28:31], v[92:95]
	v_mfma_f32_16x16x32_bf16 v[92:95], v[132:135], v[28:31], v[96:99]
	s_waitcnt lgkmcnt(0)
	v_mfma_f32_16x16x32_bf16 v[96:99], v[104:107], v[28:31], v[100:103]
	v_mfma_f32_16x16x32_bf16 v[100:103], v[136:139], v[28:31], v[112:115]
	ds_read_b128 v[104:107], v49 offset:15360
	s_nop 1
	ds_read_b128 v[112:115], v49 offset:13312
	ds_read_b128 v[120:123], v49 offset:11264
	ds_read_b128 v[124:127], v49 offset:9216
	v_mfma_f32_16x16x32_bf16 v[116:119], v[140:143], v[28:31], v[116:119]
	ds_read_b128 v[128:131], v49 offset:7168
	ds_read_b128 v[132:135], v49 offset:5120
	ds_read_b128 v[136:139], v49 offset:3072
	ds_read_b128 v[140:143], v49 offset:1024
	v_mfma_f32_16x16x32_bf16 v[28:31], v[144:147], v[28:31], v[32:35]
	s_add_u32 s100, s10, 0x11610300
	s_addc_u32 s101, s11, 0
	s_mov_b32 m0, s13
	s_nop 0
	global_load_lds_dwordx4 v240, s[100:101]
	s_waitcnt lgkmcnt(0)
	v_mfma_f32_16x16x32_bf16 v[32:35], v[140:143], v[24:27], v[36:39]
	v_mfma_f32_16x16x32_bf16 v[36:39], v[136:139], v[24:27], v[44:47]
	v_mfma_f32_16x16x32_bf16 v[40:43], v[132:135], v[24:27], v[40:43]
	v_mfma_f32_16x16x32_bf16 v[44:47], v[128:131], v[24:27], v[66:69]
	v_mfma_f32_16x16x32_bf16 v[50:53], v[124:127], v[24:27], v[50:53]
	v_mfma_f32_16x16x32_bf16 v[66:69], v[120:123], v[24:27], v[72:75]
	s_nop 2
	ds_read_b128 v[72:75], v49 offset:33792
	ds_read_b128 v[120:123], v49 offset:35840
	ds_read_b128 v[124:127], v49 offset:37888
	ds_read_b128 v[128:131], v49 offset:39936
	v_mfma_f32_16x16x32_bf16 v[76:79], v[112:115], v[24:27], v[76:79]
	ds_read_b128 v[112:115], v49 offset:41984
	ds_read_b128 v[132:135], v49 offset:44032
	ds_read_b128 v[136:139], v49 offset:46080
	ds_read_b128 v[140:143], v49 offset:48128
	v_mfma_f32_16x16x32_bf16 v[104:107], v[104:107], v[24:27], v[108:111]
	s_add_u32 s100, s10, 0x11600380
	s_addc_u32 s101, s11, 0
	s_mov_b32 m0, s12
	s_nop 0
	global_load_lds_dwordx4 v240, s[100:101]
	s_waitcnt lgkmcnt(0)
	v_mfma_f32_16x16x32_bf16 v[72:75], v[72:75], v[24:27], v[80:83]
	v_mfma_f32_16x16x32_bf16 v[80:83], v[120:123], v[24:27], v[84:87]
	v_mfma_f32_16x16x32_bf16 v[84:87], v[124:127], v[24:27], v[88:91]
	v_mfma_f32_16x16x32_bf16 v[88:91], v[128:131], v[24:27], v[92:95]
	v_mfma_f32_16x16x32_bf16 v[92:95], v[112:115], v[24:27], v[96:99]
	v_mfma_f32_16x16x32_bf16 v[96:99], v[132:135], v[24:27], v[100:103]
	s_nop 2
	ds_read_b128 v[100:103], v49 offset:30720
	ds_read_b128 v[108:111], v49 offset:28672
	ds_read_b128 v[112:115], v49 offset:26624
	ds_read_b128 v[120:123], v49 offset:24576
	v_mfma_f32_16x16x32_bf16 v[116:119], v[136:139], v[24:27], v[116:119]
	ds_read_b128 v[124:127], v49 offset:22528
	ds_read_b128 v[128:131], v49 offset:20480
	ds_read_b128 v[132:135], v49 offset:18432
	ds_read_b128 v[136:139], v49 offset:16384
	v_mfma_f32_16x16x32_bf16 v[24:27], v[140:143], v[24:27], v[28:31]
	s_add_u32 s100, s10, 0x11610380
	s_addc_u32 s101, s11, 0
	s_mov_b32 m0, s14
	s_nop 0
	global_load_lds_dwordx4 v240, s[100:101]
	s_waitcnt lgkmcnt(0)
	v_mfma_f32_16x16x32_bf16 v[28:31], v[136:139], v[20:23], v[32:35]
	v_mfma_f32_16x16x32_bf16 v[32:35], v[132:135], v[20:23], v[36:39]
	v_mfma_f32_16x16x32_bf16 v[36:39], v[128:131], v[20:23], v[40:43]
	v_mfma_f32_16x16x32_bf16 v[40:43], v[124:127], v[20:23], v[44:47]
	v_mfma_f32_16x16x32_bf16 v[44:47], v[120:123], v[20:23], v[50:53]
	v_mfma_f32_16x16x32_bf16 v[50:53], v[112:115], v[20:23], v[66:69]
	s_nop 2
	ds_read_b128 v[66:69], v49 offset:49152
	ds_read_b128 v[112:115], v49 offset:51200
	ds_read_b128 v[120:123], v49 offset:53248
	ds_read_b128 v[124:127], v49 offset:55296
	v_mfma_f32_16x16x32_bf16 v[76:79], v[108:111], v[20:23], v[76:79]
	ds_read_b128 v[108:111], v49 offset:57344
	ds_read_b128 v[128:131], v49 offset:59392
	ds_read_b128 v[132:135], v49 offset:61440
	ds_read_b128 v[136:139], v49 offset:63488
	v_mfma_f32_16x16x32_bf16 v[100:103], v[100:103], v[20:23], v[104:107]
	s_add_u32 s100, s10, 0x11620300
	s_addc_u32 s101, s11, 0
	s_mov_b32 m0, s15
	s_nop 0
	global_load_lds_dwordx4 v240, s[100:101]
	s_waitcnt lgkmcnt(0)
	v_mfma_f32_16x16x32_bf16 v[66:69], v[66:69], v[20:23], v[72:75]
	v_mfma_f32_16x16x32_bf16 v[72:75], v[112:115], v[20:23], v[80:83]
	v_mfma_f32_16x16x32_bf16 v[80:83], v[120:123], v[20:23], v[84:87]
	v_mfma_f32_16x16x32_bf16 v[84:87], v[124:127], v[20:23], v[88:91]
	v_mfma_f32_16x16x32_bf16 v[88:91], v[108:111], v[20:23], v[92:95]
	v_mfma_f32_16x16x32_bf16 v[92:95], v[128:131], v[20:23], v[96:99]
	s_nop 2
	ds_read_b128 v[96:99], v49 offset:31744
	ds_read_b128 v[104:107], v49 offset:29696
	ds_read_b128 v[108:111], v49 offset:27648
	ds_read_b128 v[112:115], v49 offset:25600
	v_mfma_f32_16x16x32_bf16 v[116:119], v[132:135], v[20:23], v[116:119]
	ds_read_b128 v[120:123], v49 offset:23552
	ds_read_b128 v[124:127], v49 offset:21504
	ds_read_b128 v[128:131], v49 offset:19456
	ds_read_b128 v[132:135], v49 offset:17408
	v_mfma_f32_16x16x32_bf16 v[20:23], v[136:139], v[20:23], v[24:27]
	s_add_u32 s100, s10, 0x11630300
	s_addc_u32 s101, s11, 0
	s_mov_b32 m0, s16
	s_nop 0
	global_load_lds_dwordx4 v240, s[100:101]
	s_waitcnt lgkmcnt(0)
	v_mfma_f32_16x16x32_bf16 v[24:27], v[132:135], v[16:19], v[28:31]
	v_mfma_f32_16x16x32_bf16 v[28:31], v[128:131], v[16:19], v[32:35]
	v_mfma_f32_16x16x32_bf16 v[32:35], v[124:127], v[16:19], v[36:39]
	v_mfma_f32_16x16x32_bf16 v[36:39], v[120:123], v[16:19], v[40:43]
	v_mfma_f32_16x16x32_bf16 v[40:43], v[112:115], v[16:19], v[44:47]
	v_mfma_f32_16x16x32_bf16 v[50:53], v[108:111], v[16:19], v[50:53]
	s_nop 1
	ds_read_b128 v[44:47], v49 offset:50176
	ds_read_b128 v[108:111], v49 offset:52224
	ds_read_b128 v[112:115], v49 offset:54272
	ds_read_b128 v[120:123], v49 offset:56320
	v_mfma_f32_16x16x32_bf16 v[76:79], v[104:107], v[16:19], v[76:79]
	ds_read_b128 v[104:107], v49 offset:58368
	ds_read_b128 v[124:127], v49 offset:60416
	ds_read_b128 v[128:131], v49 offset:62464
	ds_read_b128 v[132:135], v49 offset:64512
	v_mfma_f32_16x16x32_bf16 v[96:99], v[96:99], v[16:19], v[100:103]
	s_add_u32 s100, s10, 0x11620380
	s_addc_u32 s101, s11, 0
	s_mov_b32 m0, s17
	s_nop 0
	global_load_lds_dwordx4 v240, s[100:101]
	s_waitcnt lgkmcnt(0)
	v_mfma_f32_16x16x32_bf16 v[66:69], v[44:47], v[16:19], v[66:69]
	v_mfma_f32_16x16x32_bf16 v[72:75], v[108:111], v[16:19], v[72:75]
	v_mfma_f32_16x16x32_bf16 v[80:83], v[112:115], v[16:19], v[80:83]
	v_mfma_f32_16x16x32_bf16 v[84:87], v[120:123], v[16:19], v[84:87]
	v_mfma_f32_16x16x32_bf16 v[88:91], v[104:107], v[16:19], v[88:91]
	v_mfma_f32_16x16x32_bf16 v[92:95], v[124:127], v[16:19], v[92:95]
	v_mfma_f32_16x16x32_bf16 v[100:103], v[128:131], v[16:19], v[116:119]
	v_mfma_f32_16x16x32_bf16 v[16:19], v[132:135], v[16:19], v[20:23]
	s_add_u32 s100, s10, 0x11630380
	s_addc_u32 s101, s11, 0
	s_mov_b32 m0, s18
	s_nop 0
	global_load_lds_dwordx4 v240, s[100:101]
	s_waitcnt vmcnt(0)
	s_waitcnt vmcnt(0)
	s_barrier
	v_mov_b32_e32 v49, v48
	ds_read_b128 v[20:23], v49
	ds_read_b128 v[104:107], v49 offset:2048
	s_waitcnt lgkmcnt(0)
	v_mfma_f32_16x16x32_bf16 v[20:23], v[20:23], v[12:15], v[24:27]
	s_nop 2
	ds_read_b128 v[24:27], v49 offset:4096
	v_mfma_f32_16x16x32_bf16 v[28:31], v[104:107], v[12:15], v[28:31]
	ds_read_b128 v[104:107], v49 offset:6144
	s_waitcnt lgkmcnt(0)
	v_mfma_f32_16x16x32_bf16 v[24:27], v[24:27], v[12:15], v[32:35]
	s_nop 2
	ds_read_b128 v[32:35], v49 offset:8192
	v_mfma_f32_16x16x32_bf16 v[36:39], v[104:107], v[12:15], v[36:39]
	ds_read_b128 v[104:107], v49 offset:10240
	s_waitcnt lgkmcnt(0)
	v_mfma_f32_16x16x32_bf16 v[32:35], v[32:35], v[12:15], v[40:43]
	s_nop 2
	ds_read_b128 v[40:43], v49 offset:12288
	ds_read_b128 v[108:111], v49 offset:14336
	v_mfma_f32_16x16x32_bf16 v[50:53], v[104:107], v[12:15], v[50:53]
	ds_read_b128 v[104:107], v49 offset:32768
	ds_read_b128 v[112:115], v49 offset:34816
	ds_read_b128 v[116:119], v49 offset:36864
	ds_read_b128 v[120:123], v49 offset:38912
	s_waitcnt lgkmcnt(0)
	v_mfma_f32_16x16x32_bf16 v[40:43], v[40:43], v[12:15], v[76:79]
	s_nop 2
	ds_read_b128 v[76:79], v49 offset:40960
	ds_read_b128 v[124:127], v49 offset:43008
	ds_read_b128 v[128:131], v49 offset:45056
	ds_read_b128 v[132:135], v49 offset:47104
	v_mfma_f32_16x16x32_bf16 v[96:99], v[108:111], v[12:15], v[96:99]
	s_add_u32 s100, s10, 0x11e00000
	s_addc_u32 s101, s11, 0
	s_mov_b32 m0, s22
	s_nop 0
	global_load_lds_dwordx4 v241, s[100:101]
	v_mfma_f32_16x16x32_bf16 v[66:69], v[104:107], v[12:15], v[66:69]
	v_mfma_f32_16x16x32_bf16 v[72:75], v[112:115], v[12:15], v[72:75]
	v_mfma_f32_16x16x32_bf16 v[80:83], v[116:119], v[12:15], v[80:83]
	v_mfma_f32_16x16x32_bf16 v[84:87], v[120:123], v[12:15], v[84:87]
	s_waitcnt lgkmcnt(0)
	v_mfma_f32_16x16x32_bf16 v[76:79], v[76:79], v[12:15], v[88:91]
	v_mfma_f32_16x16x32_bf16 v[88:91], v[124:127], v[12:15], v[92:95]
	s_nop 2
	ds_read_b128 v[92:95], v49 offset:15360
	ds_read_b128 v[104:107], v49 offset:13312
	ds_read_b128 v[108:111], v49 offset:11264
	ds_read_b128 v[112:115], v49 offset:9216
	v_mfma_f32_16x16x32_bf16 v[100:103], v[128:131], v[12:15], v[100:103]
	ds_read_b128 v[116:119], v49 offset:7168
	ds_read_b128 v[120:123], v49 offset:5120
	ds_read_b128 v[124:127], v49 offset:3072
	ds_read_b128 v[128:131], v49 offset:1024
	v_mfma_f32_16x16x32_bf16 v[12:15], v[132:135], v[12:15], v[16:19]
	s_add_u32 s100, s10, 0x11e08000
	s_addc_u32 s101, s11, 0
	s_mov_b32 m0, s21
	s_nop 0
	global_load_lds_dwordx4 v241, s[100:101]
	s_waitcnt lgkmcnt(0)
	v_mfma_f32_16x16x32_bf16 v[16:19], v[128:131], v[8:11], v[20:23]
	v_mfma_f32_16x16x32_bf16 v[20:23], v[124:127], v[8:11], v[28:31]
	v_mfma_f32_16x16x32_bf16 v[24:27], v[120:123], v[8:11], v[24:27]
	v_mfma_f32_16x16x32_bf16 v[28:31], v[116:119], v[8:11], v[36:39]
	v_mfma_f32_16x16x32_bf16 v[32:35], v[112:115], v[8:11], v[32:35]
	v_mfma_f32_16x16x32_bf16 v[36:39], v[108:111], v[8:11], v[50:53]
	s_nop 2
	ds_read_b128 v[50:53], v49 offset:33792
	ds_read_b128 v[108:111], v49 offset:35840
	ds_read_b128 v[112:115], v49 offset:37888
	ds_read_b128 v[116:119], v49 offset:39936
	v_mfma_f32_16x16x32_bf16 v[40:43], v[104:107], v[8:11], v[40:43]
	ds_read_b128 v[104:107], v49 offset:41984
	ds_read_b128 v[120:123], v49 offset:44032
	ds_read_b128 v[124:127], v49 offset:46080
	ds_read_b128 v[128:131], v49 offset:48128
	v_mfma_f32_16x16x32_bf16 v[92:95], v[92:95], v[8:11], v[96:99]
	s_add_u32 s100, s10, 0x11e00080
	s_addc_u32 s101, s11, 0
	s_mov_b32 m0, s20
	s_nop 0
	global_load_lds_dwordx4 v241, s[100:101]
	s_waitcnt lgkmcnt(0)
	v_mfma_f32_16x16x32_bf16 v[50:53], v[50:53], v[8:11], v[66:69]
	v_mfma_f32_16x16x32_bf16 v[66:69], v[108:111], v[8:11], v[72:75]
	v_mfma_f32_16x16x32_bf16 v[72:75], v[112:115], v[8:11], v[80:83]
	v_mfma_f32_16x16x32_bf16 v[80:83], v[116:119], v[8:11], v[84:87]
	v_mfma_f32_16x16x32_bf16 v[76:79], v[104:107], v[8:11], v[76:79]
	v_mfma_f32_16x16x32_bf16 v[84:87], v[120:123], v[8:11], v[88:91]
	s_nop 2
	ds_read_b128 v[88:91], v49 offset:30720
	ds_read_b128 v[96:99], v49 offset:28672
	ds_read_b128 v[104:107], v49 offset:26624
	ds_read_b128 v[108:111], v49 offset:24576
	v_mfma_f32_16x16x32_bf16 v[100:103], v[124:127], v[8:11], v[100:103]
	ds_read_b128 v[112:115], v49 offset:22528
	ds_read_b128 v[116:119], v49 offset:20480
	ds_read_b128 v[120:123], v49 offset:18432
	ds_read_b128 v[124:127], v49 offset:16384
	v_mfma_f32_16x16x32_bf16 v[8:11], v[128:131], v[8:11], v[12:15]
	s_add_u32 s100, s10, 0x11e08080
	s_addc_u32 s101, s11, 0
	s_mov_b32 m0, s23
	s_nop 0
	global_load_lds_dwordx4 v241, s[100:101]
	s_waitcnt lgkmcnt(0)
	v_mfma_f32_16x16x32_bf16 v[12:15], v[124:127], v[4:7], v[16:19]
	v_mfma_f32_16x16x32_bf16 v[16:19], v[120:123], v[4:7], v[20:23]
	v_mfma_f32_16x16x32_bf16 v[20:23], v[116:119], v[4:7], v[24:27]
	v_mfma_f32_16x16x32_bf16 v[24:27], v[112:115], v[4:7], v[28:31]
	v_mfma_f32_16x16x32_bf16 v[28:31], v[108:111], v[4:7], v[32:35]
	v_mfma_f32_16x16x32_bf16 v[32:35], v[104:107], v[4:7], v[36:39]
	s_nop 2
	ds_read_b128 v[36:39], v49 offset:49152
	ds_read_b128 v[104:107], v49 offset:51200
	ds_read_b128 v[108:111], v49 offset:53248
	ds_read_b128 v[112:115], v49 offset:55296
	v_mfma_f32_16x16x32_bf16 v[96:99], v[96:99], v[4:7], v[40:43]
	s_nop 2
	ds_read_b128 v[40:43], v49 offset:57344
	ds_read_b128 v[116:119], v49 offset:59392
	ds_read_b128 v[120:123], v49 offset:61440
	ds_read_b128 v[124:127], v49 offset:63488
	v_mfma_f32_16x16x32_bf16 v[88:91], v[88:91], v[4:7], v[92:95]
	s_add_u32 s100, s10, 0x11e10000
	s_addc_u32 s101, s11, 0
	s_mov_b32 m0, s24
	s_nop 0
	global_load_lds_dwordx4 v241, s[100:101]
	s_waitcnt lgkmcnt(0)
	v_mfma_f32_16x16x32_bf16 v[50:53], v[36:39], v[4:7], v[50:53]
	v_mfma_f32_16x16x32_bf16 v[66:69], v[104:107], v[4:7], v[66:69]
	v_mfma_f32_16x16x32_bf16 v[72:75], v[108:111], v[4:7], v[72:75]
	v_mfma_f32_16x16x32_bf16 v[80:83], v[112:115], v[4:7], v[80:83]
	v_mfma_f32_16x16x32_bf16 v[76:79], v[40:43], v[4:7], v[76:79]
	ds_read_b128 v[92:95], v49 offset:31744
	ds_read_b128 v[36:39], v49 offset:29696
	ds_read_b128 v[40:43], v49 offset:27648
	ds_read_b128 v[104:107], v49 offset:25600
	v_mfma_f32_16x16x32_bf16 v[84:87], v[116:119], v[4:7], v[84:87]
	v_mfma_f32_16x16x32_bf16 v[100:103], v[120:123], v[4:7], v[100:103]
	ds_read_b128 v[108:111], v49 offset:23552
	ds_read_b128 v[112:115], v49 offset:21504
	ds_read_b128 v[116:119], v49 offset:19456
	ds_read_b128 v[120:123], v49 offset:17408
	v_mfma_f32_16x16x32_bf16 v[124:127], v[124:127], v[4:7], v[8:11]
	s_add_u32 s100, s10, 0x11e18000
	s_addc_u32 s101, s11, 0
	s_mov_b32 m0, s25
	s_nop 0
	global_load_lds_dwordx4 v241, s[100:101]
	s_waitcnt lgkmcnt(0)
	v_mfma_f32_16x16x32_bf16 v[120:123], v[120:123], v[0:3], v[12:15]
	v_mfma_f32_16x16x32_bf16 v[116:119], v[116:119], v[0:3], v[16:19]
	ds_read_b128 v[4:7], v49 offset:50176
	ds_read_b128 v[8:11], v49 offset:52224
	ds_read_b128 v[12:15], v49 offset:54272
	ds_read_b128 v[16:19], v49 offset:56320
	v_mfma_f32_16x16x32_bf16 v[36:39], v[36:39], v[0:3], v[96:99]
	s_nop 2
	ds_read_b128 v[96:99], v49 offset:58368
	ds_read_b128 v[128:131], v49 offset:60416
	ds_read_b128 v[132:135], v49 offset:62464
	ds_read_b128 v[136:139], v49 offset:64512
	v_mfma_f32_16x16x32_bf16 v[112:115], v[112:115], v[0:3], v[20:23]
	v_mfma_f32_16x16x32_bf16 v[108:111], v[108:111], v[0:3], v[24:27]
	v_mfma_f32_16x16x32_bf16 v[104:107], v[104:107], v[0:3], v[28:31]
	v_mfma_f32_16x16x32_bf16 v[40:43], v[40:43], v[0:3], v[32:35]
	v_mfma_f32_16x16x32_bf16 v[32:35], v[92:95], v[0:3], v[88:91]
	s_add_u32 s100, s10, 0x11e10080
	s_addc_u32 s101, s11, 0
	s_mov_b32 m0, s26
	s_nop 0
	global_load_lds_dwordx4 v241, s[100:101]
	s_waitcnt lgkmcnt(0)
	v_mfma_f32_16x16x32_bf16 v[28:31], v[4:7], v[0:3], v[50:53]
	v_mfma_f32_16x16x32_bf16 v[24:27], v[8:11], v[0:3], v[66:69]
	v_mfma_f32_16x16x32_bf16 v[20:23], v[12:15], v[0:3], v[72:75]
	v_mfma_f32_16x16x32_bf16 v[16:19], v[16:19], v[0:3], v[80:83]
	v_mfma_f32_16x16x32_bf16 v[12:15], v[96:99], v[0:3], v[76:79]
	v_mfma_f32_16x16x32_bf16 v[8:11], v[128:131], v[0:3], v[84:87]
	v_mfma_f32_16x16x32_bf16 v[4:7], v[132:135], v[0:3], v[100:103]
	v_mfma_f32_16x16x32_bf16 v[0:3], v[136:139], v[0:3], v[124:127]
	s_add_u32 s100, s10, 0x11e18080
	s_addc_u32 s101, s11, 0
	s_mov_b32 m0, s27
	s_nop 0
	global_load_lds_dwordx4 v241, s[100:101]
	v_max_f32_e32 v49, v123, v123
	v_max_f32_e32 v50, v122, v122
	v_max_f32_e32 v49, v50, v49
	v_max_f32_e32 v50, v117, v117
	v_max_f32_e32 v51, v116, v116
	v_max_f32_e32 v50, v51, v50
	v_max_f32_e32 v51, v119, v119
	v_max_f32_e32 v52, v118, v118
	v_max3_f32 v49, v120, v121, v49
	v_max_f32_e32 v51, v52, v51
	v_max3_f32 v49, v49, v50, v51
	v_max_f32_e32 v50, v113, v113
	v_max_f32_e32 v51, v112, v112
	v_max_f32_e32 v50, v51, v50
	v_max_f32_e32 v51, v115, v115
	v_max_f32_e32 v52, v114, v114
	v_max_f32_e32 v51, v52, v51
	v_max3_f32 v49, v49, v50, v51
	v_max_f32_e32 v50, v109, v109
	v_max_f32_e32 v51, v108, v108
	v_max_f32_e32 v50, v51, v50
	v_max_f32_e32 v51, v111, v111
	v_max_f32_e32 v52, v110, v110
	v_max_f32_e32 v51, v52, v51
	v_max3_f32 v49, v49, v50, v51
	v_max_f32_e32 v50, v105, v105
	v_max_f32_e32 v51, v104, v104
	v_max_f32_e32 v50, v51, v50
	v_max_f32_e32 v51, v107, v107
	v_max_f32_e32 v52, v106, v106
	v_max_f32_e32 v51, v52, v51
	v_max3_f32 v49, v49, v50, v51
	v_max_f32_e32 v50, v41, v41
	v_max_f32_e32 v51, v40, v40
	v_max_f32_e32 v50, v51, v50
	v_max_f32_e32 v51, v43, v43
	v_max_f32_e32 v52, v42, v42
	v_max_f32_e32 v51, v52, v51
	v_max3_f32 v49, v49, v50, v51
	v_max_f32_e32 v50, v37, v37
	v_max_f32_e32 v51, v36, v36
	v_max_f32_e32 v50, v51, v50
	v_max_f32_e32 v51, v39, v39
	v_max_f32_e32 v52, v38, v38
	v_max_f32_e32 v51, v52, v51
	v_max3_f32 v49, v49, v50, v51
	v_max_f32_e32 v50, v33, v33
	v_max_f32_e32 v51, v32, v32
	v_max_f32_e32 v50, v51, v50
	v_max_f32_e32 v51, v35, v35
	v_max_f32_e32 v52, v34, v34
	v_max_f32_e32 v51, v52, v51
	v_max3_f32 v49, v49, v50, v51
	v_max_f32_e32 v50, v29, v29
	v_max_f32_e32 v51, v28, v28
	v_max_f32_e32 v50, v51, v50
	v_max_f32_e32 v51, v31, v31
	v_max_f32_e32 v52, v30, v30
	v_max_f32_e32 v51, v52, v51
	v_max3_f32 v49, v49, v50, v51
	v_max_f32_e32 v50, v25, v25
	v_max_f32_e32 v51, v24, v24
	v_max_f32_e32 v50, v51, v50
	v_max_f32_e32 v51, v27, v27
	v_max_f32_e32 v52, v26, v26
	v_max_f32_e32 v51, v52, v51
	v_max3_f32 v49, v49, v50, v51
	v_max_f32_e32 v50, v21, v21
	v_max_f32_e32 v51, v20, v20
	v_max_f32_e32 v50, v51, v50
	v_max_f32_e32 v51, v23, v23
	v_max_f32_e32 v52, v22, v22
	v_max_f32_e32 v51, v52, v51
	v_max3_f32 v49, v49, v50, v51
	v_max_f32_e32 v50, v17, v17
	v_max_f32_e32 v51, v16, v16
	v_max_f32_e32 v50, v51, v50
	v_max_f32_e32 v51, v19, v19
	v_max_f32_e32 v52, v18, v18
	v_max_f32_e32 v51, v52, v51
	v_max3_f32 v49, v49, v50, v51
	v_max_f32_e32 v50, v13, v13
	v_max_f32_e32 v51, v12, v12
	v_max_f32_e32 v50, v51, v50
	v_max_f32_e32 v51, v15, v15
	v_max_f32_e32 v52, v14, v14
	v_max_f32_e32 v51, v52, v51
	v_max3_f32 v49, v49, v50, v51
	v_max_f32_e32 v50, v9, v9
	v_max_f32_e32 v51, v8, v8
	v_max_f32_e32 v50, v51, v50
	v_max_f32_e32 v51, v11, v11
	v_max_f32_e32 v52, v10, v10
	v_max_f32_e32 v51, v52, v51
	v_max3_f32 v49, v49, v50, v51
	v_max_f32_e32 v50, v5, v5
	v_max_f32_e32 v51, v4, v4
	v_max_f32_e32 v50, v51, v50
	v_max_f32_e32 v51, v7, v7
	v_max_f32_e32 v52, v6, v6
	v_max_f32_e32 v51, v52, v51
	v_max3_f32 v49, v49, v50, v51
	v_max_f32_e32 v50, v1, v1
	v_max_f32_e32 v51, v0, v0
	v_max_f32_e32 v50, v51, v50
	v_max_f32_e32 v51, v3, v3
	v_max_f32_e32 v52, v2, v2
	v_max_f32_e32 v51, v52, v51
	v_max3_f32 v49, v49, v50, v51
	v_mbcnt_lo_u32_b32 v50, -1, 0
	v_mbcnt_hi_u32_b32 v50, -1, v50
	v_and_b32_e32 v52, 64, v50
	v_xor_b32_e32 v51, 16, v50
	v_add_u32_e32 v52, 64, v52
	v_cmp_lt_i32_e32 vcc, v51, v52
	s_nop 1
	v_cndmask_b32_e32 v51, v50, v51, vcc
	v_lshlrev_b32_e32 v51, 2, v51
	v_mov_b32_e32 v53, v49
	s_nop 1
	v_permlane16_swap_b32_e32 v53, v49
	s_waitcnt lgkmcnt(0)
	v_max_f32_e32 v53, v53, v53
	v_max_f32_e32 v49, v49, v53
	v_xor_b32_e32 v53, 32, v50
	v_cmp_lt_i32_e32 vcc, v53, v52
	s_nop 1
	v_cndmask_b32_e32 v50, v50, v53, vcc
	v_lshlrev_b32_e32 v50, 2, v50
	v_mov_b32_e32 v52, v49
	s_nop 1
	v_permlane32_swap_b32_e32 v52, v49
	s_waitcnt lgkmcnt(0)
	v_max_f32_e32 v52, v52, v52
	v_max_f32_e32 v49, v49, v52
	v_sub_f32_e32 v52, v120, v49
	v_exp_f32_e32 v52, v52
	v_sub_f32_e32 v53, v121, v49
	v_exp_f32_e32 v53, v53
	v_sub_f32_e32 v54, v122, v49
	v_exp_f32_e32 v54, v54
	v_sub_f32_e32 v55, v123, v49
	v_exp_f32_e32 v55, v55
	v_sub_f32_e32 v59, v116, v49
	v_add_f32_e32 v57, 0, v52
	v_exp_f32_e32 v59, v59
	v_sub_f32_e32 v62, v117, v49
	v_add_f32_e32 v57, v53, v57
	v_exp_f32_e32 v62, v62
	v_sub_f32_e32 v63, v118, v49
	v_add_f32_e32 v57, v54, v57
	v_exp_f32_e32 v63, v63
	v_sub_f32_e32 v64, v119, v49
	v_add_f32_e32 v57, v55, v57
	v_exp_f32_e32 v64, v64
	v_sub_f32_e32 v66, v112, v49
	v_add_f32_e32 v57, v59, v57
	v_exp_f32_e32 v66, v66
	v_sub_f32_e32 v67, v113, v49
	v_add_f32_e32 v57, v62, v57
	v_exp_f32_e32 v67, v67
	v_sub_f32_e32 v68, v114, v49
	v_add_f32_e32 v57, v63, v57
	v_exp_f32_e32 v68, v68
	v_sub_f32_e32 v69, v115, v49
	v_add_f32_e32 v57, v64, v57
	v_exp_f32_e32 v69, v69
	v_sub_f32_e32 v71, v108, v49
	v_add_f32_e32 v57, v66, v57
	v_exp_f32_e32 v71, v71
	v_sub_f32_e32 v72, v109, v49
	v_add_f32_e32 v57, v67, v57
	v_exp_f32_e32 v72, v72
	v_sub_f32_e32 v73, v110, v49
	v_add_f32_e32 v57, v68, v57
	v_exp_f32_e32 v73, v73
	v_sub_f32_e32 v74, v111, v49
	v_add_f32_e32 v57, v69, v57
	v_exp_f32_e32 v74, v74
	v_sub_f32_e32 v75, v104, v49
	v_add_f32_e32 v57, v71, v57
	v_exp_f32_e32 v75, v75
	v_sub_f32_e32 v76, v105, v49
	v_add_f32_e32 v57, v72, v57
	v_exp_f32_e32 v76, v76
	v_sub_f32_e32 v77, v106, v49
	v_add_f32_e32 v57, v73, v57
	v_exp_f32_e32 v77, v77
	v_sub_f32_e32 v78, v107, v49
	v_add_f32_e32 v57, v74, v57
	v_exp_f32_e32 v78, v78
	v_sub_f32_e32 v40, v40, v49
	v_add_f32_e32 v57, v75, v57
	v_exp_f32_e32 v40, v40
	v_sub_f32_e32 v41, v41, v49
	v_add_f32_e32 v57, v76, v57
	v_exp_f32_e32 v41, v41
	v_sub_f32_e32 v42, v42, v49
	v_add_f32_e32 v57, v77, v57
	v_exp_f32_e32 v42, v42
	v_sub_f32_e32 v43, v43, v49
	v_add_f32_e32 v57, v78, v57
	v_exp_f32_e32 v43, v43
	v_sub_f32_e32 v36, v36, v49
	v_add_f32_e32 v57, v40, v57
	v_exp_f32_e32 v36, v36
	v_sub_f32_e32 v37, v37, v49
	v_add_f32_e32 v57, v41, v57
	v_exp_f32_e32 v37, v37
	v_sub_f32_e32 v38, v38, v49
	v_add_f32_e32 v57, v42, v57
	v_exp_f32_e32 v38, v38
	v_sub_f32_e32 v39, v39, v49
	v_add_f32_e32 v57, v43, v57
	v_exp_f32_e32 v39, v39
	v_sub_f32_e32 v32, v32, v49
	v_add_f32_e32 v57, v36, v57
	v_exp_f32_e32 v32, v32
	v_sub_f32_e32 v33, v33, v49
	v_add_f32_e32 v57, v37, v57
	v_exp_f32_e32 v33, v33
	v_sub_f32_e32 v34, v34, v49
	v_add_f32_e32 v57, v38, v57
	v_exp_f32_e32 v34, v34
	v_sub_f32_e32 v35, v35, v49
	v_add_f32_e32 v57, v39, v57
	v_exp_f32_e32 v35, v35
	v_sub_f32_e32 v28, v28, v49
	v_add_f32_e32 v57, v32, v57
	v_exp_f32_e32 v79, v28
	v_sub_f32_e32 v28, v29, v49
	v_add_f32_e32 v57, v33, v57
	v_exp_f32_e32 v80, v28
	v_sub_f32_e32 v28, v30, v49
	v_add_f32_e32 v57, v34, v57
	v_exp_f32_e32 v81, v28
	v_sub_f32_e32 v28, v31, v49
	v_add_f32_e32 v57, v35, v57
	v_exp_f32_e32 v82, v28
	v_sub_f32_e32 v24, v24, v49
	v_add_f32_e32 v28, v79, v57
	v_exp_f32_e32 v57, v24
	v_sub_f32_e32 v24, v25, v49
	v_add_f32_e32 v28, v80, v28
	v_exp_f32_e32 v83, v24
	v_sub_f32_e32 v24, v26, v49
	v_add_f32_e32 v28, v81, v28
	v_exp_f32_e32 v84, v24
	v_sub_f32_e32 v24, v27, v49
	v_add_f32_e32 v28, v82, v28
	v_exp_f32_e32 v85, v24
	v_sub_f32_e32 v20, v20, v49
	v_add_f32_e32 v24, v57, v28
	v_exp_f32_e32 v86, v20
	v_sub_f32_e32 v20, v21, v49
	v_add_f32_e32 v24, v83, v24
	v_exp_f32_e32 v87, v20
	v_sub_f32_e32 v20, v22, v49
	v_add_f32_e32 v24, v84, v24
	v_exp_f32_e32 v88, v20
	v_sub_f32_e32 v20, v23, v49
	v_add_f32_e32 v24, v85, v24
	v_exp_f32_e32 v89, v20
	v_sub_f32_e32 v16, v16, v49
	v_add_f32_e32 v20, v86, v24
	v_exp_f32_e32 v90, v16
	v_sub_f32_e32 v16, v17, v49
	v_add_f32_e32 v20, v87, v20
	v_exp_f32_e32 v91, v16
	v_sub_f32_e32 v16, v18, v49
	v_add_f32_e32 v20, v88, v20
	v_exp_f32_e32 v92, v16
	v_sub_f32_e32 v16, v19, v49
	v_add_f32_e32 v20, v89, v20
	v_exp_f32_e32 v93, v16
	v_sub_f32_e32 v12, v12, v49
	v_add_f32_e32 v16, v90, v20
	v_exp_f32_e32 v94, v12
	v_sub_f32_e32 v12, v13, v49
	v_add_f32_e32 v16, v91, v16
	v_exp_f32_e32 v95, v12
	v_sub_f32_e32 v12, v14, v49
	v_add_f32_e32 v16, v92, v16
	v_exp_f32_e32 v96, v12
	v_sub_f32_e32 v12, v15, v49
	v_add_f32_e32 v16, v93, v16
	v_exp_f32_e32 v97, v12
	v_sub_f32_e32 v8, v8, v49
	v_add_f32_e32 v12, v94, v16
	v_exp_f32_e32 v98, v8
	v_sub_f32_e32 v8, v9, v49
	v_add_f32_e32 v12, v95, v12
	v_exp_f32_e32 v99, v8
	v_sub_f32_e32 v8, v10, v49
	v_add_f32_e32 v12, v96, v12
	v_exp_f32_e32 v100, v8
	v_sub_f32_e32 v8, v11, v49
	v_add_f32_e32 v12, v97, v12
	v_exp_f32_e32 v11, v8
	v_sub_f32_e32 v4, v4, v49
	v_add_f32_e32 v8, v98, v12
	v_exp_f32_e32 v101, v4
	v_sub_f32_e32 v4, v5, v49
	v_add_f32_e32 v8, v99, v8
	v_exp_f32_e32 v102, v4
	v_sub_f32_e32 v4, v6, v49
	v_add_f32_e32 v8, v100, v8
	v_exp_f32_e32 v103, v4
	v_sub_f32_e32 v4, v7, v49
	v_add_f32_e32 v8, v11, v8
	v_exp_f32_e32 v104, v4
	v_sub_f32_e32 v0, v0, v49
	v_add_f32_e32 v4, v101, v8
	v_exp_f32_e32 v105, v0
	v_sub_f32_e32 v0, v1, v49
	v_add_f32_e32 v4, v102, v4
	v_exp_f32_e32 v106, v0
	v_sub_f32_e32 v0, v2, v49
	v_add_f32_e32 v4, v103, v4
	v_exp_f32_e32 v107, v0
	v_sub_f32_e32 v0, v3, v49
	v_add_f32_e32 v4, v104, v4
	v_exp_f32_e32 v3, v0
	v_add_f32_e32 v0, v105, v4
	v_add_f32_e32 v0, v106, v0
	v_add_f32_e32 v0, v107, v0
	v_add_f32_e32 v0, v3, v0
	v_mov_b32_e32 v1, v0
	s_nop 1
	v_permlane16_swap_b32_e32 v1, v0
	v_cvt_pk_bf16_f32 v28, v52, v53
	v_cvt_pk_bf16_f32 v29, v54, v55
	v_cvt_pk_bf16_f32 v30, v59, v62
	v_cvt_pk_bf16_f32 v31, v63, v64
	s_waitcnt lgkmcnt(0)
	v_add_f32_e32 v0, v0, v1
	v_mov_b32_e32 v1, v0
	s_nop 1
	v_permlane32_swap_b32_e32 v1, v0
	v_cvt_pk_bf16_f32 v20, v66, v67
	v_cvt_pk_bf16_f32 v21, v68, v69
	v_cvt_pk_bf16_f32 v22, v71, v72
	v_cvt_pk_bf16_f32 v23, v73, v74
	s_waitcnt lgkmcnt(0)
	v_add_f32_e32 v49, v0, v1
	v_cvt_pk_bf16_f32 v24, v75, v76
	v_cvt_pk_bf16_f32 v25, v77, v78
	v_cvt_pk_bf16_f32 v26, v40, v41
	v_cvt_pk_bf16_f32 v27, v42, v43
	v_cvt_pk_bf16_f32 v16, v36, v37
	v_cvt_pk_bf16_f32 v17, v38, v39
	v_cvt_pk_bf16_f32 v18, v32, v33
	v_cvt_pk_bf16_f32 v19, v34, v35
	v_cvt_pk_bf16_f32 v12, v79, v80
	v_cvt_pk_bf16_f32 v13, v81, v82
	v_cvt_pk_bf16_f32 v14, v57, v83
	v_cvt_pk_bf16_f32 v15, v84, v85
	v_cvt_pk_bf16_f32 v4, v86, v87
	v_cvt_pk_bf16_f32 v5, v88, v89
	v_cvt_pk_bf16_f32 v6, v90, v91
	v_cvt_pk_bf16_f32 v7, v92, v93
	v_cvt_pk_bf16_f32 v8, v94, v95
	v_cvt_pk_bf16_f32 v9, v96, v97
	v_cvt_pk_bf16_f32 v10, v98, v99
	v_cvt_pk_bf16_f32 v11, v100, v11
	v_cvt_pk_bf16_f32 v0, v101, v102
	v_cvt_pk_bf16_f32 v1, v103, v104
	v_cvt_pk_bf16_f32 v2, v105, v106
	v_cvt_pk_bf16_f32 v3, v107, v3
	s_waitcnt vmcnt(0)
	s_waitcnt vmcnt(0)
	s_barrier
	v_mov_b32_e32 v64, v65
	v_div_scale_f32 v62, vcc, 1.0, v49, 1.0
	v_lshlrev_b32_e32 v54, 2, v70
	v_ashrrev_i32_e32 v55, 31, v54
	ds_read_b128 v[32:35], v64
	ds_read_b128 v[36:39], v64 offset:2048
	v_div_scale_f32 v57, s[0:1], v49, v49, 1.0
	v_rcp_f32_e32 v59, v57
	s_waitcnt lgkmcnt(0)
	v_mfma_f32_16x16x32_bf16 v[44:47], v[32:35], v[28:31], 0
	v_fma_f32 v40, -v57, v59, 1.0
	v_fmac_f32_e32 v59, v40, v59
	ds_read_b128 v[40:43], v64 offset:4096
	ds_read_b128 v[32:35], v64 offset:6144
	v_mul_f32_e32 v63, v62, v59
	v_fma_f32 v66, -v57, v63, v62
	v_fmac_f32_e32 v63, v66, v59
	v_mfma_f32_16x16x32_bf16 v[50:53], v[36:39], v[28:31], 0
	v_fma_f32 v36, -v57, v63, v62
	ds_read_b128 v[66:69], v64 offset:8192
	ds_read_b128 v[70:73], v64 offset:10240
	v_div_fmas_f32 v36, v36, v59, v63
	s_waitcnt lgkmcnt(0)
	v_mfma_f32_16x16x32_bf16 v[74:77], v[32:35], v[28:31], 0
	v_lshl_add_u64 v[34:35], v[54:55], 1, v[60:61]
	ds_read_b128 v[60:63], v64 offset:12288
	ds_read_b128 v[78:81], v64 offset:14336
	ds_read_b128 v[82:85], v64 offset:32768
	ds_read_b128 v[86:89], v64 offset:34816
	ds_read_b128 v[90:93], v64 offset:36864
	ds_read_b128 v[94:97], v64 offset:38912
	ds_read_b128 v[98:101], v64 offset:40960
	ds_read_b128 v[102:105], v64 offset:43008
	ds_read_b128 v[106:109], v64 offset:45056
	ds_read_b128 v[110:113], v64 offset:47104
	s_mov_b64 s[0:1], 0x1000000
	v_mfma_f32_16x16x32_bf16 v[38:41], v[40:43], v[28:31], 0
	v_div_fixup_f32 v36, v36, v49, 1.0
	v_lshl_add_u64 v[32:33], v[34:35], 0, s[0:1]
	v_mfma_f32_16x16x32_bf16 v[66:69], v[66:69], v[28:31], 0
	v_mfma_f32_16x16x32_bf16 v[70:73], v[70:73], v[28:31], 0
	s_waitcnt lgkmcnt(0)
	v_mfma_f32_16x16x32_bf16 v[60:63], v[60:63], v[28:31], 0
	v_mfma_f32_16x16x32_bf16 v[78:81], v[78:81], v[28:31], 0
	s_add_u32 s100, s10, 0x11e00100
	s_addc_u32 s101, s11, 0
	s_mov_b32 m0, s19
	s_nop 0
	global_load_lds_dwordx4 v241, s[100:101]
	ds_read_b128 v[114:117], v64 offset:30720
	ds_read_b128 v[118:121], v64 offset:28672
	ds_read_b128 v[122:125], v64 offset:26624
	ds_read_b128 v[126:129], v64 offset:24576
	ds_read_b128 v[130:133], v64 offset:22528
	ds_read_b128 v[134:137], v64 offset:20480
	ds_read_b128 v[138:141], v64 offset:18432
	ds_read_b128 v[142:145], v64 offset:16384
	v_mfma_f32_16x16x32_bf16 v[82:85], v[82:85], v[28:31], 0
	v_mfma_f32_16x16x32_bf16 v[86:89], v[86:89], v[28:31], 0
	v_mfma_f32_16x16x32_bf16 v[90:93], v[90:93], v[28:31], 0
	v_mfma_f32_16x16x32_bf16 v[94:97], v[94:97], v[28:31], 0
	v_mfma_f32_16x16x32_bf16 v[98:101], v[98:101], v[28:31], 0
	v_mfma_f32_16x16x32_bf16 v[102:105], v[102:105], v[28:31], 0
	v_mfma_f32_16x16x32_bf16 v[106:109], v[106:109], v[28:31], 0
	v_mfma_f32_16x16x32_bf16 v[110:113], v[110:113], v[28:31], 0
	s_add_u32 s100, s10, 0x11e08100
	s_addc_u32 s101, s11, 0
	s_mov_b32 m0, s13
	s_nop 0
	global_load_lds_dwordx4 v241, s[100:101]
	s_waitcnt lgkmcnt(0)
	v_mfma_f32_16x16x32_bf16 v[42:45], v[142:145], v[24:27], v[44:47]
	v_mfma_f32_16x16x32_bf16 v[50:53], v[138:141], v[24:27], v[50:53]
	v_mfma_f32_16x16x32_bf16 v[38:41], v[134:137], v[24:27], v[38:41]
	v_mfma_f32_16x16x32_bf16 v[74:77], v[130:133], v[24:27], v[74:77]
	v_mfma_f32_16x16x32_bf16 v[66:69], v[126:129], v[24:27], v[66:69]
	v_mfma_f32_16x16x32_bf16 v[70:73], v[122:125], v[24:27], v[70:73]
	ds_read_b128 v[122:125], v64 offset:49152
	ds_read_b128 v[126:129], v64 offset:51200
	ds_read_b128 v[130:133], v64 offset:53248
	ds_read_b128 v[134:137], v64 offset:55296
	v_mfma_f32_16x16x32_bf16 v[60:63], v[118:121], v[24:27], v[60:63]
	ds_read_b128 v[118:121], v64 offset:57344
	ds_read_b128 v[138:141], v64 offset:59392
	ds_read_b128 v[142:145], v64 offset:61440
	ds_read_b128 v[146:149], v64 offset:63488
	v_mfma_f32_16x16x32_bf16 v[78:81], v[114:117], v[24:27], v[78:81]
	s_add_u32 s100, s10, 0x11e00180
	s_addc_u32 s101, s11, 0
	s_mov_b32 m0, s12
	s_nop 0
	global_load_lds_dwordx4 v241, s[100:101]
	s_waitcnt lgkmcnt(0)
	v_mfma_f32_16x16x32_bf16 v[82:85], v[122:125], v[24:27], v[82:85]
	v_mfma_f32_16x16x32_bf16 v[86:89], v[126:129], v[24:27], v[86:89]
	v_mfma_f32_16x16x32_bf16 v[90:93], v[130:133], v[24:27], v[90:93]
	v_mfma_f32_16x16x32_bf16 v[94:97], v[134:137], v[24:27], v[94:97]
	v_mfma_f32_16x16x32_bf16 v[98:101], v[118:121], v[24:27], v[98:101]
	ds_read_b128 v[114:117], v64 offset:15360
	ds_read_b128 v[118:121], v64 offset:13312
	ds_read_b128 v[122:125], v64 offset:11264
	ds_read_b128 v[126:129], v64 offset:9216
	v_mfma_f32_16x16x32_bf16 v[102:105], v[138:141], v[24:27], v[102:105]
	v_mfma_f32_16x16x32_bf16 v[106:109], v[142:145], v[24:27], v[106:109]
	ds_read_b128 v[130:133], v64 offset:7168
	ds_read_b128 v[134:137], v64 offset:5120
	ds_read_b128 v[138:141], v64 offset:3072
	ds_read_b128 v[142:145], v64 offset:1024
	v_mfma_f32_16x16x32_bf16 v[110:113], v[146:149], v[24:27], v[110:113]
	s_add_u32 s100, s10, 0x11e08180
	s_addc_u32 s101, s11, 0
	s_mov_b32 m0, s14
	s_nop 0
	global_load_lds_dwordx4 v241, s[100:101]
	s_waitcnt lgkmcnt(0)
	v_mfma_f32_16x16x32_bf16 v[42:45], v[142:145], v[20:23], v[42:45]
	v_mfma_f32_16x16x32_bf16 v[50:53], v[138:141], v[20:23], v[50:53]
	v_mfma_f32_16x16x32_bf16 v[38:41], v[134:137], v[20:23], v[38:41]
	v_mfma_f32_16x16x32_bf16 v[74:77], v[130:133], v[20:23], v[74:77]
	v_mfma_f32_16x16x32_bf16 v[66:69], v[126:129], v[20:23], v[66:69]
	v_mfma_f32_16x16x32_bf16 v[70:73], v[122:125], v[20:23], v[70:73]
	ds_read_b128 v[122:125], v64 offset:33792
	ds_read_b128 v[126:129], v64 offset:35840
	ds_read_b128 v[130:133], v64 offset:37888
	ds_read_b128 v[134:137], v64 offset:39936
	v_mfma_f32_16x16x32_bf16 v[60:63], v[118:121], v[20:23], v[60:63]
	ds_read_b128 v[118:121], v64 offset:41984
	ds_read_b128 v[138:141], v64 offset:44032
	ds_read_b128 v[142:145], v64 offset:46080
	ds_read_b128 v[146:149], v64 offset:48128
	v_mfma_f32_16x16x32_bf16 v[78:81], v[114:117], v[20:23], v[78:81]
	s_add_u32 s100, s10, 0x11e10100
	s_addc_u32 s101, s11, 0
	s_mov_b32 m0, s15
	s_nop 0
	global_load_lds_dwordx4 v241, s[100:101]
	s_waitcnt lgkmcnt(0)
	v_mfma_f32_16x16x32_bf16 v[82:85], v[122:125], v[20:23], v[82:85]
	v_mfma_f32_16x16x32_bf16 v[86:89], v[126:129], v[20:23], v[86:89]
	v_mfma_f32_16x16x32_bf16 v[90:93], v[130:133], v[20:23], v[90:93]
	v_mfma_f32_16x16x32_bf16 v[94:97], v[134:137], v[20:23], v[94:97]
	v_mfma_f32_16x16x32_bf16 v[98:101], v[118:121], v[20:23], v[98:101]
	ds_read_b128 v[114:117], v64 offset:31744
	ds_read_b128 v[118:121], v64 offset:29696
	ds_read_b128 v[122:125], v64 offset:27648
	ds_read_b128 v[126:129], v64 offset:25600
	v_mfma_f32_16x16x32_bf16 v[102:105], v[138:141], v[20:23], v[102:105]
	v_mfma_f32_16x16x32_bf16 v[106:109], v[142:145], v[20:23], v[106:109]
	ds_read_b128 v[130:133], v64 offset:23552
	ds_read_b128 v[134:137], v64 offset:21504
	ds_read_b128 v[138:141], v64 offset:19456
	ds_read_b128 v[142:145], v64 offset:17408
	v_mfma_f32_16x16x32_bf16 v[110:113], v[146:149], v[20:23], v[110:113]
	s_add_u32 s100, s10, 0x11e18100
	s_addc_u32 s101, s11, 0
	s_mov_b32 m0, s16
	s_nop 0
	global_load_lds_dwordx4 v241, s[100:101]
	s_waitcnt lgkmcnt(0)
	v_mfma_f32_16x16x32_bf16 v[42:45], v[142:145], v[16:19], v[42:45]
	v_mfma_f32_16x16x32_bf16 v[50:53], v[138:141], v[16:19], v[50:53]
	v_mfma_f32_16x16x32_bf16 v[38:41], v[134:137], v[16:19], v[38:41]
	v_mfma_f32_16x16x32_bf16 v[74:77], v[130:133], v[16:19], v[74:77]
	v_mfma_f32_16x16x32_bf16 v[66:69], v[126:129], v[16:19], v[66:69]
	v_mfma_f32_16x16x32_bf16 v[70:73], v[122:125], v[16:19], v[70:73]
	ds_read_b128 v[122:125], v64 offset:50176
	ds_read_b128 v[126:129], v64 offset:52224
	ds_read_b128 v[130:133], v64 offset:54272
	ds_read_b128 v[134:137], v64 offset:56320
	v_mfma_f32_16x16x32_bf16 v[60:63], v[118:121], v[16:19], v[60:63]
	ds_read_b128 v[118:121], v64 offset:58368
	ds_read_b128 v[138:141], v64 offset:60416
	ds_read_b128 v[142:145], v64 offset:62464
	ds_read_b128 v[146:149], v64 offset:64512
	v_mfma_f32_16x16x32_bf16 v[78:81], v[114:117], v[16:19], v[78:81]
	s_add_u32 s100, s10, 0x11e10180
	s_addc_u32 s101, s11, 0
	s_mov_b32 m0, s17
	s_nop 0
	global_load_lds_dwordx4 v241, s[100:101]
	s_waitcnt lgkmcnt(0)
	v_mfma_f32_16x16x32_bf16 v[82:85], v[122:125], v[16:19], v[82:85]
	v_mfma_f32_16x16x32_bf16 v[86:89], v[126:129], v[16:19], v[86:89]
	v_mfma_f32_16x16x32_bf16 v[90:93], v[130:133], v[16:19], v[90:93]
	v_mfma_f32_16x16x32_bf16 v[94:97], v[134:137], v[16:19], v[94:97]
	v_mfma_f32_16x16x32_bf16 v[98:101], v[118:121], v[16:19], v[98:101]
	v_mfma_f32_16x16x32_bf16 v[102:105], v[138:141], v[16:19], v[102:105]
	v_mfma_f32_16x16x32_bf16 v[106:109], v[142:145], v[16:19], v[106:109]
	v_mfma_f32_16x16x32_bf16 v[110:113], v[146:149], v[16:19], v[110:113]
	s_add_u32 s100, s10, 0x11e18180
	s_addc_u32 s101, s11, 0
	s_mov_b32 m0, s18
	s_nop 0
	global_load_lds_dwordx4 v241, s[100:101]
	s_waitcnt vmcnt(0)
	s_waitcnt vmcnt(0)
	s_barrier
	v_mov_b32_e32 v37, v48
	ds_read_b128 v[114:117], v37
	ds_read_b128 v[118:121], v37 offset:2048
	s_waitcnt lgkmcnt(0)
	v_mfma_f32_16x16x32_bf16 v[42:45], v[114:117], v[12:15], v[42:45]
	ds_read_b128 v[114:117], v37 offset:4096
	v_mfma_f32_16x16x32_bf16 v[50:53], v[118:121], v[12:15], v[50:53]
	ds_read_b128 v[118:121], v37 offset:6144
	s_waitcnt lgkmcnt(0)
	v_mfma_f32_16x16x32_bf16 v[38:41], v[114:117], v[12:15], v[38:41]
	ds_read_b128 v[114:117], v37 offset:8192
	v_mfma_f32_16x16x32_bf16 v[74:77], v[118:121], v[12:15], v[74:77]
	ds_read_b128 v[118:121], v37 offset:10240
	s_waitcnt lgkmcnt(0)
	v_mfma_f32_16x16x32_bf16 v[66:69], v[114:117], v[12:15], v[66:69]
	ds_read_b128 v[114:117], v37 offset:12288
	ds_read_b128 v[122:125], v37 offset:14336
	v_mfma_f32_16x16x32_bf16 v[70:73], v[118:121], v[12:15], v[70:73]
	ds_read_b128 v[118:121], v37 offset:32768
	ds_read_b128 v[126:129], v37 offset:34816
	ds_read_b128 v[130:133], v37 offset:36864
	ds_read_b128 v[134:137], v37 offset:38912
	s_waitcnt lgkmcnt(0)
	v_mfma_f32_16x16x32_bf16 v[60:63], v[114:117], v[12:15], v[60:63]
	ds_read_b128 v[114:117], v37 offset:40960
	ds_read_b128 v[138:141], v37 offset:43008
	ds_read_b128 v[142:145], v37 offset:45056
	ds_read_b128 v[146:149], v37 offset:47104
	v_mfma_f32_16x16x32_bf16 v[78:81], v[122:125], v[12:15], v[78:81]
	s_add_u32 s100, s10, 0x11e20000
	s_addc_u32 s101, s11, 0
	s_mov_b32 m0, s22
	s_nop 0
	global_load_lds_dwordx4 v241, s[100:101]
	v_mfma_f32_16x16x32_bf16 v[82:85], v[118:121], v[12:15], v[82:85]
	v_mfma_f32_16x16x32_bf16 v[86:89], v[126:129], v[12:15], v[86:89]
	v_mfma_f32_16x16x32_bf16 v[90:93], v[130:133], v[12:15], v[90:93]
	v_mfma_f32_16x16x32_bf16 v[94:97], v[134:137], v[12:15], v[94:97]
	s_waitcnt lgkmcnt(0)
	v_mfma_f32_16x16x32_bf16 v[98:101], v[114:117], v[12:15], v[98:101]
	ds_read_b128 v[114:117], v37 offset:30720
	ds_read_b128 v[118:121], v37 offset:28672
	ds_read_b128 v[122:125], v37 offset:26624
	ds_read_b128 v[126:129], v37 offset:24576
	v_mfma_f32_16x16x32_bf16 v[102:105], v[138:141], v[12:15], v[102:105]
	v_mfma_f32_16x16x32_bf16 v[106:109], v[142:145], v[12:15], v[106:109]
	ds_read_b128 v[130:133], v37 offset:22528
	ds_read_b128 v[134:137], v37 offset:20480
	ds_read_b128 v[138:141], v37 offset:18432
	ds_read_b128 v[142:145], v37 offset:16384
	v_mfma_f32_16x16x32_bf16 v[110:113], v[146:149], v[12:15], v[110:113]
	s_add_u32 s100, s10, 0x11e28000
	s_addc_u32 s101, s11, 0
	s_mov_b32 m0, s21
	s_nop 0
	global_load_lds_dwordx4 v241, s[100:101]
	s_waitcnt lgkmcnt(0)
	v_mfma_f32_16x16x32_bf16 v[42:45], v[142:145], v[8:11], v[42:45]
	v_mfma_f32_16x16x32_bf16 v[50:53], v[138:141], v[8:11], v[50:53]
	v_mfma_f32_16x16x32_bf16 v[38:41], v[134:137], v[8:11], v[38:41]
	v_mfma_f32_16x16x32_bf16 v[74:77], v[130:133], v[8:11], v[74:77]
	v_mfma_f32_16x16x32_bf16 v[66:69], v[126:129], v[8:11], v[66:69]
	v_mfma_f32_16x16x32_bf16 v[70:73], v[122:125], v[8:11], v[70:73]
	ds_read_b128 v[122:125], v37 offset:49152
	ds_read_b128 v[126:129], v37 offset:51200
	ds_read_b128 v[130:133], v37 offset:53248
	ds_read_b128 v[134:137], v37 offset:55296
	v_mfma_f32_16x16x32_bf16 v[60:63], v[118:121], v[8:11], v[60:63]
	ds_read_b128 v[118:121], v37 offset:57344
	ds_read_b128 v[138:141], v37 offset:59392
	ds_read_b128 v[142:145], v37 offset:61440
	ds_read_b128 v[146:149], v37 offset:63488
	v_mfma_f32_16x16x32_bf16 v[78:81], v[114:117], v[8:11], v[78:81]
	s_add_u32 s100, s10, 0x11e20080
	s_addc_u32 s101, s11, 0
	s_mov_b32 m0, s20
	s_nop 0
	global_load_lds_dwordx4 v241, s[100:101]
	s_waitcnt lgkmcnt(0)
	v_mfma_f32_16x16x32_bf16 v[82:85], v[122:125], v[8:11], v[82:85]
	v_mfma_f32_16x16x32_bf16 v[86:89], v[126:129], v[8:11], v[86:89]
	v_mfma_f32_16x16x32_bf16 v[90:93], v[130:133], v[8:11], v[90:93]
	v_mfma_f32_16x16x32_bf16 v[94:97], v[134:137], v[8:11], v[94:97]
	v_mfma_f32_16x16x32_bf16 v[98:101], v[118:121], v[8:11], v[98:101]
	ds_read_b128 v[114:117], v37 offset:15360
	ds_read_b128 v[118:121], v37 offset:13312
	ds_read_b128 v[122:125], v37 offset:11264
	ds_read_b128 v[126:129], v37 offset:9216
	v_mfma_f32_16x16x32_bf16 v[102:105], v[138:141], v[8:11], v[102:105]
	v_mfma_f32_16x16x32_bf16 v[106:109], v[142:145], v[8:11], v[106:109]
	ds_read_b128 v[130:133], v37 offset:7168
	ds_read_b128 v[134:137], v37 offset:5120
	ds_read_b128 v[138:141], v37 offset:3072
	ds_read_b128 v[142:145], v37 offset:1024
	v_mfma_f32_16x16x32_bf16 v[110:113], v[146:149], v[8:11], v[110:113]
	s_add_u32 s100, s10, 0x11e28080
	s_addc_u32 s101, s11, 0
	s_mov_b32 m0, s23
	s_nop 0
	global_load_lds_dwordx4 v241, s[100:101]
	s_waitcnt lgkmcnt(0)
	v_mfma_f32_16x16x32_bf16 v[42:45], v[142:145], v[4:7], v[42:45]
	v_mfma_f32_16x16x32_bf16 v[50:53], v[138:141], v[4:7], v[50:53]
	v_mfma_f32_16x16x32_bf16 v[38:41], v[134:137], v[4:7], v[38:41]
	v_mfma_f32_16x16x32_bf16 v[74:77], v[130:133], v[4:7], v[74:77]
	v_mfma_f32_16x16x32_bf16 v[66:69], v[126:129], v[4:7], v[66:69]
	v_mfma_f32_16x16x32_bf16 v[70:73], v[122:125], v[4:7], v[70:73]
	ds_read_b128 v[122:125], v37 offset:33792
	ds_read_b128 v[126:129], v37 offset:35840
	ds_read_b128 v[130:133], v37 offset:37888
	ds_read_b128 v[134:137], v37 offset:39936
	v_mfma_f32_16x16x32_bf16 v[60:63], v[118:121], v[4:7], v[60:63]
	ds_read_b128 v[118:121], v37 offset:41984
	ds_read_b128 v[138:141], v37 offset:44032
	ds_read_b128 v[142:145], v37 offset:46080
	ds_read_b128 v[146:149], v37 offset:48128
	v_mfma_f32_16x16x32_bf16 v[78:81], v[114:117], v[4:7], v[78:81]
	s_add_u32 s100, s10, 0x11e30000
	s_addc_u32 s101, s11, 0
	s_mov_b32 m0, s24
	s_nop 0
	global_load_lds_dwordx4 v241, s[100:101]
	s_waitcnt lgkmcnt(0)
	v_mfma_f32_16x16x32_bf16 v[82:85], v[122:125], v[4:7], v[82:85]
	v_mfma_f32_16x16x32_bf16 v[86:89], v[126:129], v[4:7], v[86:89]
	v_mfma_f32_16x16x32_bf16 v[90:93], v[130:133], v[4:7], v[90:93]
	v_mfma_f32_16x16x32_bf16 v[94:97], v[134:137], v[4:7], v[94:97]
	v_mfma_f32_16x16x32_bf16 v[98:101], v[118:121], v[4:7], v[98:101]
	ds_read_b128 v[114:117], v37 offset:31744
	ds_read_b128 v[118:121], v37 offset:29696
	ds_read_b128 v[122:125], v37 offset:27648
	ds_read_b128 v[126:129], v37 offset:25600
	v_mfma_f32_16x16x32_bf16 v[102:105], v[138:141], v[4:7], v[102:105]
	v_mfma_f32_16x16x32_bf16 v[106:109], v[142:145], v[4:7], v[106:109]
	ds_read_b128 v[130:133], v37 offset:23552
	ds_read_b128 v[134:137], v37 offset:21504
	ds_read_b128 v[138:141], v37 offset:19456
	ds_read_b128 v[142:145], v37 offset:17408
	v_mfma_f32_16x16x32_bf16 v[110:113], v[146:149], v[4:7], v[110:113]
	s_add_u32 s100, s10, 0x11e38000
	s_addc_u32 s101, s11, 0
	s_mov_b32 m0, s25
	s_nop 0
	global_load_lds_dwordx4 v241, s[100:101]
	s_waitcnt lgkmcnt(0)
	v_mfma_f32_16x16x32_bf16 v[42:45], v[142:145], v[0:3], v[42:45]
	v_mfma_f32_16x16x32_bf16 v[50:53], v[138:141], v[0:3], v[50:53]
	v_mfma_f32_16x16x32_bf16 v[38:41], v[134:137], v[0:3], v[38:41]
	v_mfma_f32_16x16x32_bf16 v[74:77], v[130:133], v[0:3], v[74:77]
	v_mfma_f32_16x16x32_bf16 v[66:69], v[126:129], v[0:3], v[66:69]
	v_mfma_f32_16x16x32_bf16 v[70:73], v[122:125], v[0:3], v[70:73]
	ds_read_b128 v[122:125], v37 offset:50176
	ds_read_b128 v[126:129], v37 offset:52224
	ds_read_b128 v[130:133], v37 offset:54272
	ds_read_b128 v[134:137], v37 offset:56320
	v_mfma_f32_16x16x32_bf16 v[60:63], v[118:121], v[0:3], v[60:63]
	ds_read_b128 v[118:121], v37 offset:58368
	ds_read_b128 v[138:141], v37 offset:60416
	ds_read_b128 v[142:145], v37 offset:62464
	ds_read_b128 v[146:149], v37 offset:64512
	v_mfma_f32_16x16x32_bf16 v[78:81], v[114:117], v[0:3], v[78:81]
	s_add_u32 s100, s10, 0x11e30080
	s_addc_u32 s101, s11, 0
	s_mov_b32 m0, s26
	s_nop 0
	global_load_lds_dwordx4 v241, s[100:101]
	s_waitcnt lgkmcnt(0)
	v_mfma_f32_16x16x32_bf16 v[82:85], v[122:125], v[0:3], v[82:85]
	v_mfma_f32_16x16x32_bf16 v[86:89], v[126:129], v[0:3], v[86:89]
	v_mfma_f32_16x16x32_bf16 v[90:93], v[130:133], v[0:3], v[90:93]
	v_mfma_f32_16x16x32_bf16 v[94:97], v[134:137], v[0:3], v[94:97]
	v_mfma_f32_16x16x32_bf16 v[98:101], v[118:121], v[0:3], v[98:101]
	v_mfma_f32_16x16x32_bf16 v[102:105], v[138:141], v[0:3], v[102:105]
	v_mfma_f32_16x16x32_bf16 v[106:109], v[142:145], v[0:3], v[106:109]
	v_mfma_f32_16x16x32_bf16 v[110:113], v[146:149], v[0:3], v[110:113]
	s_add_u32 s100, s10, 0x11e38080
	s_addc_u32 s101, s11, 0
	s_mov_b32 m0, s27
	s_nop 0
	global_load_lds_dwordx4 v241, s[100:101]
	s_mov_b32 s0, 0x1000000
	v_add_co_u32_e32 v34, vcc, s0, v34
	v_addc_co_u32_e32 v35, vcc, 0, v35, vcc
	v_mbcnt_lo_u32_b32 v212, -1, 0
	v_mbcnt_hi_u32_b32 v212, -1, v212
	v_lshrrev_b32_e32 v212, 4, v212
	v_and_b32_e32 v212, 1, v212
	v_mul_u32_u24_e32 v212, 24, v212
	v_mov_b32_e32 v213, 0
	v_lshl_add_u64 v[214:215], v[32:33], 0, v[212:213]
	v_mul_f32_e32 v200, v36, v42
	v_mul_f32_e32 v204, v36, v43
	v_cvt_pk_bf16_f32 v200, v200, v204
	v_mul_f32_e32 v201, v36, v44
	v_mul_f32_e32 v204, v36, v45
	v_cvt_pk_bf16_f32 v201, v201, v204
	v_mul_f32_e32 v202, v36, v50
	v_mul_f32_e32 v204, v36, v51
	v_cvt_pk_bf16_f32 v202, v202, v204
	v_mul_f32_e32 v203, v36, v52
	v_mul_f32_e32 v204, v36, v53
	v_cvt_pk_bf16_f32 v203, v203, v204
	s_nop 1
	v_permlane16_swap_b32_e32 v200, v202
	v_permlane16_swap_b32_e32 v201, v203
	global_store_dwordx4 v[214:215], v[200:203], off offset:0
	v_mul_f32_e32 v206, v36, v38
	v_mul_f32_e32 v210, v36, v39
	v_cvt_pk_bf16_f32 v206, v206, v210
	v_mul_f32_e32 v207, v36, v40
	v_mul_f32_e32 v210, v36, v41
	v_cvt_pk_bf16_f32 v207, v207, v210
	v_mul_f32_e32 v208, v36, v74
	v_mul_f32_e32 v210, v36, v75
	v_cvt_pk_bf16_f32 v208, v208, v210
	v_mul_f32_e32 v209, v36, v76
	v_mul_f32_e32 v210, v36, v77
	v_cvt_pk_bf16_f32 v209, v209, v210
	s_nop 1
	v_permlane16_swap_b32_e32 v206, v208
	v_permlane16_swap_b32_e32 v207, v209
	global_store_dwordx4 v[214:215], v[206:209], off offset:64
	v_mul_f32_e32 v200, v36, v66
	v_mul_f32_e32 v204, v36, v67
	v_cvt_pk_bf16_f32 v200, v200, v204
	v_mul_f32_e32 v201, v36, v68
	v_mul_f32_e32 v204, v36, v69
	v_cvt_pk_bf16_f32 v201, v201, v204
	v_mul_f32_e32 v202, v36, v70
	v_mul_f32_e32 v204, v36, v71
	v_cvt_pk_bf16_f32 v202, v202, v204
	v_mul_f32_e32 v203, v36, v72
	v_mul_f32_e32 v204, v36, v73
	v_cvt_pk_bf16_f32 v203, v203, v204
	s_nop 1
	v_permlane16_swap_b32_e32 v200, v202
	v_permlane16_swap_b32_e32 v201, v203
	global_store_dwordx4 v[214:215], v[200:203], off offset:128
	v_mul_f32_e32 v206, v36, v60
	v_mul_f32_e32 v210, v36, v61
	v_cvt_pk_bf16_f32 v206, v206, v210
	v_mul_f32_e32 v207, v36, v62
	v_mul_f32_e32 v210, v36, v63
	v_cvt_pk_bf16_f32 v207, v207, v210
	v_mul_f32_e32 v208, v36, v78
	v_mul_f32_e32 v210, v36, v79
	v_cvt_pk_bf16_f32 v208, v208, v210
	v_mul_f32_e32 v209, v36, v80
	v_mul_f32_e32 v210, v36, v81
	v_cvt_pk_bf16_f32 v209, v209, v210
	s_nop 1
	v_permlane16_swap_b32_e32 v206, v208
	v_permlane16_swap_b32_e32 v207, v209
	global_store_dwordx4 v[214:215], v[206:209], off offset:192
	v_mul_f32_e32 v200, v36, v82
	v_mul_f32_e32 v204, v36, v83
	v_cvt_pk_bf16_f32 v200, v200, v204
	v_mul_f32_e32 v201, v36, v84
	v_mul_f32_e32 v204, v36, v85
	v_cvt_pk_bf16_f32 v201, v201, v204
	v_mul_f32_e32 v202, v36, v86
	v_mul_f32_e32 v204, v36, v87
	v_cvt_pk_bf16_f32 v202, v202, v204
	v_mul_f32_e32 v203, v36, v88
	v_mul_f32_e32 v204, v36, v89
	v_cvt_pk_bf16_f32 v203, v203, v204
	s_nop 1
	v_permlane16_swap_b32_e32 v200, v202
	v_permlane16_swap_b32_e32 v201, v203
	global_store_dwordx4 v[214:215], v[200:203], off offset:256
	v_mul_f32_e32 v206, v36, v90
	v_mul_f32_e32 v210, v36, v91
	v_cvt_pk_bf16_f32 v206, v206, v210
	v_mul_f32_e32 v207, v36, v92
	v_mul_f32_e32 v210, v36, v93
	v_cvt_pk_bf16_f32 v207, v207, v210
	v_mul_f32_e32 v208, v36, v94
	v_mul_f32_e32 v210, v36, v95
	v_cvt_pk_bf16_f32 v208, v208, v210
	v_mul_f32_e32 v209, v36, v96
	v_mul_f32_e32 v210, v36, v97
	v_cvt_pk_bf16_f32 v209, v209, v210
	s_nop 1
	v_permlane16_swap_b32_e32 v206, v208
	v_permlane16_swap_b32_e32 v207, v209
	global_store_dwordx4 v[214:215], v[206:209], off offset:320
	v_mul_f32_e32 v200, v36, v98
	v_mul_f32_e32 v204, v36, v99
	v_cvt_pk_bf16_f32 v200, v200, v204
	v_mul_f32_e32 v201, v36, v100
	v_mul_f32_e32 v204, v36, v101
	v_cvt_pk_bf16_f32 v201, v201, v204
	v_mul_f32_e32 v202, v36, v102
	v_mul_f32_e32 v204, v36, v103
	v_cvt_pk_bf16_f32 v202, v202, v204
	v_mul_f32_e32 v203, v36, v104
	v_mul_f32_e32 v204, v36, v105
	v_cvt_pk_bf16_f32 v203, v203, v204
	s_nop 1
	v_permlane16_swap_b32_e32 v200, v202
	v_permlane16_swap_b32_e32 v201, v203
	global_store_dwordx4 v[214:215], v[200:203], off offset:384
	v_mul_f32_e32 v206, v36, v106
	v_mul_f32_e32 v210, v36, v107
	v_cvt_pk_bf16_f32 v206, v206, v210
	v_mul_f32_e32 v207, v36, v108
	v_mul_f32_e32 v210, v36, v109
	v_cvt_pk_bf16_f32 v207, v207, v210
	v_mul_f32_e32 v208, v36, v110
	v_mul_f32_e32 v210, v36, v111
	v_cvt_pk_bf16_f32 v208, v208, v210
	v_mul_f32_e32 v209, v36, v112
	v_mul_f32_e32 v210, v36, v113
	v_cvt_pk_bf16_f32 v209, v209, v210
	s_nop 1
	v_permlane16_swap_b32_e32 v206, v208
	v_permlane16_swap_b32_e32 v207, v209
	global_store_dwordx4 v[214:215], v[206:209], off offset:448
	s_waitcnt vmcnt(8)
	s_waitcnt vmcnt(8)
	s_barrier
	ds_read_b128 v[38:41], v65
	ds_read_b128 v[42:45], v65 offset:2048
	ds_read_b128 v[50:53], v65 offset:4096
	ds_read_b128 v[54:57], v65 offset:6144
	ds_read_b128 v[58:61], v65 offset:8192
	ds_read_b128 v[66:69], v65 offset:10240
	ds_read_b128 v[70:73], v65 offset:12288
	ds_read_b128 v[74:77], v65 offset:14336
	ds_read_b128 v[78:81], v65 offset:32768
	ds_read_b128 v[82:85], v65 offset:34816
	ds_read_b128 v[86:89], v65 offset:36864
	ds_read_b128 v[90:93], v65 offset:38912
	ds_read_b128 v[94:97], v65 offset:40960
	ds_read_b128 v[98:101], v65 offset:43008
	ds_read_b128 v[102:105], v65 offset:45056
	ds_read_b128 v[106:109], v65 offset:47104
	s_waitcnt lgkmcnt(0)
	v_mfma_f32_16x16x32_bf16 v[38:41], v[38:41], v[28:31], 0
	v_mfma_f32_16x16x32_bf16 v[42:45], v[42:45], v[28:31], 0
	v_mfma_f32_16x16x32_bf16 v[50:53], v[50:53], v[28:31], 0
	v_mfma_f32_16x16x32_bf16 v[54:57], v[54:57], v[28:31], 0
	v_mfma_f32_16x16x32_bf16 v[58:61], v[58:61], v[28:31], 0
	v_mfma_f32_16x16x32_bf16 v[66:69], v[66:69], v[28:31], 0
	v_mfma_f32_16x16x32_bf16 v[70:73], v[70:73], v[28:31], 0
	v_mfma_f32_16x16x32_bf16 v[74:77], v[74:77], v[28:31], 0
	s_add_u32 s100, s10, 0x11e20100
	s_addc_u32 s101, s11, 0
	s_mov_b32 m0, s19
	s_nop 0
	global_load_lds_dwordx4 v241, s[100:101]
	ds_read_b128 v[110:113], v65 offset:30720
	ds_read_b128 v[114:117], v65 offset:28672
	ds_read_b128 v[118:121], v65 offset:26624
	ds_read_b128 v[122:125], v65 offset:24576
	ds_read_b128 v[126:129], v65 offset:22528
	ds_read_b128 v[130:133], v65 offset:20480
	ds_read_b128 v[134:137], v65 offset:18432
	ds_read_b128 v[138:141], v65 offset:16384
	v_mfma_f32_16x16x32_bf16 v[78:81], v[78:81], v[28:31], 0
	v_mfma_f32_16x16x32_bf16 v[82:85], v[82:85], v[28:31], 0
	v_mfma_f32_16x16x32_bf16 v[86:89], v[86:89], v[28:31], 0
	v_mfma_f32_16x16x32_bf16 v[90:93], v[90:93], v[28:31], 0
	v_mfma_f32_16x16x32_bf16 v[94:97], v[94:97], v[28:31], 0
	v_mfma_f32_16x16x32_bf16 v[98:101], v[98:101], v[28:31], 0
	v_mfma_f32_16x16x32_bf16 v[102:105], v[102:105], v[28:31], 0
	v_mfma_f32_16x16x32_bf16 v[28:31], v[106:109], v[28:31], 0
	s_add_u32 s100, s10, 0x11e28100
	s_addc_u32 s101, s11, 0
	s_mov_b32 m0, s13
	s_nop 0
	global_load_lds_dwordx4 v241, s[100:101]
	s_waitcnt lgkmcnt(0)
	v_mfma_f32_16x16x32_bf16 v[38:41], v[138:141], v[24:27], v[38:41]
	v_mfma_f32_16x16x32_bf16 v[42:45], v[134:137], v[24:27], v[42:45]
	v_mfma_f32_16x16x32_bf16 v[50:53], v[130:133], v[24:27], v[50:53]
	v_mfma_f32_16x16x32_bf16 v[54:57], v[126:129], v[24:27], v[54:57]
	v_mfma_f32_16x16x32_bf16 v[58:61], v[122:125], v[24:27], v[58:61]
	v_mfma_f32_16x16x32_bf16 v[66:69], v[118:121], v[24:27], v[66:69]
	ds_read_b128 v[106:109], v65 offset:49152
	ds_read_b128 v[118:121], v65 offset:51200
	ds_read_b128 v[122:125], v65 offset:53248
	ds_read_b128 v[126:129], v65 offset:55296
	v_mfma_f32_16x16x32_bf16 v[70:73], v[114:117], v[24:27], v[70:73]
	ds_read_b128 v[114:117], v65 offset:57344
	ds_read_b128 v[130:133], v65 offset:59392
	ds_read_b128 v[134:137], v65 offset:61440
	ds_read_b128 v[138:141], v65 offset:63488
	v_mfma_f32_16x16x32_bf16 v[74:77], v[110:113], v[24:27], v[74:77]
	s_add_u32 s100, s10, 0x11e20180
	s_addc_u32 s101, s11, 0
	s_mov_b32 m0, s12
	s_nop 0
	global_load_lds_dwordx4 v241, s[100:101]
	s_waitcnt lgkmcnt(0)
	v_mfma_f32_16x16x32_bf16 v[78:81], v[106:109], v[24:27], v[78:81]
	v_mfma_f32_16x16x32_bf16 v[82:85], v[118:121], v[24:27], v[82:85]
	v_mfma_f32_16x16x32_bf16 v[86:89], v[122:125], v[24:27], v[86:89]
	v_mfma_f32_16x16x32_bf16 v[90:93], v[126:129], v[24:27], v[90:93]
	v_mfma_f32_16x16x32_bf16 v[94:97], v[114:117], v[24:27], v[94:97]
	ds_read_b128 v[106:109], v65 offset:15360
	ds_read_b128 v[110:113], v65 offset:13312
	ds_read_b128 v[114:117], v65 offset:11264
	ds_read_b128 v[118:121], v65 offset:9216
	v_mfma_f32_16x16x32_bf16 v[98:101], v[130:133], v[24:27], v[98:101]
	v_mfma_f32_16x16x32_bf16 v[102:105], v[134:137], v[24:27], v[102:105]
	ds_read_b128 v[122:125], v65 offset:7168
	ds_read_b128 v[126:129], v65 offset:5120
	ds_read_b128 v[130:133], v65 offset:3072
	ds_read_b128 v[134:137], v65 offset:1024
	v_mfma_f32_16x16x32_bf16 v[24:27], v[138:141], v[24:27], v[28:31]
	s_add_u32 s100, s10, 0x11e28180
	s_addc_u32 s101, s11, 0
	s_mov_b32 m0, s14
	s_nop 0
	global_load_lds_dwordx4 v241, s[100:101]
	s_waitcnt lgkmcnt(0)
	v_mfma_f32_16x16x32_bf16 v[28:31], v[134:137], v[20:23], v[38:41]
	v_mfma_f32_16x16x32_bf16 v[38:41], v[130:133], v[20:23], v[42:45]
	v_mfma_f32_16x16x32_bf16 v[42:45], v[126:129], v[20:23], v[50:53]
	v_mfma_f32_16x16x32_bf16 v[50:53], v[122:125], v[20:23], v[54:57]
	v_mfma_f32_16x16x32_bf16 v[54:57], v[118:121], v[20:23], v[58:61]
	v_mfma_f32_16x16x32_bf16 v[58:61], v[114:117], v[20:23], v[66:69]
	s_nop 2
	ds_read_b128 v[66:69], v65 offset:33792
	ds_read_b128 v[114:117], v65 offset:35840
	ds_read_b128 v[118:121], v65 offset:37888
	ds_read_b128 v[122:125], v65 offset:39936
	v_mfma_f32_16x16x32_bf16 v[70:73], v[110:113], v[20:23], v[70:73]
	ds_read_b128 v[110:113], v65 offset:41984
	ds_read_b128 v[126:129], v65 offset:44032
	ds_read_b128 v[130:133], v65 offset:46080
	ds_read_b128 v[134:137], v65 offset:48128
	v_mfma_f32_16x16x32_bf16 v[74:77], v[106:109], v[20:23], v[74:77]
	s_add_u32 s100, s10, 0x11e30100
	s_addc_u32 s101, s11, 0
	s_mov_b32 m0, s15
	s_nop 0
	global_load_lds_dwordx4 v241, s[100:101]
	s_waitcnt lgkmcnt(0)
	v_mfma_f32_16x16x32_bf16 v[66:69], v[66:69], v[20:23], v[78:81]
	v_mfma_f32_16x16x32_bf16 v[78:81], v[114:117], v[20:23], v[82:85]
	v_mfma_f32_16x16x32_bf16 v[82:85], v[118:121], v[20:23], v[86:89]
	v_mfma_f32_16x16x32_bf16 v[86:89], v[122:125], v[20:23], v[90:93]
	v_mfma_f32_16x16x32_bf16 v[90:93], v[110:113], v[20:23], v[94:97]
	v_mfma_f32_16x16x32_bf16 v[94:97], v[126:129], v[20:23], v[98:101]
	s_nop 2
	ds_read_b128 v[98:101], v65 offset:31744
	ds_read_b128 v[106:109], v65 offset:29696
	ds_read_b128 v[110:113], v65 offset:27648
	ds_read_b128 v[114:117], v65 offset:25600
	v_mfma_f32_16x16x32_bf16 v[102:105], v[130:133], v[20:23], v[102:105]
	ds_read_b128 v[118:121], v65 offset:23552
	ds_read_b128 v[122:125], v65 offset:21504
	ds_read_b128 v[126:129], v65 offset:19456
	ds_read_b128 v[130:133], v65 offset:17408
	v_mfma_f32_16x16x32_bf16 v[20:23], v[134:137], v[20:23], v[24:27]
	s_add_u32 s100, s10, 0x11e38100
	s_addc_u32 s101, s11, 0
	s_mov_b32 m0, s16
	s_nop 0
	global_load_lds_dwordx4 v241, s[100:101]
	s_waitcnt lgkmcnt(0)
	v_mfma_f32_16x16x32_bf16 v[24:27], v[130:133], v[16:19], v[28:31]
	v_mfma_f32_16x16x32_bf16 v[28:31], v[126:129], v[16:19], v[38:41]
	v_mfma_f32_16x16x32_bf16 v[38:41], v[122:125], v[16:19], v[42:45]
	v_mfma_f32_16x16x32_bf16 v[42:45], v[118:121], v[16:19], v[50:53]
	v_mfma_f32_16x16x32_bf16 v[50:53], v[114:117], v[16:19], v[54:57]
	v_mfma_f32_16x16x32_bf16 v[54:57], v[110:113], v[16:19], v[58:61]
	s_nop 2
	ds_read_b128 v[58:61], v65 offset:50176
	ds_read_b128 v[110:113], v65 offset:52224
	ds_read_b128 v[114:117], v65 offset:54272
	ds_read_b128 v[118:121], v65 offset:56320
	v_mfma_f32_16x16x32_bf16 v[70:73], v[106:109], v[16:19], v[70:73]
	ds_read_b128 v[106:109], v65 offset:58368
	ds_read_b128 v[122:125], v65 offset:60416
	ds_read_b128 v[126:129], v65 offset:62464
	ds_read_b128 v[62:65], v65 offset:64512
	v_mfma_f32_16x16x32_bf16 v[74:77], v[98:101], v[16:19], v[74:77]
	s_add_u32 s100, s10, 0x11e30180
	s_addc_u32 s101, s11, 0
	s_mov_b32 m0, s17
	s_nop 0
	global_load_lds_dwordx4 v241, s[100:101]
	s_waitcnt lgkmcnt(0)
	v_mfma_f32_16x16x32_bf16 v[58:61], v[58:61], v[16:19], v[66:69]
	v_mfma_f32_16x16x32_bf16 v[66:69], v[110:113], v[16:19], v[78:81]
	v_mfma_f32_16x16x32_bf16 v[78:81], v[114:117], v[16:19], v[82:85]
	v_mfma_f32_16x16x32_bf16 v[82:85], v[118:121], v[16:19], v[86:89]
	v_mfma_f32_16x16x32_bf16 v[86:89], v[106:109], v[16:19], v[90:93]
	v_mfma_f32_16x16x32_bf16 v[90:93], v[122:125], v[16:19], v[94:97]
	v_mfma_f32_16x16x32_bf16 v[94:97], v[126:129], v[16:19], v[102:105]
	v_mfma_f32_16x16x32_bf16 v[16:19], v[62:65], v[16:19], v[20:23]
	s_add_u32 s100, s10, 0x11e38180
	s_addc_u32 s101, s11, 0
	s_mov_b32 m0, s18
	s_nop 0
	global_load_lds_dwordx4 v241, s[100:101]
	s_waitcnt vmcnt(0)
	s_waitcnt vmcnt(0)
	s_barrier
	s_nop 0
	ds_read_b128 v[20:23], v48
	ds_read_b128 v[62:65], v48 offset:2048
	s_waitcnt lgkmcnt(1)
	v_mfma_f32_16x16x32_bf16 v[20:23], v[20:23], v[12:15], v[24:27]
	s_nop 2
	ds_read_b128 v[24:27], v48 offset:4096
	s_waitcnt lgkmcnt(1)
	v_mfma_f32_16x16x32_bf16 v[28:31], v[62:65], v[12:15], v[28:31]
	ds_read_b128 v[62:65], v48 offset:6144
	s_waitcnt lgkmcnt(1)
	v_mfma_f32_16x16x32_bf16 v[24:27], v[24:27], v[12:15], v[38:41]
	s_nop 2
	ds_read_b128 v[38:41], v48 offset:8192
	s_waitcnt lgkmcnt(1)
	v_mfma_f32_16x16x32_bf16 v[42:45], v[62:65], v[12:15], v[42:45]
	ds_read_b128 v[62:65], v48 offset:10240
	s_waitcnt lgkmcnt(1)
	v_mfma_f32_16x16x32_bf16 v[38:41], v[38:41], v[12:15], v[50:53]
	s_nop 2
	ds_read_b128 v[50:53], v48 offset:12288
	ds_read_b128 v[98:101], v48 offset:14336
	s_waitcnt lgkmcnt(2)
	v_mfma_f32_16x16x32_bf16 v[54:57], v[62:65], v[12:15], v[54:57]
	ds_read_b128 v[62:65], v48 offset:32768
	ds_read_b128 v[102:105], v48 offset:34816
	ds_read_b128 v[106:109], v48 offset:36864
	ds_read_b128 v[110:113], v48 offset:38912
	s_waitcnt lgkmcnt(5)
	v_mfma_f32_16x16x32_bf16 v[50:53], v[50:53], v[12:15], v[70:73]
	s_nop 2
	ds_read_b128 v[70:73], v48 offset:40960
	ds_read_b128 v[114:117], v48 offset:43008
	ds_read_b128 v[118:121], v48 offset:45056
	ds_read_b128 v[122:125], v48 offset:47104
	s_waitcnt lgkmcnt(8)
	v_mfma_f32_16x16x32_bf16 v[74:77], v[98:101], v[12:15], v[74:77]
	s_waitcnt lgkmcnt(7)
	v_mfma_f32_16x16x32_bf16 v[58:61], v[62:65], v[12:15], v[58:61]
	s_waitcnt lgkmcnt(6)
	v_mfma_f32_16x16x32_bf16 v[62:65], v[102:105], v[12:15], v[66:69]
	s_waitcnt lgkmcnt(5)
	v_mfma_f32_16x16x32_bf16 v[66:69], v[106:109], v[12:15], v[78:81]
	s_waitcnt lgkmcnt(4)
	v_mfma_f32_16x16x32_bf16 v[78:81], v[110:113], v[12:15], v[82:85]
	s_waitcnt lgkmcnt(3)
	v_mfma_f32_16x16x32_bf16 v[70:73], v[70:73], v[12:15], v[86:89]
	s_waitcnt lgkmcnt(2)
	v_mfma_f32_16x16x32_bf16 v[82:85], v[114:117], v[12:15], v[90:93]
	s_nop 0
	ds_read_b128 v[86:89], v48 offset:30720
	s_nop 0
	ds_read_b128 v[90:93], v48 offset:28672
	ds_read_b128 v[98:101], v48 offset:26624
	ds_read_b128 v[102:105], v48 offset:24576
	s_waitcnt lgkmcnt(5)
	v_mfma_f32_16x16x32_bf16 v[94:97], v[118:121], v[12:15], v[94:97]
	ds_read_b128 v[106:109], v48 offset:22528
	ds_read_b128 v[110:113], v48 offset:20480
	ds_read_b128 v[114:117], v48 offset:18432
	ds_read_b128 v[118:121], v48 offset:16384
	s_waitcnt lgkmcnt(8)
	v_mfma_f32_16x16x32_bf16 v[12:15], v[122:125], v[12:15], v[16:19]
	s_waitcnt lgkmcnt(0)
	v_mfma_f32_16x16x32_bf16 v[16:19], v[118:121], v[8:11], v[20:23]
	v_mfma_f32_16x16x32_bf16 v[20:23], v[114:117], v[8:11], v[28:31]
	v_mfma_f32_16x16x32_bf16 v[24:27], v[110:113], v[8:11], v[24:27]
	v_mfma_f32_16x16x32_bf16 v[28:31], v[106:109], v[8:11], v[42:45]
	v_mfma_f32_16x16x32_bf16 v[38:41], v[102:105], v[8:11], v[38:41]
	v_mfma_f32_16x16x32_bf16 v[42:45], v[98:101], v[8:11], v[54:57]
	s_nop 2
	ds_read_b128 v[54:57], v48 offset:49152
	ds_read_b128 v[98:101], v48 offset:51200
	ds_read_b128 v[102:105], v48 offset:53248
	ds_read_b128 v[106:109], v48 offset:55296
	v_mfma_f32_16x16x32_bf16 v[50:53], v[90:93], v[8:11], v[50:53]
	ds_read_b128 v[90:93], v48 offset:57344
	ds_read_b128 v[110:113], v48 offset:59392
	ds_read_b128 v[114:117], v48 offset:61440
	ds_read_b128 v[118:121], v48 offset:63488
	v_mfma_f32_16x16x32_bf16 v[74:77], v[86:89], v[8:11], v[74:77]
	s_waitcnt lgkmcnt(7)
	v_mfma_f32_16x16x32_bf16 v[54:57], v[54:57], v[8:11], v[58:61]
	s_waitcnt lgkmcnt(6)
	v_mfma_f32_16x16x32_bf16 v[58:61], v[98:101], v[8:11], v[62:65]
	s_waitcnt lgkmcnt(5)
	v_mfma_f32_16x16x32_bf16 v[62:65], v[102:105], v[8:11], v[66:69]
	s_waitcnt lgkmcnt(4)
	v_mfma_f32_16x16x32_bf16 v[66:69], v[106:109], v[8:11], v[78:81]
	s_waitcnt lgkmcnt(3)
	v_mfma_f32_16x16x32_bf16 v[70:73], v[90:93], v[8:11], v[70:73]
	s_waitcnt lgkmcnt(2)
	v_mfma_f32_16x16x32_bf16 v[78:81], v[110:113], v[8:11], v[82:85]
	s_nop 2
	ds_read_b128 v[82:85], v48 offset:15360
	ds_read_b128 v[86:89], v48 offset:13312
	ds_read_b128 v[90:93], v48 offset:11264
	ds_read_b128 v[98:101], v48 offset:9216
	s_waitcnt lgkmcnt(5)
	v_mfma_f32_16x16x32_bf16 v[94:97], v[114:117], v[8:11], v[94:97]
	ds_read_b128 v[102:105], v48 offset:7168
	ds_read_b128 v[106:109], v48 offset:5120
	ds_read_b128 v[110:113], v48 offset:3072
	ds_read_b128 v[114:117], v48 offset:1024
	s_waitcnt lgkmcnt(8)
	v_mfma_f32_16x16x32_bf16 v[8:11], v[118:121], v[8:11], v[12:15]
	s_waitcnt lgkmcnt(0)
	v_mfma_f32_16x16x32_bf16 v[12:15], v[114:117], v[4:7], v[16:19]
	v_mfma_f32_16x16x32_bf16 v[16:19], v[110:113], v[4:7], v[20:23]
	v_mfma_f32_16x16x32_bf16 v[20:23], v[106:109], v[4:7], v[24:27]
	v_mfma_f32_16x16x32_bf16 v[24:27], v[102:105], v[4:7], v[28:31]
	v_mfma_f32_16x16x32_bf16 v[28:31], v[98:101], v[4:7], v[38:41]
	v_mfma_f32_16x16x32_bf16 v[38:41], v[90:93], v[4:7], v[42:45]
	s_nop 2
	ds_read_b128 v[42:45], v48 offset:33792
	ds_read_b128 v[90:93], v48 offset:35840
	ds_read_b128 v[98:101], v48 offset:37888
	ds_read_b128 v[102:105], v48 offset:39936
	v_mfma_f32_16x16x32_bf16 v[50:53], v[86:89], v[4:7], v[50:53]
	ds_read_b128 v[86:89], v48 offset:41984
	ds_read_b128 v[106:109], v48 offset:44032
	ds_read_b128 v[110:113], v48 offset:46080
	ds_read_b128 v[114:117], v48 offset:48128
	v_mfma_f32_16x16x32_bf16 v[74:77], v[82:85], v[4:7], v[74:77]
	s_waitcnt lgkmcnt(7)
	v_mfma_f32_16x16x32_bf16 v[42:45], v[42:45], v[4:7], v[54:57]
	s_waitcnt lgkmcnt(6)
	v_mfma_f32_16x16x32_bf16 v[54:57], v[90:93], v[4:7], v[58:61]
	s_waitcnt lgkmcnt(5)
	v_mfma_f32_16x16x32_bf16 v[58:61], v[98:101], v[4:7], v[62:65]
	s_waitcnt lgkmcnt(4)
	v_mfma_f32_16x16x32_bf16 v[62:65], v[102:105], v[4:7], v[66:69]
	s_waitcnt lgkmcnt(3)
	v_mfma_f32_16x16x32_bf16 v[66:69], v[86:89], v[4:7], v[70:73]
	s_waitcnt lgkmcnt(2)
	v_mfma_f32_16x16x32_bf16 v[70:73], v[106:109], v[4:7], v[78:81]
	s_nop 2
	ds_read_b128 v[78:81], v48 offset:31744
	ds_read_b128 v[82:85], v48 offset:29696
	ds_read_b128 v[86:89], v48 offset:27648
	ds_read_b128 v[90:93], v48 offset:25600
	s_waitcnt lgkmcnt(5)
	v_mfma_f32_16x16x32_bf16 v[94:97], v[110:113], v[4:7], v[94:97]
	ds_read_b128 v[98:101], v48 offset:23552
	ds_read_b128 v[102:105], v48 offset:21504
	ds_read_b128 v[106:109], v48 offset:19456
	ds_read_b128 v[110:113], v48 offset:17408
	s_waitcnt lgkmcnt(8)
	v_mfma_f32_16x16x32_bf16 v[4:7], v[114:117], v[4:7], v[8:11]
	s_waitcnt lgkmcnt(0)
	v_mfma_f32_16x16x32_bf16 v[8:11], v[110:113], v[0:3], v[12:15]
	v_mfma_f32_16x16x32_bf16 v[12:15], v[106:109], v[0:3], v[16:19]
	v_mfma_f32_16x16x32_bf16 v[16:19], v[102:105], v[0:3], v[20:23]
	v_mfma_f32_16x16x32_bf16 v[20:23], v[98:101], v[0:3], v[24:27]
	v_mfma_f32_16x16x32_bf16 v[24:27], v[90:93], v[0:3], v[28:31]
	v_mfma_f32_16x16x32_bf16 v[28:31], v[86:89], v[0:3], v[38:41]
	s_nop 2
	ds_read_b128 v[38:41], v48 offset:50176
	ds_read_b128 v[86:89], v48 offset:52224
	ds_read_b128 v[90:93], v48 offset:54272
	ds_read_b128 v[98:101], v48 offset:56320
	v_mfma_f32_16x16x32_bf16 v[50:53], v[82:85], v[0:3], v[50:53]
	ds_read_b128 v[82:85], v48 offset:58368
	ds_read_b128 v[102:105], v48 offset:60416
	ds_read_b128 v[106:109], v48 offset:62464
	ds_read_b128 v[46:49], v48 offset:64512
	v_mfma_f32_16x16x32_bf16 v[74:77], v[78:81], v[0:3], v[74:77]
	s_waitcnt lgkmcnt(7)
	v_mfma_f32_16x16x32_bf16 v[38:41], v[38:41], v[0:3], v[42:45]
	s_waitcnt lgkmcnt(6)
	v_mfma_f32_16x16x32_bf16 v[42:45], v[86:89], v[0:3], v[54:57]
	s_waitcnt lgkmcnt(5)
	v_mfma_f32_16x16x32_bf16 v[54:57], v[90:93], v[0:3], v[58:61]
	s_waitcnt lgkmcnt(4)
	v_mfma_f32_16x16x32_bf16 v[58:61], v[98:101], v[0:3], v[62:65]
	s_waitcnt lgkmcnt(3)
	v_mfma_f32_16x16x32_bf16 v[62:65], v[82:85], v[0:3], v[66:69]
	s_waitcnt lgkmcnt(2)
	v_mfma_f32_16x16x32_bf16 v[66:69], v[102:105], v[0:3], v[70:73]
	s_waitcnt lgkmcnt(1)
	v_mfma_f32_16x16x32_bf16 v[70:73], v[106:109], v[0:3], v[94:97]
	s_waitcnt lgkmcnt(0)
	v_mfma_f32_16x16x32_bf16 v[0:3], v[46:49], v[0:3], v[4:7]
	s_nop 2
	v_mul_f32_e32 v200, v36, v8
	v_mul_f32_e32 v204, v36, v9
	v_cvt_pk_bf16_f32 v200, v200, v204
	v_mul_f32_e32 v201, v36, v10
	v_mul_f32_e32 v204, v36, v11
	v_cvt_pk_bf16_f32 v201, v201, v204
	v_mul_f32_e32 v202, v36, v12
	v_mul_f32_e32 v204, v36, v13
	v_cvt_pk_bf16_f32 v202, v202, v204
	v_mul_f32_e32 v203, v36, v14
	v_mul_f32_e32 v204, v36, v15
	v_cvt_pk_bf16_f32 v203, v203, v204
	s_nop 1
	v_permlane16_swap_b32_e32 v200, v202
	v_permlane16_swap_b32_e32 v201, v203
	global_store_dwordx4 v[214:215], v[200:203], off offset:512
	v_mul_f32_e32 v206, v36, v16
	v_mul_f32_e32 v210, v36, v17
	v_cvt_pk_bf16_f32 v206, v206, v210
	v_mul_f32_e32 v207, v36, v18
	v_mul_f32_e32 v210, v36, v19
	v_cvt_pk_bf16_f32 v207, v207, v210
	v_mul_f32_e32 v208, v36, v20
	v_mul_f32_e32 v210, v36, v21
	v_cvt_pk_bf16_f32 v208, v208, v210
	v_mul_f32_e32 v209, v36, v22
	v_mul_f32_e32 v210, v36, v23
	v_cvt_pk_bf16_f32 v209, v209, v210
	s_nop 1
	v_permlane16_swap_b32_e32 v206, v208
	v_permlane16_swap_b32_e32 v207, v209
	global_store_dwordx4 v[214:215], v[206:209], off offset:576
	v_mul_f32_e32 v200, v36, v24
	v_mul_f32_e32 v204, v36, v25
	v_cvt_pk_bf16_f32 v200, v200, v204
	v_mul_f32_e32 v201, v36, v26
	v_mul_f32_e32 v204, v36, v27
	v_cvt_pk_bf16_f32 v201, v201, v204
	v_mul_f32_e32 v202, v36, v28
	v_mul_f32_e32 v204, v36, v29
	v_cvt_pk_bf16_f32 v202, v202, v204
	v_mul_f32_e32 v203, v36, v30
	v_mul_f32_e32 v204, v36, v31
	v_cvt_pk_bf16_f32 v203, v203, v204
	s_nop 1
	v_permlane16_swap_b32_e32 v200, v202
	v_permlane16_swap_b32_e32 v201, v203
	global_store_dwordx4 v[214:215], v[200:203], off offset:640
	v_mul_f32_e32 v206, v36, v50
	v_mul_f32_e32 v210, v36, v51
	v_cvt_pk_bf16_f32 v206, v206, v210
	v_mul_f32_e32 v207, v36, v52
	v_mul_f32_e32 v210, v36, v53
	v_cvt_pk_bf16_f32 v207, v207, v210
	v_mul_f32_e32 v208, v36, v74
	v_mul_f32_e32 v210, v36, v75
	v_cvt_pk_bf16_f32 v208, v208, v210
	v_mul_f32_e32 v209, v36, v76
	v_mul_f32_e32 v210, v36, v77
	v_cvt_pk_bf16_f32 v209, v209, v210
	s_nop 1
	v_permlane16_swap_b32_e32 v206, v208
	v_permlane16_swap_b32_e32 v207, v209
	global_store_dwordx4 v[214:215], v[206:209], off offset:704
	v_mul_f32_e32 v200, v36, v38
	v_mul_f32_e32 v204, v36, v39
	v_cvt_pk_bf16_f32 v200, v200, v204
	v_mul_f32_e32 v201, v36, v40
	v_mul_f32_e32 v204, v36, v41
	v_cvt_pk_bf16_f32 v201, v201, v204
	v_mul_f32_e32 v202, v36, v42
	v_mul_f32_e32 v204, v36, v43
	v_cvt_pk_bf16_f32 v202, v202, v204
	v_mul_f32_e32 v203, v36, v44
	v_mul_f32_e32 v204, v36, v45
	v_cvt_pk_bf16_f32 v203, v203, v204
	s_nop 1
	v_permlane16_swap_b32_e32 v200, v202
	v_permlane16_swap_b32_e32 v201, v203
	global_store_dwordx4 v[214:215], v[200:203], off offset:768
	v_mul_f32_e32 v206, v36, v54
	v_mul_f32_e32 v210, v36, v55
	v_cvt_pk_bf16_f32 v206, v206, v210
	v_mul_f32_e32 v207, v36, v56
	v_mul_f32_e32 v210, v36, v57
	v_cvt_pk_bf16_f32 v207, v207, v210
	v_mul_f32_e32 v208, v36, v58
	v_mul_f32_e32 v210, v36, v59
	v_cvt_pk_bf16_f32 v208, v208, v210
	v_mul_f32_e32 v209, v36, v60
	v_mul_f32_e32 v210, v36, v61
	v_cvt_pk_bf16_f32 v209, v209, v210
	s_nop 1
	v_permlane16_swap_b32_e32 v206, v208
	v_permlane16_swap_b32_e32 v207, v209
	global_store_dwordx4 v[214:215], v[206:209], off offset:832
	v_mul_f32_e32 v200, v36, v62
	v_mul_f32_e32 v204, v36, v63
	v_cvt_pk_bf16_f32 v200, v200, v204
	v_mul_f32_e32 v201, v36, v64
	v_mul_f32_e32 v204, v36, v65
	v_cvt_pk_bf16_f32 v201, v201, v204
	v_mul_f32_e32 v202, v36, v66
	v_mul_f32_e32 v204, v36, v67
	v_cvt_pk_bf16_f32 v202, v202, v204
	v_mul_f32_e32 v203, v36, v68
	v_mul_f32_e32 v204, v36, v69
	v_cvt_pk_bf16_f32 v203, v203, v204
	s_nop 1
	v_permlane16_swap_b32_e32 v200, v202
	v_permlane16_swap_b32_e32 v201, v203
	global_store_dwordx4 v[214:215], v[200:203], off offset:896
	v_mul_f32_e32 v206, v36, v70
	v_mul_f32_e32 v210, v36, v71
	v_cvt_pk_bf16_f32 v206, v206, v210
	v_mul_f32_e32 v207, v36, v72
	v_mul_f32_e32 v210, v36, v73
	v_cvt_pk_bf16_f32 v207, v207, v210
	v_mul_f32_e32 v208, v36, v0
	v_mul_f32_e32 v210, v36, v1
	v_cvt_pk_bf16_f32 v208, v208, v210
	v_mul_f32_e32 v209, v36, v2
	v_mul_f32_e32 v210, v36, v3
	v_cvt_pk_bf16_f32 v209, v209, v210
	s_nop 1
	v_permlane16_swap_b32_e32 v206, v208
	v_permlane16_swap_b32_e32 v207, v209
	global_store_dwordx4 v[214:215], v[206:209], off offset:960
	s_waitcnt vmcnt(0)
	s_barrier
